# stack + phase-0 bias dot-product loop fully unrolled (40 loads in flight) + all s_setprio removed
# baseline (speedup 1.0000x reference)
; #define VBID ((int)(blockIdx.x * 2) + HALF())
; DI void phase0(const Params& p, const int L, bf16_t* lds) {
;     ...
;     for (int item = VBID; item < 128; item += NVB) {
;       const int kv = item >> 6, kc = item & 63;
;       const float* pos = (kv ? p.cmp_pos_v : p.cmp_pos_k) + L * 2048 + kc * 32;
;       const float* w1 = (kv ? p.cmp_w1_v : p.cmp_w1_k) + (size_t)L * 2048 * 256 + (size_t)kc * 32 * 256;
;       float a = 0.f;
; #pragma unroll 8
;       for (int k = 0; k < 32; ++k) a += pos[k] * w1[(size_t)k * 256 + n];
;       part[item * 256 + n] = a;
;     }
.LBB0_70:
	global_load_dword v35, v[4:5], off offset:-4096
	s_add_u32 s20, s5, 0
	s_addc_u32 s21, s13, 0
	v_add_co_u32_e32 v12, vcc, 0xfffff000, v4
	s_nop 1
	v_addc_co_u32_e32 v13, vcc, -1, v5, vcc
	global_load_dwordx4 v[24:27], v1, s[20:21]
	global_load_dword v32, v[12:13], off offset:-3072
	global_load_dword v33, v[12:13], off offset:-2048
	global_load_dword v34, v[12:13], off offset:-1024
	global_load_dword v36, v[4:5], off offset:-3072
	global_load_dwordx4 v[28:31], v1, s[20:21] offset:16
	global_load_dword v37, v[4:5], off offset:-2048
	global_load_dword v38, v[4:5], off offset:-1024
	global_load_dword v39, v[4:5], off
	v_lshl_add_u64 v[4:5], v[4:5], 0, s[14:15]
	global_load_dword v51, v[4:5], off offset:-4096
	s_add_u32 s20, s5, 32
	s_addc_u32 s21, s13, 0
	v_add_co_u32_e32 v12, vcc, 0xfffff000, v4
	s_nop 1
	v_addc_co_u32_e32 v13, vcc, -1, v5, vcc
	global_load_dwordx4 v[40:43], v1, s[20:21]
	global_load_dword v48, v[12:13], off offset:-3072
	global_load_dword v49, v[12:13], off offset:-2048
	global_load_dword v50, v[12:13], off offset:-1024
	global_load_dword v52, v[4:5], off offset:-3072
	global_load_dwordx4 v[44:47], v1, s[20:21] offset:16
	global_load_dword v53, v[4:5], off offset:-2048
	global_load_dword v54, v[4:5], off offset:-1024
	global_load_dword v55, v[4:5], off
	v_lshl_add_u64 v[4:5], v[4:5], 0, s[14:15]
	global_load_dword v79, v[4:5], off offset:-4096
	s_add_u32 s20, s5, 64
	s_addc_u32 s21, s13, 0
	v_add_co_u32_e32 v12, vcc, 0xfffff000, v4
	s_nop 1
	v_addc_co_u32_e32 v13, vcc, -1, v5, vcc
	global_load_dwordx4 v[68:71], v1, s[20:21]
	global_load_dword v76, v[12:13], off offset:-3072
	global_load_dword v77, v[12:13], off offset:-2048
	global_load_dword v78, v[12:13], off offset:-1024
	global_load_dword v80, v[4:5], off offset:-3072
	global_load_dwordx4 v[72:75], v1, s[20:21] offset:16
	global_load_dword v81, v[4:5], off offset:-2048
	global_load_dword v82, v[4:5], off offset:-1024
	global_load_dword v83, v[4:5], off
	v_lshl_add_u64 v[4:5], v[4:5], 0, s[14:15]
	global_load_dword v95, v[4:5], off offset:-4096
	s_add_u32 s20, s5, 96
	s_addc_u32 s21, s13, 0
	v_add_co_u32_e32 v12, vcc, 0xfffff000, v4
	s_nop 1
	v_addc_co_u32_e32 v13, vcc, -1, v5, vcc
	global_load_dwordx4 v[84:87], v1, s[20:21]
	global_load_dword v92, v[12:13], off offset:-3072
	global_load_dword v93, v[12:13], off offset:-2048
	global_load_dword v94, v[12:13], off offset:-1024
	global_load_dword v96, v[4:5], off offset:-3072
	global_load_dwordx4 v[88:91], v1, s[20:21] offset:16
	global_load_dword v97, v[4:5], off offset:-2048
	global_load_dword v98, v[4:5], off offset:-1024
	global_load_dword v99, v[4:5], off
	v_lshl_add_u64 v[4:5], v[4:5], 0, s[14:15]
	s_waitcnt vmcnt(0)
	v_fmac_f32_e32 v6, v24, v32
	v_fmac_f32_e32 v6, v25, v33
	v_fmac_f32_e32 v6, v26, v34
	v_fmac_f32_e32 v6, v27, v35
	v_fmac_f32_e32 v6, v28, v36
	v_fmac_f32_e32 v6, v29, v37
	v_fmac_f32_e32 v6, v30, v38
	v_fmac_f32_e32 v6, v31, v39
	v_fmac_f32_e32 v6, v40, v48
	v_fmac_f32_e32 v6, v41, v49
	v_fmac_f32_e32 v6, v42, v50
	v_fmac_f32_e32 v6, v43, v51
	v_fmac_f32_e32 v6, v44, v52
	v_fmac_f32_e32 v6, v45, v53
	v_fmac_f32_e32 v6, v46, v54
	v_fmac_f32_e32 v6, v47, v55
	v_fmac_f32_e32 v6, v68, v76
	v_fmac_f32_e32 v6, v69, v77
	v_fmac_f32_e32 v6, v70, v78
	v_fmac_f32_e32 v6, v71, v79
	v_fmac_f32_e32 v6, v72, v80
	v_fmac_f32_e32 v6, v73, v81
	v_fmac_f32_e32 v6, v74, v82
	v_fmac_f32_e32 v6, v75, v83
	v_fmac_f32_e32 v6, v84, v92
	v_fmac_f32_e32 v6, v85, v93
	v_fmac_f32_e32 v6, v86, v94
	v_fmac_f32_e32 v6, v87, v95
	v_fmac_f32_e32 v6, v88, v96
	v_fmac_f32_e32 v6, v89, v97
	v_fmac_f32_e32 v6, v90, v98
	v_fmac_f32_e32 v6, v91, v99
	v_lshl_or_b32 v4, s9, 8, v0
	v_readlane_b32 s6, v254, 45
	v_ashrrev_i32_e32 v5, 31, v4
	v_readlane_b32 s7, v254, 46
	s_add_i32 s9, s9, s10
	s_add_i32 s11, s11, s12
	v_lshl_add_u64 v[4:5], v[4:5], 2, s[6:7]
	s_cmpk_gt_i32 s9, 0x7f
	global_store_dword v[4:5], v6, off
	s_cbranch_scc0 .LBB0_69

; DI f32x4 mfma16(bf16x8 a, bf16x8 b, f32x4 c) { return __builtin_amdgcn_mfma_f32_16x16x32_bf16(a, b, c, 0, 0, 0); }
; #pragma unroll
;   for (int ks = KS0; ks < KS1; ++ks) {
;     bf16x8 af[8], bfr[4];
; #pragma unroll
;     for (int i = 0; i < 8; ++i) {
;       const int r = wm * 128 + i * 16 + (lane & 15);
;       af[i] = *(const bf16x8*)(S + r * 64 + (((ks * 4 + (lane >> 4)) ^ ((r >> 1) & 7)) << 3));
;     }
; #pragma unroll
;     for (int j = 0; j < 4; ++j) {
;       const int r = wn * 64 + j * 16 + (lane & 15);
;       bfr[j] = *(const bf16x8*)(S + 16384 + r * 64 + (((ks * 4 + (lane >> 4)) ^ ((r >> 1) & 7)) << 3));
;     }
;     __builtin_amdgcn_s_setprio(1);
; #pragma unroll
;     for (int i = 0; i < 8; ++i)
; #pragma unroll
;       for (int j = 0; j < 4; ++j) acc[i][j] = mfma16(bfr[j], af[i], acc[i][j]);
;     __builtin_amdgcn_s_setprio(0);
;   }
; }
; DI void gemm8_accum(f32x4 (&acc)[8][4], const bf16_t* a, size_t lda, const bf16_t* b, size_t ldb, int nkb, bf16_t* L,
;                     const bool pre, const bf16_t* an, size_t ldan, const bf16_t* bn, size_t ldbn) {
;     ...
;   for (int kb = 0; kb + 2 < nkb; ++kb) {
;     __syncthreads();
;     g8_store1(L + ((kb + 1) & 1) * 32768, ra, lrow, lch);
;     g8_load1o(ra, a + (kb + 2) * 64, offa);
;     __builtin_amdgcn_sched_barrier(0);
;     g8_compute<0, 1>(acc, L + (kb & 1) * 32768, wm, wn, lane);
;     __builtin_amdgcn_sched_barrier(0);
;     g8_store1(L + ((kb + 1) & 1) * 32768 + 16384, rb, lrow, lch);
;     g8_load1o(rb, b + (kb + 2) * 64, offb);
;     __builtin_amdgcn_sched_barrier(0);
;     g8_compute<1, 2>(acc, L + (kb & 1) * 32768, wm, wn, lane);
;   }
.Lstg_134_a:
	s_waitcnt vmcnt(5)
	ds_write_b128 v167, v[22:25]
	ds_write_b128 v167, v[18:21] offset:8192
	ds_write_b128 v167, v[26:29] offset:16384
	s_waitcnt vmcnt(4)
	ds_write_b128 v167, v[30:33] offset:24576
	s_add_u32 s54, s52, s0
	s_addc_u32 s55, s53, s1
	global_load_dwordx4 v[22:25], v185, s[54:55]
	global_load_dwordx4 v[26:29], v181, s[54:55]
	global_load_dwordx4 v[18:21], v183, s[54:55]
	s_nop 0
	global_load_dwordx4 v[30:33], v179, s[54:55]
	s_and_b32 s2, s2, 0x8000
	s_lshl_b32 s2, s2, 1
	s_add_i32 s2, s2, 0
	v_lshl_add_u32 v169, v191, 1, s2
	v_add_u32_e32 v198, v169, v187
	ds_read_b128 v[192:195], v198
	ds_read_b128 v[206:209], v198 offset:2048
	ds_read_b128 v[210:213], v198 offset:4096
	ds_read_b128 v[214:217], v198 offset:6144
	ds_read_b128 v[218:221], v198 offset:8192
	ds_read_b128 v[222:225], v198 offset:10240
	ds_read_b128 v[226:229], v198 offset:12288
	ds_read_b128 v[230:233], v198 offset:14336
	v_add_u32_e32 v169, v169, v186
	ds_read_b128 v[234:237], v169 offset:32768
	ds_read_b128 v[238:241], v169 offset:34816
	ds_read_b128 v[242:245], v169 offset:36864
	ds_read_b128 v[246:249], v169 offset:38912
	s_waitcnt lgkmcnt(3)
	v_mfma_f32_16x16x32_bf16 v[34:37], v[234:237], v[192:195], v[34:37]
	s_waitcnt lgkmcnt(2)
	v_mfma_f32_16x16x32_bf16 v[38:41], v[238:241], v[192:195], v[38:41]
	s_waitcnt lgkmcnt(1)
	v_mfma_f32_16x16x32_bf16 v[42:45], v[242:245], v[192:195], v[42:45]
	s_waitcnt lgkmcnt(0)
	v_mfma_f32_16x16x32_bf16 v[46:49], v[246:249], v[192:195], v[46:49]
	v_mfma_f32_16x16x32_bf16 v[50:53], v[234:237], v[206:209], v[50:53]
	v_mfma_f32_16x16x32_bf16 v[54:57], v[238:241], v[206:209], v[54:57]
	v_mfma_f32_16x16x32_bf16 v[58:61], v[242:245], v[206:209], v[58:61]
	v_mfma_f32_16x16x32_bf16 v[62:65], v[246:249], v[206:209], v[62:65]
	v_mfma_f32_16x16x32_bf16 v[66:69], v[234:237], v[210:213], v[66:69]
	v_mfma_f32_16x16x32_bf16 v[70:73], v[238:241], v[210:213], v[70:73]
	v_mfma_f32_16x16x32_bf16 v[74:77], v[242:245], v[210:213], v[74:77]
	v_mfma_f32_16x16x32_bf16 v[78:81], v[246:249], v[210:213], v[78:81]
	v_mfma_f32_16x16x32_bf16 v[82:85], v[234:237], v[214:217], v[82:85]
	v_mfma_f32_16x16x32_bf16 v[86:89], v[238:241], v[214:217], v[86:89]
	v_mfma_f32_16x16x32_bf16 v[90:93], v[242:245], v[214:217], v[90:93]
	v_mfma_f32_16x16x32_bf16 v[94:97], v[246:249], v[214:217], v[94:97]
	v_mfma_f32_16x16x32_bf16 v[98:101], v[234:237], v[218:221], v[98:101]
	v_mfma_f32_16x16x32_bf16 v[102:105], v[238:241], v[218:221], v[102:105]
	v_mfma_f32_16x16x32_bf16 v[106:109], v[242:245], v[218:221], v[106:109]
	v_mfma_f32_16x16x32_bf16 v[110:113], v[246:249], v[218:221], v[110:113]
	v_mfma_f32_16x16x32_bf16 v[114:117], v[234:237], v[222:225], v[114:117]
	v_mfma_f32_16x16x32_bf16 v[118:121], v[238:241], v[222:225], v[118:121]
	v_mfma_f32_16x16x32_bf16 v[122:125], v[242:245], v[222:225], v[122:125]
	v_mfma_f32_16x16x32_bf16 v[126:129], v[246:249], v[222:225], v[126:129]
	v_mfma_f32_16x16x32_bf16 v[130:133], v[234:237], v[226:229], v[130:133]
	v_mfma_f32_16x16x32_bf16 v[134:137], v[238:241], v[226:229], v[134:137]
	v_mfma_f32_16x16x32_bf16 v[138:141], v[242:245], v[226:229], v[138:141]
	v_mfma_f32_16x16x32_bf16 v[142:145], v[246:249], v[226:229], v[142:145]
	v_mfma_f32_16x16x32_bf16 v[146:149], v[234:237], v[230:233], v[146:149]
	v_mfma_f32_16x16x32_bf16 v[150:153], v[238:241], v[230:233], v[150:153]
	v_mfma_f32_16x16x32_bf16 v[154:157], v[242:245], v[230:233], v[154:157]
	v_mfma_f32_16x16x32_bf16 v[158:161], v[246:249], v[230:233], v[158:161]
	s_waitcnt vmcnt(7)
	ds_write_b128 v167, v[6:9] offset:32768
	s_waitcnt vmcnt(6)
	ds_write_b128 v167, v[2:5] offset:40960
	s_waitcnt vmcnt(5)
	ds_write_b128 v167, v[10:13] offset:49152
	s_waitcnt vmcnt(4)
	ds_write_b128 v167, v[14:17] offset:57344
	s_add_u32 s58, s56, s0
	s_addc_u32 s59, s57, s1
	global_load_dwordx4 v[6:9], v177, s[58:59]
	s_nop 0
	global_load_dwordx4 v[2:5], v175, s[58:59]
	s_nop 0
	global_load_dwordx4 v[10:13], v173, s[58:59]
	s_nop 0
	global_load_dwordx4 v[14:17], v171, s[58:59]
	v_lshl_add_u32 v167, v188, 1, s2
	v_add_u32_e32 v169, v167, v187
	ds_read_b128 v[192:195], v169
	ds_read_b128 v[206:209], v169 offset:2048
	ds_read_b128 v[210:213], v169 offset:4096
	ds_read_b128 v[214:217], v169 offset:6144
	ds_read_b128 v[218:221], v169 offset:8192
	ds_read_b128 v[222:225], v169 offset:10240
	ds_read_b128 v[226:229], v169 offset:12288
	ds_read_b128 v[230:233], v169 offset:14336
	v_add_u32_e32 v167, v167, v186
	ds_read_b128 v[234:237], v167 offset:32768
	ds_read_b128 v[238:241], v167 offset:34816
	ds_read_b128 v[242:245], v167 offset:36864
	ds_read_b128 v[246:249], v167 offset:38912
	s_cmp_lg_u32 s101, 0
	s_cbranch_scc1 .Lstg_134_b
	s_waitcnt lgkmcnt(3)
	v_mfma_f32_16x16x32_bf16 v[34:37], v[234:237], v[192:195], v[34:37]
	s_waitcnt lgkmcnt(2)
	v_mfma_f32_16x16x32_bf16 v[38:41], v[238:241], v[192:195], v[38:41]
	s_waitcnt lgkmcnt(1)
	v_mfma_f32_16x16x32_bf16 v[42:45], v[242:245], v[192:195], v[42:45]
	s_waitcnt lgkmcnt(0)
	v_mfma_f32_16x16x32_bf16 v[46:49], v[246:249], v[192:195], v[46:49]
	v_mfma_f32_16x16x32_bf16 v[50:53], v[234:237], v[206:209], v[50:53]
	v_mfma_f32_16x16x32_bf16 v[54:57], v[238:241], v[206:209], v[54:57]
	v_mfma_f32_16x16x32_bf16 v[58:61], v[242:245], v[206:209], v[58:61]
	v_mfma_f32_16x16x32_bf16 v[62:65], v[246:249], v[206:209], v[62:65]
	v_mfma_f32_16x16x32_bf16 v[66:69], v[234:237], v[210:213], v[66:69]
	v_mfma_f32_16x16x32_bf16 v[70:73], v[238:241], v[210:213], v[70:73]
	v_mfma_f32_16x16x32_bf16 v[74:77], v[242:245], v[210:213], v[74:77]
	v_mfma_f32_16x16x32_bf16 v[78:81], v[246:249], v[210:213], v[78:81]
	v_mfma_f32_16x16x32_bf16 v[82:85], v[234:237], v[214:217], v[82:85]
	v_mfma_f32_16x16x32_bf16 v[86:89], v[238:241], v[214:217], v[86:89]
	v_mfma_f32_16x16x32_bf16 v[90:93], v[242:245], v[214:217], v[90:93]
	v_mfma_f32_16x16x32_bf16 v[94:97], v[246:249], v[214:217], v[94:97]
	v_mfma_f32_16x16x32_bf16 v[98:101], v[234:237], v[218:221], v[98:101]
	v_mfma_f32_16x16x32_bf16 v[102:105], v[238:241], v[218:221], v[102:105]
	v_mfma_f32_16x16x32_bf16 v[106:109], v[242:245], v[218:221], v[106:109]
	v_mfma_f32_16x16x32_bf16 v[110:113], v[246:249], v[218:221], v[110:113]
	v_mfma_f32_16x16x32_bf16 v[114:117], v[234:237], v[222:225], v[114:117]
	v_mfma_f32_16x16x32_bf16 v[118:121], v[238:241], v[222:225], v[118:121]
	v_mfma_f32_16x16x32_bf16 v[122:125], v[242:245], v[222:225], v[122:125]
	v_mfma_f32_16x16x32_bf16 v[126:129], v[246:249], v[222:225], v[126:129]
	v_mfma_f32_16x16x32_bf16 v[130:133], v[234:237], v[226:229], v[130:133]
	v_mfma_f32_16x16x32_bf16 v[134:137], v[238:241], v[226:229], v[134:137]
	v_mfma_f32_16x16x32_bf16 v[138:141], v[242:245], v[226:229], v[138:141]
	v_mfma_f32_16x16x32_bf16 v[142:145], v[246:249], v[226:229], v[142:145]
	v_mfma_f32_16x16x32_bf16 v[146:149], v[234:237], v[230:233], v[146:149]
	v_mfma_f32_16x16x32_bf16 v[150:153], v[238:241], v[230:233], v[150:153]
	v_mfma_f32_16x16x32_bf16 v[154:157], v[242:245], v[230:233], v[154:157]
	v_mfma_f32_16x16x32_bf16 v[158:161], v[246:249], v[230:233], v[158:161]

; DI f32x4 mfma16(bf16x8 a, bf16x8 b, f32x4 c) { return __builtin_amdgcn_mfma_f32_16x16x32_bf16(a, b, c, 0, 0, 0); }
; #pragma unroll
;   for (int ks = KS0; ks < KS1; ++ks) {
;     bf16x8 af[8], bfr[4];
; #pragma unroll
;     for (int i = 0; i < 8; ++i) {
;       const int r = wm * 128 + i * 16 + (lane & 15);
;       af[i] = *(const bf16x8*)(S + r * 64 + (((ks * 4 + (lane >> 4)) ^ ((r >> 1) & 7)) << 3));
;     }
; #pragma unroll
;     for (int j = 0; j < 4; ++j) {
;       const int r = wn * 64 + j * 16 + (lane & 15);
;       bfr[j] = *(const bf16x8*)(S + 16384 + r * 64 + (((ks * 4 + (lane >> 4)) ^ ((r >> 1) & 7)) << 3));
;     }
;     __builtin_amdgcn_s_setprio(1);
; #pragma unroll
;     for (int i = 0; i < 8; ++i)
; #pragma unroll
;       for (int j = 0; j < 4; ++j) acc[i][j] = mfma16(bfr[j], af[i], acc[i][j]);
;     __builtin_amdgcn_s_setprio(0);
;   }
; }
; DI void gemm8_accum(f32x4 (&acc)[8][4], const bf16_t* a, size_t lda, const bf16_t* b, size_t ldb, int nkb, bf16_t* L,
;                     const bool pre, const bf16_t* an, size_t ldan, const bf16_t* bn, size_t ldbn) {
;     ...
;   for (int kb = 0; kb + 2 < nkb; ++kb) {
;     __syncthreads();
;     g8_store1(L + ((kb + 1) & 1) * 32768, ra, lrow, lch);
;     g8_load1o(ra, a + (kb + 2) * 64, offa);
;     __builtin_amdgcn_sched_barrier(0);
;     g8_compute<0, 1>(acc, L + (kb & 1) * 32768, wm, wn, lane);
;     __builtin_amdgcn_sched_barrier(0);
;     g8_store1(L + ((kb + 1) & 1) * 32768 + 16384, rb, lrow, lch);
;     g8_load1o(rb, b + (kb + 2) * 64, offb);
;     __builtin_amdgcn_sched_barrier(0);
;     g8_compute<1, 2>(acc, L + (kb & 1) * 32768, wm, wn, lane);
;   }
.Lstg_778_a:
	s_waitcnt vmcnt(5)
	ds_write_b128 v191, v[22:25]
	ds_write_b128 v191, v[18:21] offset:8192
	ds_write_b128 v191, v[26:29] offset:16384
	s_waitcnt vmcnt(4)
	ds_write_b128 v191, v[30:33] offset:24576
	s_add_u32 s54, s52, s0
	s_addc_u32 s55, s53, s1
	global_load_dwordx4 v[22:25], v187, s[54:55]
	global_load_dwordx4 v[26:29], v183, s[54:55]
	global_load_dwordx4 v[18:21], v185, s[54:55]
	s_nop 0
	global_load_dwordx4 v[30:33], v181, s[54:55]
	s_and_b32 s2, s2, 0x8000
	s_lshl_b32 s2, s2, 1
	s_add_i32 s2, s2, 0
	v_lshl_add_u32 v202, v169, 1, s2
	v_add_u32_e32 v203, v202, v188
	ds_read_b128 v[192:195], v203
	ds_read_b128 v[198:201], v203 offset:2048
	ds_read_b128 v[206:209], v203 offset:4096
	ds_read_b128 v[210:213], v203 offset:6144
	ds_read_b128 v[214:217], v203 offset:8192
	ds_read_b128 v[218:221], v203 offset:10240
	ds_read_b128 v[222:225], v203 offset:12288
	ds_read_b128 v[226:229], v203 offset:14336
	v_add_u32_e32 v202, v202, v171
	ds_read_b128 v[230:233], v202 offset:32768
	ds_read_b128 v[234:237], v202 offset:34816
	ds_read_b128 v[238:241], v202 offset:36864
	ds_read_b128 v[242:245], v202 offset:38912
	s_waitcnt lgkmcnt(3)
	v_mfma_f32_16x16x32_bf16 v[158:161], v[230:233], v[192:195], v[158:161]
	s_waitcnt lgkmcnt(2)
	v_mfma_f32_16x16x32_bf16 v[154:157], v[234:237], v[192:195], v[154:157]
	s_waitcnt lgkmcnt(1)
	v_mfma_f32_16x16x32_bf16 v[150:153], v[238:241], v[192:195], v[150:153]
	s_waitcnt lgkmcnt(0)
	v_mfma_f32_16x16x32_bf16 v[146:149], v[242:245], v[192:195], v[146:149]
	v_mfma_f32_16x16x32_bf16 v[142:145], v[230:233], v[198:201], v[142:145]
	v_mfma_f32_16x16x32_bf16 v[138:141], v[234:237], v[198:201], v[138:141]
	v_mfma_f32_16x16x32_bf16 v[134:137], v[238:241], v[198:201], v[134:137]
	v_mfma_f32_16x16x32_bf16 v[130:133], v[242:245], v[198:201], v[130:133]
	v_mfma_f32_16x16x32_bf16 v[126:129], v[230:233], v[206:209], v[126:129]
	v_mfma_f32_16x16x32_bf16 v[122:125], v[234:237], v[206:209], v[122:125]
	v_mfma_f32_16x16x32_bf16 v[118:121], v[238:241], v[206:209], v[118:121]
	v_mfma_f32_16x16x32_bf16 v[114:117], v[242:245], v[206:209], v[114:117]
	v_mfma_f32_16x16x32_bf16 v[110:113], v[230:233], v[210:213], v[110:113]
	v_mfma_f32_16x16x32_bf16 v[106:109], v[234:237], v[210:213], v[106:109]
	v_mfma_f32_16x16x32_bf16 v[102:105], v[238:241], v[210:213], v[102:105]
	v_mfma_f32_16x16x32_bf16 v[98:101], v[242:245], v[210:213], v[98:101]
	v_mfma_f32_16x16x32_bf16 v[94:97], v[230:233], v[214:217], v[94:97]
	v_mfma_f32_16x16x32_bf16 v[90:93], v[234:237], v[214:217], v[90:93]
	v_mfma_f32_16x16x32_bf16 v[86:89], v[238:241], v[214:217], v[86:89]
	v_mfma_f32_16x16x32_bf16 v[82:85], v[242:245], v[214:217], v[82:85]
	v_mfma_f32_16x16x32_bf16 v[78:81], v[230:233], v[218:221], v[78:81]
	v_mfma_f32_16x16x32_bf16 v[74:77], v[234:237], v[218:221], v[74:77]
	v_mfma_f32_16x16x32_bf16 v[70:73], v[238:241], v[218:221], v[70:73]
	v_mfma_f32_16x16x32_bf16 v[66:69], v[242:245], v[218:221], v[66:69]
	v_mfma_f32_16x16x32_bf16 v[62:65], v[230:233], v[222:225], v[62:65]
	v_mfma_f32_16x16x32_bf16 v[58:61], v[234:237], v[222:225], v[58:61]
	v_mfma_f32_16x16x32_bf16 v[54:57], v[238:241], v[222:225], v[54:57]
	v_mfma_f32_16x16x32_bf16 v[50:53], v[242:245], v[222:225], v[50:53]
	v_mfma_f32_16x16x32_bf16 v[46:49], v[230:233], v[226:229], v[46:49]
	v_mfma_f32_16x16x32_bf16 v[42:45], v[234:237], v[226:229], v[42:45]
	v_mfma_f32_16x16x32_bf16 v[38:41], v[238:241], v[226:229], v[38:41]
	v_mfma_f32_16x16x32_bf16 v[34:37], v[242:245], v[226:229], v[34:37]
	s_waitcnt vmcnt(7)
	ds_write_b128 v191, v[14:17] offset:32768
	s_waitcnt vmcnt(6)
	ds_write_b128 v191, v[2:5] offset:40960
	s_waitcnt vmcnt(5)
	ds_write_b128 v191, v[6:9] offset:49152
	s_waitcnt vmcnt(4)
	ds_write_b128 v191, v[10:13] offset:57344
	s_add_u32 s58, s56, s0
	s_addc_u32 s59, s57, s1
	global_load_dwordx4 v[14:17], v179, s[58:59]
	s_nop 0
	global_load_dwordx4 v[2:5], v177, s[58:59]
	s_nop 0
	global_load_dwordx4 v[6:9], v175, s[58:59]
	s_nop 0
	global_load_dwordx4 v[10:13], v173, s[58:59]
	v_lshl_add_u32 v191, v189, 1, s2
	v_add_u32_e32 v202, v191, v188
	ds_read_b128 v[192:195], v202
	ds_read_b128 v[198:201], v202 offset:2048
	ds_read_b128 v[206:209], v202 offset:4096
	ds_read_b128 v[210:213], v202 offset:6144
	ds_read_b128 v[214:217], v202 offset:8192
	ds_read_b128 v[218:221], v202 offset:10240
	ds_read_b128 v[222:225], v202 offset:12288
	ds_read_b128 v[226:229], v202 offset:14336
	v_add_u32_e32 v191, v191, v171
	ds_read_b128 v[230:233], v191 offset:32768
	ds_read_b128 v[234:237], v191 offset:34816
	ds_read_b128 v[238:241], v191 offset:36864
	ds_read_b128 v[242:245], v191 offset:38912
	s_cmp_lg_u32 s101, 0
	s_cbranch_scc1 .Lstg_778_b
	s_waitcnt lgkmcnt(3)
	v_mfma_f32_16x16x32_bf16 v[158:161], v[230:233], v[192:195], v[158:161]
	s_waitcnt lgkmcnt(2)
	v_mfma_f32_16x16x32_bf16 v[154:157], v[234:237], v[192:195], v[154:157]
	s_waitcnt lgkmcnt(1)
	v_mfma_f32_16x16x32_bf16 v[150:153], v[238:241], v[192:195], v[150:153]
	s_waitcnt lgkmcnt(0)
	v_mfma_f32_16x16x32_bf16 v[146:149], v[242:245], v[192:195], v[146:149]
	v_mfma_f32_16x16x32_bf16 v[142:145], v[230:233], v[198:201], v[142:145]
	v_mfma_f32_16x16x32_bf16 v[138:141], v[234:237], v[198:201], v[138:141]
	v_mfma_f32_16x16x32_bf16 v[134:137], v[238:241], v[198:201], v[134:137]
	v_mfma_f32_16x16x32_bf16 v[130:133], v[242:245], v[198:201], v[130:133]
	v_mfma_f32_16x16x32_bf16 v[126:129], v[230:233], v[206:209], v[126:129]
	v_mfma_f32_16x16x32_bf16 v[122:125], v[234:237], v[206:209], v[122:125]
	v_mfma_f32_16x16x32_bf16 v[118:121], v[238:241], v[206:209], v[118:121]
	v_mfma_f32_16x16x32_bf16 v[114:117], v[242:245], v[206:209], v[114:117]
	v_mfma_f32_16x16x32_bf16 v[110:113], v[230:233], v[210:213], v[110:113]
	v_mfma_f32_16x16x32_bf16 v[106:109], v[234:237], v[210:213], v[106:109]
	v_mfma_f32_16x16x32_bf16 v[102:105], v[238:241], v[210:213], v[102:105]
	v_mfma_f32_16x16x32_bf16 v[98:101], v[242:245], v[210:213], v[98:101]
	v_mfma_f32_16x16x32_bf16 v[94:97], v[230:233], v[214:217], v[94:97]
	v_mfma_f32_16x16x32_bf16 v[90:93], v[234:237], v[214:217], v[90:93]
	v_mfma_f32_16x16x32_bf16 v[86:89], v[238:241], v[214:217], v[86:89]
	v_mfma_f32_16x16x32_bf16 v[82:85], v[242:245], v[214:217], v[82:85]
	v_mfma_f32_16x16x32_bf16 v[78:81], v[230:233], v[218:221], v[78:81]
	v_mfma_f32_16x16x32_bf16 v[74:77], v[234:237], v[218:221], v[74:77]
	v_mfma_f32_16x16x32_bf16 v[70:73], v[238:241], v[218:221], v[70:73]
	v_mfma_f32_16x16x32_bf16 v[66:69], v[242:245], v[218:221], v[66:69]
	v_mfma_f32_16x16x32_bf16 v[62:65], v[230:233], v[222:225], v[62:65]
	v_mfma_f32_16x16x32_bf16 v[58:61], v[234:237], v[222:225], v[58:61]
	v_mfma_f32_16x16x32_bf16 v[54:57], v[238:241], v[222:225], v[54:57]
	v_mfma_f32_16x16x32_bf16 v[50:53], v[242:245], v[222:225], v[50:53]
	v_mfma_f32_16x16x32_bf16 v[46:49], v[230:233], v[226:229], v[46:49]
	v_mfma_f32_16x16x32_bf16 v[42:45], v[234:237], v[226:229], v[42:45]
	v_mfma_f32_16x16x32_bf16 v[38:41], v[238:241], v[226:229], v[38:41]
	v_mfma_f32_16x16x32_bf16 v[34:37], v[242:245], v[226:229], v[34:37]

; DI void gemm8_accum(f32x4 (&acc)[8][4], const bf16_t* a, size_t lda, const bf16_t* b, size_t ldb, int nkb, bf16_t* L,
;                     const bool pre, const bf16_t* an, size_t ldan, const bf16_t* bn, size_t ldbn) {
;     ...
;   __syncthreads();
;   g8_store1(L + 32768, ra, lrow, lch);
;   g8_load1(ra, an, ldan, 0, lrow, lch);
;   __builtin_amdgcn_sched_barrier(0);
;   g8_compute<0, 1>(acc, L, wm, wn, lane);
;   __builtin_amdgcn_sched_barrier(0);
;   g8_store1(L + 32768 + 16384, rb, lrow, lch);
;   g8_load1(rb, bn, ldbn, 0, lrow, lch);
;   __builtin_amdgcn_sched_barrier(0);
;   g8_compute<1, 2>(acc, L, wm, wn, lane);
;   __syncthreads();
;   g8_store1(L, ra, lrow, lch);
;   __builtin_amdgcn_sched_barrier(0);
;   g8_compute<0, 1>(acc, L + 32768, wm, wn, lane);
.Lstg_778_c:
	s_mul_i32 s0, s13, 0x2a30
	s_movk_i32 s25, 0x1518
	s_add_u32 s2, s16, s0
	v_mad_u64_u32 v[180:181], s[0:1], v190, s25, v[170:171]
	s_addc_u32 s3, s17, 0
	v_mov_b32_e32 v181, v1
	v_lshl_add_u64 v[172:173], v[180:181], 1, s[2:3]
	v_add_u32_e32 v174, 0x54600, v180
	v_mov_b32_e32 v175, v1
	v_add_u32_e32 v182, 0xa8c00, v180
	v_mov_b32_e32 v183, v1
	v_add_u32_e32 v180, 0xfd200, v180
	v_lshl_add_u64 v[176:177], v[174:175], 1, s[2:3]
	v_lshl_add_u64 v[182:183], v[182:183], 1, s[2:3]
	v_lshl_add_u64 v[184:185], v[180:181], 1, s[2:3]
	s_barrier
	global_load_dwordx4 v[172:175], v[172:173], off offset:2608
	s_nop 0
	global_load_dwordx4 v[176:179], v[176:177], off offset:2608
	s_nop 0
	global_load_dwordx4 v[180:183], v[182:183], off offset:2608
	s_nop 0
	global_load_dwordx4 v[184:187], v[184:185], off offset:2608
	s_mul_i32 s0, s7, 0x2a3000
	s_lshl_b32 s1, s6, 1
	v_readlane_b32 s6, v252, 1
	v_readlane_b32 s7, v252, 2
	s_add_u32 s6, s6, s1
	s_addc_u32 s7, s7, 0
	s_add_i32 s20, 0, 0x10000
	v_add3_u32 v170, s20, v165, v167
	s_waitcnt vmcnt(11)
	ds_write_b128 v170, v[22:25]
	s_waitcnt vmcnt(9)
	ds_write_b128 v170, v[18:21] offset:8192
	ds_write_b128 v170, v[26:29] offset:16384
	s_waitcnt vmcnt(8)
	ds_write_b128 v170, v[30:33] offset:24576
	v_lshlrev_b32_e32 v170, 1, v169
	v_add_u32_e32 v169, 0, v170
	v_add_u32_e32 v194, v169, v188
	ds_read_b128 v[18:21], v194
	ds_read_b128 v[22:25], v194 offset:2048
	ds_read_b128 v[26:29], v194 offset:4096
	ds_read_b128 v[30:33], v194 offset:6144
	ds_read_b128 v[190:193], v194 offset:8192
	ds_read_b128 v[198:201], v194 offset:10240
	ds_read_b128 v[206:209], v194 offset:12288
	ds_read_b128 v[210:213], v194 offset:14336
	v_add_u32_e32 v169, v169, v171
	ds_read_b128 v[214:217], v169 offset:32768
	ds_read_b128 v[218:221], v169 offset:34816
	ds_read_b128 v[222:225], v169 offset:36864
	ds_read_b128 v[226:229], v169 offset:38912
	s_waitcnt lgkmcnt(3)
	v_mfma_f32_16x16x32_bf16 v[158:161], v[214:217], v[18:21], v[158:161]
	s_waitcnt lgkmcnt(2)
	v_mfma_f32_16x16x32_bf16 v[154:157], v[218:221], v[18:21], v[154:157]
	s_waitcnt lgkmcnt(1)
	v_mfma_f32_16x16x32_bf16 v[150:153], v[222:225], v[18:21], v[150:153]
	s_waitcnt lgkmcnt(0)
	v_mfma_f32_16x16x32_bf16 v[18:21], v[226:229], v[18:21], v[146:149]
	v_mfma_f32_16x16x32_bf16 v[142:145], v[214:217], v[22:25], v[142:145]
	v_mfma_f32_16x16x32_bf16 v[138:141], v[218:221], v[22:25], v[138:141]
	v_mfma_f32_16x16x32_bf16 v[134:137], v[222:225], v[22:25], v[134:137]
	v_mfma_f32_16x16x32_bf16 v[22:25], v[226:229], v[22:25], v[130:133]
	v_mfma_f32_16x16x32_bf16 v[126:129], v[214:217], v[26:29], v[126:129]
	v_mfma_f32_16x16x32_bf16 v[122:125], v[218:221], v[26:29], v[122:125]
	v_mfma_f32_16x16x32_bf16 v[118:121], v[222:225], v[26:29], v[118:121]
	v_mfma_f32_16x16x32_bf16 v[26:29], v[226:229], v[26:29], v[114:117]
	v_mfma_f32_16x16x32_bf16 v[110:113], v[214:217], v[30:33], v[110:113]
	v_mfma_f32_16x16x32_bf16 v[106:109], v[218:221], v[30:33], v[106:109]
	v_mfma_f32_16x16x32_bf16 v[102:105], v[222:225], v[30:33], v[102:105]
	v_mfma_f32_16x16x32_bf16 v[30:33], v[226:229], v[30:33], v[98:101]
	v_mfma_f32_16x16x32_bf16 v[94:97], v[214:217], v[190:193], v[94:97]
	v_mfma_f32_16x16x32_bf16 v[90:93], v[218:221], v[190:193], v[90:93]
	v_mfma_f32_16x16x32_bf16 v[86:89], v[222:225], v[190:193], v[86:89]
	v_mfma_f32_16x16x32_bf16 v[82:85], v[226:229], v[190:193], v[82:85]
	v_mfma_f32_16x16x32_bf16 v[78:81], v[214:217], v[198:201], v[78:81]
	v_mfma_f32_16x16x32_bf16 v[74:77], v[218:221], v[198:201], v[74:77]
	v_mfma_f32_16x16x32_bf16 v[70:73], v[222:225], v[198:201], v[70:73]
	v_mfma_f32_16x16x32_bf16 v[66:69], v[226:229], v[198:201], v[66:69]
	v_mfma_f32_16x16x32_bf16 v[62:65], v[214:217], v[206:209], v[62:65]
	v_mfma_f32_16x16x32_bf16 v[58:61], v[218:221], v[206:209], v[58:61]
	v_mfma_f32_16x16x32_bf16 v[54:57], v[222:225], v[206:209], v[54:57]
	v_mfma_f32_16x16x32_bf16 v[50:53], v[226:229], v[206:209], v[50:53]
	v_mfma_f32_16x16x32_bf16 v[46:49], v[214:217], v[210:213], v[46:49]
	v_mfma_f32_16x16x32_bf16 v[42:45], v[218:221], v[210:213], v[42:45]
	v_mfma_f32_16x16x32_bf16 v[38:41], v[222:225], v[210:213], v[38:41]
	v_mfma_f32_16x16x32_bf16 v[34:37], v[226:229], v[210:213], v[34:37]
	v_readlane_b32 s1, v254, 36
	v_mov_b32_e32 v169, v1
	s_nop 0
	v_add3_u32 v98, s1, v165, v167
	v_mov_b32_e32 v167, v1
	v_mov_b32_e32 v165, v1
	s_waitcnt vmcnt(7)
	ds_write_b128 v98, v[14:17]
	s_waitcnt vmcnt(6)
	ds_write_b128 v98, v[2:5] offset:8192
	s_waitcnt vmcnt(5)
	ds_write_b128 v98, v[6:9] offset:16384
	s_waitcnt vmcnt(4)
	ds_write_b128 v98, v[10:13] offset:24576
	v_lshl_add_u64 v[2:3], v[0:1], 1, s[6:7]
	v_lshl_add_u64 v[6:7], v[168:169], 1, s[6:7]
	v_lshl_add_u64 v[10:11], v[166:167], 1, s[6:7]
	v_lshl_add_u64 v[14:15], v[164:165], 1, s[6:7]
	global_load_dwordx4 v[2:5], v[2:3], off
	s_nop 0
	global_load_dwordx4 v[6:9], v[6:7], off
	s_nop 0
	global_load_dwordx4 v[10:13], v[10:11], off
	s_nop 0
	global_load_dwordx4 v[14:17], v[14:15], off
	v_lshlrev_b32_e32 v0, 1, v189
	v_add_u32_e32 v168, 0, v0
	v_add_u32_e32 v169, v168, v188
	ds_read_b128 v[98:101], v169
	ds_read_b128 v[114:117], v169 offset:2048
	ds_read_b128 v[130:133], v169 offset:4096
	ds_read_b128 v[146:149], v169 offset:6144
	ds_read_b128 v[164:167], v169 offset:8192
	ds_read_b128 v[190:193], v169 offset:10240
	ds_read_b128 v[198:201], v169 offset:12288
	ds_read_b128 v[206:209], v169 offset:14336
	v_add_u32_e32 v168, v168, v171
	ds_read_b128 v[210:213], v168 offset:32768
	ds_read_b128 v[214:217], v168 offset:34816
	ds_read_b128 v[218:221], v168 offset:36864
	ds_read_b128 v[222:225], v168 offset:38912
	s_waitcnt lgkmcnt(3)
; DI void gemm8_accum(f32x4 (&acc)[8][4], const bf16_t* a, size_t lda, const bf16_t* b, size_t ldb, int nkb, bf16_t* L,
;                     const bool pre, const bf16_t* an, size_t ldan, const bf16_t* bn, size_t ldbn) {
;     ...
;   g8_compute<1, 2>(acc, L, wm, wn, lane);
;   __syncthreads();
;   g8_store1(L, ra, lrow, lch);
;   __builtin_amdgcn_sched_barrier(0);
;   g8_compute<0, 1>(acc, L + 32768, wm, wn, lane);
;   __builtin_amdgcn_sched_barrier(0);
;   g8_store1(L + 16384, rb, lrow, lch);
;   __builtin_amdgcn_sched_barrier(0);
;   g8_compute<1, 2>(acc, L + 32768, wm, wn, lane);
	v_mfma_f32_16x16x32_bf16 v[158:161], v[210:213], v[98:101], v[158:161]
	s_waitcnt lgkmcnt(2)
	v_mfma_f32_16x16x32_bf16 v[154:157], v[214:217], v[98:101], v[154:157]
	s_waitcnt lgkmcnt(1)
	v_mfma_f32_16x16x32_bf16 v[150:153], v[218:221], v[98:101], v[150:153]
	s_waitcnt lgkmcnt(0)
	v_mfma_f32_16x16x32_bf16 v[18:21], v[222:225], v[98:101], v[18:21]
	v_mfma_f32_16x16x32_bf16 v[98:101], v[210:213], v[114:117], v[142:145]
	v_mfma_f32_16x16x32_bf16 v[138:141], v[214:217], v[114:117], v[138:141]
	v_mfma_f32_16x16x32_bf16 v[134:137], v[218:221], v[114:117], v[134:137]
	v_mfma_f32_16x16x32_bf16 v[22:25], v[222:225], v[114:117], v[22:25]
	v_mfma_f32_16x16x32_bf16 v[114:117], v[210:213], v[130:133], v[126:129]
	v_mfma_f32_16x16x32_bf16 v[122:125], v[214:217], v[130:133], v[122:125]
	v_mfma_f32_16x16x32_bf16 v[118:121], v[218:221], v[130:133], v[118:121]
	v_mfma_f32_16x16x32_bf16 v[26:29], v[222:225], v[130:133], v[26:29]
	v_mfma_f32_16x16x32_bf16 v[110:113], v[210:213], v[146:149], v[110:113]
	v_mfma_f32_16x16x32_bf16 v[106:109], v[214:217], v[146:149], v[106:109]
	v_mfma_f32_16x16x32_bf16 v[102:105], v[218:221], v[146:149], v[102:105]
	v_mfma_f32_16x16x32_bf16 v[30:33], v[222:225], v[146:149], v[30:33]
	v_mfma_f32_16x16x32_bf16 v[94:97], v[210:213], v[164:167], v[94:97]
	v_mfma_f32_16x16x32_bf16 v[90:93], v[214:217], v[164:167], v[90:93]
	v_mfma_f32_16x16x32_bf16 v[86:89], v[218:221], v[164:167], v[86:89]
	v_mfma_f32_16x16x32_bf16 v[82:85], v[222:225], v[164:167], v[82:85]
	v_mfma_f32_16x16x32_bf16 v[78:81], v[210:213], v[190:193], v[78:81]
	v_mfma_f32_16x16x32_bf16 v[74:77], v[214:217], v[190:193], v[74:77]
	v_mfma_f32_16x16x32_bf16 v[70:73], v[218:221], v[190:193], v[70:73]
	v_mfma_f32_16x16x32_bf16 v[66:69], v[222:225], v[190:193], v[66:69]
	v_mfma_f32_16x16x32_bf16 v[62:65], v[210:213], v[198:201], v[62:65]
	v_mfma_f32_16x16x32_bf16 v[58:61], v[214:217], v[198:201], v[58:61]
	v_mfma_f32_16x16x32_bf16 v[54:57], v[218:221], v[198:201], v[54:57]
	v_mfma_f32_16x16x32_bf16 v[50:53], v[222:225], v[198:201], v[50:53]
	v_mfma_f32_16x16x32_bf16 v[46:49], v[210:213], v[206:209], v[46:49]
	v_mfma_f32_16x16x32_bf16 v[42:45], v[214:217], v[206:209], v[42:45]
	v_mfma_f32_16x16x32_bf16 v[38:41], v[218:221], v[206:209], v[38:41]
	v_mfma_f32_16x16x32_bf16 v[34:37], v[222:225], v[206:209], v[34:37]
	s_barrier
	s_waitcnt vmcnt(7)
	ds_write_b128 v163, v[172:175]
	s_waitcnt vmcnt(6)
	ds_write_b128 v163, v[176:179] offset:8192
	s_waitcnt vmcnt(5)
	ds_write_b128 v163, v[180:183] offset:16384
	s_waitcnt vmcnt(4)
	ds_write_b128 v163, v[184:187] offset:24576
	v_add3_u32 v168, s20, v170, v188
	ds_read_b128 v[126:129], v168
	ds_read_b128 v[130:133], v168 offset:2048
	ds_read_b128 v[142:145], v168 offset:4096
	ds_read_b128 v[146:149], v168 offset:6144
	ds_read_b128 v[164:167], v168 offset:8192
	ds_read_b128 v[172:175], v168 offset:10240
	ds_read_b128 v[176:179], v168 offset:12288
	ds_read_b128 v[180:183], v168 offset:14336
	v_add3_u32 v168, s1, v170, v171
	ds_read_b128 v[184:187], v168
	ds_read_b128 v[190:193], v168 offset:2048
	ds_read_b128 v[198:201], v168 offset:4096
	ds_read_b128 v[206:209], v168 offset:6144
	s_waitcnt lgkmcnt(3)
	v_mfma_f32_16x16x32_bf16 v[158:161], v[184:187], v[126:129], v[158:161]
	s_waitcnt lgkmcnt(2)
	v_mfma_f32_16x16x32_bf16 v[154:157], v[190:193], v[126:129], v[154:157]
	s_waitcnt lgkmcnt(1)
	v_mfma_f32_16x16x32_bf16 v[150:153], v[198:201], v[126:129], v[150:153]
	s_waitcnt lgkmcnt(0)
	v_mfma_f32_16x16x32_bf16 v[18:21], v[206:209], v[126:129], v[18:21]
	v_mfma_f32_16x16x32_bf16 v[98:101], v[184:187], v[130:133], v[98:101]
	v_mfma_f32_16x16x32_bf16 v[126:129], v[190:193], v[130:133], v[138:141]
	v_mfma_f32_16x16x32_bf16 v[134:137], v[198:201], v[130:133], v[134:137]
	v_mfma_f32_16x16x32_bf16 v[130:133], v[206:209], v[130:133], v[22:25]
	v_mfma_f32_16x16x32_bf16 v[114:117], v[184:187], v[142:145], v[114:117]
	v_mfma_f32_16x16x32_bf16 v[122:125], v[190:193], v[142:145], v[122:125]
	v_mfma_f32_16x16x32_bf16 v[118:121], v[198:201], v[142:145], v[118:121]
	v_mfma_f32_16x16x32_bf16 v[26:29], v[206:209], v[142:145], v[26:29]
	v_mfma_f32_16x16x32_bf16 v[110:113], v[184:187], v[146:149], v[110:113]
	v_mfma_f32_16x16x32_bf16 v[106:109], v[190:193], v[146:149], v[106:109]
	v_mfma_f32_16x16x32_bf16 v[102:105], v[198:201], v[146:149], v[102:105]
	v_mfma_f32_16x16x32_bf16 v[138:141], v[206:209], v[146:149], v[30:33]
	v_mfma_f32_16x16x32_bf16 v[142:145], v[184:187], v[164:167], v[94:97]
	v_mfma_f32_16x16x32_bf16 v[90:93], v[190:193], v[164:167], v[90:93]
	v_mfma_f32_16x16x32_bf16 v[146:149], v[198:201], v[164:167], v[86:89]
	v_mfma_f32_16x16x32_bf16 v[82:85], v[206:209], v[164:167], v[82:85]
	v_mfma_f32_16x16x32_bf16 v[164:167], v[184:187], v[172:175], v[78:81]
	v_mfma_f32_16x16x32_bf16 v[74:77], v[190:193], v[172:175], v[74:77]
	v_mfma_f32_16x16x32_bf16 v[210:213], v[198:201], v[172:175], v[70:73]
	v_mfma_f32_16x16x32_bf16 v[66:69], v[206:209], v[172:175], v[66:69]
	v_mfma_f32_16x16x32_bf16 v[172:175], v[184:187], v[176:179], v[62:65]
	v_mfma_f32_16x16x32_bf16 v[58:61], v[190:193], v[176:179], v[58:61]
	v_mfma_f32_16x16x32_bf16 v[214:217], v[198:201], v[176:179], v[54:57]
	v_mfma_f32_16x16x32_bf16 v[50:53], v[206:209], v[176:179], v[50:53]
	v_mfma_f32_16x16x32_bf16 v[176:179], v[184:187], v[180:183], v[46:49]
	v_mfma_f32_16x16x32_bf16 v[184:187], v[190:193], v[180:183], v[42:45]
	v_mfma_f32_16x16x32_bf16 v[190:193], v[198:201], v[180:183], v[38:41]
	v_mfma_f32_16x16x32_bf16 v[180:183], v[206:209], v[180:183], v[34:37]
	s_waitcnt vmcnt(3)
	ds_write_b128 v163, v[2:5] offset:32768
	s_waitcnt vmcnt(2)
	ds_write_b128 v163, v[6:9] offset:40960
	s_waitcnt vmcnt(1)
; DI float bflo(unsigned u) { return __uint_as_float(u << 16); }
; DI float bfhi(unsigned u) { return __uint_as_float(u & 0xffff0000u); }
; DI float sigmoidf(float x) { return __builtin_amdgcn_rcpf(1.f + __expf(-x)); }
; DI float inv_sigmoidf(float x) { return 1.f + __expf(-x); }
; DI void gemm8_accum(f32x4 (&acc)[8][4], const bf16_t* a, size_t lda, const bf16_t* b, size_t ldb, int nkb, bf16_t* L,
;                     const bool pre, const bf16_t* an, size_t ldan, const bf16_t* bn, size_t ldbn) {
;     ...
;   g8_store1(L + 16384, rb, lrow, lch);
;   __builtin_amdgcn_sched_barrier(0);
;   g8_compute<1, 2>(acc, L + 32768, wm, wn, lane);
;   __syncthreads();
; }
; __global__ void __launch_bounds__(512, 2) mega(Params p) {
;     ...
;       gemm8_epi(acc8, m0, n0, [&](int m, int n, f32x4& a) {
;         uint2 ua = *(const uint2*)(z + (size_t)m * ZS + C_MA + n);
;         uint2 ub = *(const uint2*)(z + (size_t)m * ZS + C_MB + n);
;         a[0] *= sigmoidf(bflo(ua.x)) * inv_sigmoidf(bflo(ub.x));
;         a[1] *= sigmoidf(bfhi(ua.x)) * inv_sigmoidf(bfhi(ub.x));
;         a[2] *= sigmoidf(bflo(ua.y)) * inv_sigmoidf(bflo(ub.y));
;         a[3] *= sigmoidf(bfhi(ua.y)) * inv_sigmoidf(bfhi(ub.y));
	ds_write_b128 v163, v[10:13] offset:49152
	s_waitcnt vmcnt(0)
	ds_write_b128 v163, v[14:17] offset:57344
	v_add3_u32 v6, s20, v0, v188
	ds_read_b128 v[2:5], v6
	ds_read_b128 v[34:37], v6 offset:2048
	ds_read_b128 v[42:45], v6 offset:4096
	ds_read_b128 v[198:201], v6 offset:6144
	ds_read_b128 v[206:209], v6 offset:8192
	ds_read_b128 v[218:221], v6 offset:10240
	ds_read_b128 v[222:225], v6 offset:12288
	ds_read_b128 v[226:229], v6 offset:14336
	v_add3_u32 v0, s1, v0, v171
	ds_read_b128 v[168:171], v0
	ds_read_b128 v[230:233], v0 offset:2048
	ds_read_b128 v[234:237], v0 offset:4096
	ds_read_b128 v[238:241], v0 offset:6144
	s_waitcnt lgkmcnt(3)
	v_mfma_f32_16x16x32_bf16 v[158:161], v[168:171], v[2:5], v[158:161]
	s_waitcnt lgkmcnt(2)
	v_mfma_f32_16x16x32_bf16 v[6:9], v[230:233], v[2:5], v[154:157]
	s_waitcnt lgkmcnt(1)
	v_mfma_f32_16x16x32_bf16 v[10:13], v[234:237], v[2:5], v[150:153]
	s_waitcnt lgkmcnt(0)
	v_mfma_f32_16x16x32_bf16 v[14:17], v[238:241], v[2:5], v[18:21]
	v_mfma_f32_16x16x32_bf16 v[22:25], v[168:171], v[34:37], v[98:101]
	v_mfma_f32_16x16x32_bf16 v[30:33], v[230:233], v[34:37], v[126:129]
	v_mfma_f32_16x16x32_bf16 v[38:41], v[234:237], v[34:37], v[134:137]
	v_mfma_f32_16x16x32_bf16 v[46:49], v[238:241], v[34:37], v[130:133]
	v_mfma_f32_16x16x32_bf16 v[54:57], v[168:171], v[42:45], v[114:117]
	v_mfma_f32_16x16x32_bf16 v[62:65], v[230:233], v[42:45], v[122:125]
	v_mfma_f32_16x16x32_bf16 v[70:73], v[234:237], v[42:45], v[118:121]
	v_mfma_f32_16x16x32_bf16 v[78:81], v[238:241], v[42:45], v[26:29]
	v_mfma_f32_16x16x32_bf16 v[86:89], v[168:171], v[198:201], v[110:113]
	v_mfma_f32_16x16x32_bf16 v[94:97], v[230:233], v[198:201], v[106:109]
	v_mfma_f32_16x16x32_bf16 v[102:105], v[234:237], v[198:201], v[102:105]
	v_mfma_f32_16x16x32_bf16 v[110:113], v[238:241], v[198:201], v[138:141]
	v_mfma_f32_16x16x32_bf16 v[118:121], v[168:171], v[206:209], v[142:145]
	v_mfma_f32_16x16x32_bf16 v[126:129], v[230:233], v[206:209], v[90:93]
	v_mfma_f32_16x16x32_bf16 v[122:125], v[234:237], v[206:209], v[146:149]
	v_mfma_f32_16x16x32_bf16 v[114:117], v[238:241], v[206:209], v[82:85]
	v_mfma_f32_16x16x32_bf16 v[106:109], v[168:171], v[218:221], v[164:167]
	v_mfma_f32_16x16x32_bf16 v[98:101], v[230:233], v[218:221], v[74:77]
	v_mfma_f32_16x16x32_bf16 v[90:93], v[234:237], v[218:221], v[210:213]
	v_mfma_f32_16x16x32_bf16 v[82:85], v[238:241], v[218:221], v[66:69]
	v_mfma_f32_16x16x32_bf16 v[74:77], v[168:171], v[222:225], v[172:175]
	v_mfma_f32_16x16x32_bf16 v[66:69], v[230:233], v[222:225], v[58:61]
	v_mfma_f32_16x16x32_bf16 v[58:61], v[234:237], v[222:225], v[214:217]
	v_mfma_f32_16x16x32_bf16 v[50:53], v[238:241], v[222:225], v[50:53]
	v_mfma_f32_16x16x32_bf16 v[42:45], v[168:171], v[226:229], v[176:179]
	v_mfma_f32_16x16x32_bf16 v[34:37], v[230:233], v[226:229], v[184:187]
	v_mfma_f32_16x16x32_bf16 v[26:29], v[234:237], v[226:229], v[190:193]
	v_mfma_f32_16x16x32_bf16 v[18:21], v[238:241], v[226:229], v[180:183]
	v_mov_b32_e32 v0, v196
	s_barrier
	v_mov_b64_e32 v[136:137], s[16:17]
	v_ashrrev_i32_e32 v3, 1, v0
	v_and_b32_e32 v2, 0xc0, v0
	v_and_b32_e32 v3, 0xffffff80, v3
	v_and_or_b32 v4, v0, 15, s13
	v_lshrrev_b32_e32 v0, 2, v0
	v_add_u32_e32 v142, v4, v3
	v_and_b32_e32 v0, 12, v0
	v_or3_b32 v0, v2, v0, s12
	v_mad_i64_i32 v[2:3], s[26:27], v142, s35, v[136:137]
	s_mov_b64 s[30:31], 0x1a30
	s_mov_b64 s[42:43], 0x2230
	v_lshl_add_u64 v[138:139], v[2:3], 0, s[30:31]
	v_lshlrev_b32_e32 v0, 1, v0
	v_lshl_add_u64 v[140:141], v[2:3], 0, s[42:43]
	v_lshl_add_u64 v[4:5], v[138:139], 0, v[0:1]
	v_lshl_add_u64 v[2:3], v[140:141], 0, v[0:1]
	s_mov_b32 s88, 0x2a300
	s_mov_b32 s89, 0
	v_mov_b64_e32 v[246:247], v[4:5]
	global_load_dwordx2 v[198:199], v[246:247], off
	global_load_dwordx2 v[200:201], v[246:247], off offset:2048
	global_load_dwordx2 v[202:203], v[246:247], off offset:32
	global_load_dwordx2 v[204:205], v[246:247], off offset:2080
	global_load_dwordx2 v[206:207], v[246:247], off offset:64
	global_load_dwordx2 v[208:209], v[246:247], off offset:2112
	global_load_dwordx2 v[210:211], v[246:247], off offset:96
	global_load_dwordx2 v[212:213], v[246:247], off offset:2144
	v_lshl_add_u64 v[246:247], v[246:247], 0, s[88:89]
	global_load_dwordx2 v[214:215], v[246:247], off
	global_load_dwordx2 v[216:217], v[246:247], off offset:2048
	global_load_dwordx2 v[218:219], v[246:247], off offset:32
	global_load_dwordx2 v[220:221], v[246:247], off offset:2080
	global_load_dwordx2 v[222:223], v[246:247], off offset:64
	global_load_dwordx2 v[224:225], v[246:247], off offset:2112
	global_load_dwordx2 v[226:227], v[246:247], off offset:96
	global_load_dwordx2 v[228:229], v[246:247], off offset:2144
	v_lshl_add_u64 v[246:247], v[246:247], 0, s[88:89]
	global_load_dwordx2 v[230:231], v[246:247], off
	global_load_dwordx2 v[232:233], v[246:247], off offset:2048
	global_load_dwordx2 v[234:235], v[246:247], off offset:32
	global_load_dwordx2 v[236:237], v[246:247], off offset:2080
	global_load_dwordx2 v[238:239], v[246:247], off offset:64
	global_load_dwordx2 v[240:241], v[246:247], off offset:2112
	global_load_dwordx2 v[242:243], v[246:247], off offset:96
	global_load_dwordx2 v[244:245], v[246:247], off offset:2144
	s_waitcnt vmcnt(23)
	v_mov_b64_e32 v[4:5], v[198:199]
	v_lshl_add_u64 v[246:247], v[246:247], 0, s[88:89]
	global_load_dwordx2 v[198:199], v[246:247], off
	v_or_b32_e32 v134, 32, v0
	s_waitcnt vmcnt(23)
; DI float bflo(unsigned u) { return __uint_as_float(u << 16); }
; DI float bfhi(unsigned u) { return __uint_as_float(u & 0xffff0000u); }
; DI float sigmoidf(float x) { return __builtin_amdgcn_rcpf(1.f + __expf(-x)); }
; DI float inv_sigmoidf(float x) { return 1.f + __expf(-x); }
; __global__ void __launch_bounds__(512, 2) mega(Params p) {
;     ...
;       gemm8_epi(acc8, m0, n0, [&](int m, int n, f32x4& a) {
;         uint2 ua = *(const uint2*)(z + (size_t)m * ZS + C_MA + n);
;         uint2 ub = *(const uint2*)(z + (size_t)m * ZS + C_MB + n);
;         a[0] *= sigmoidf(bflo(ua.x)) * inv_sigmoidf(bflo(ub.x));
;         a[1] *= sigmoidf(bfhi(ua.x)) * inv_sigmoidf(bfhi(ub.x));
;         a[2] *= sigmoidf(bflo(ua.y)) * inv_sigmoidf(bflo(ub.y));
;         a[3] *= sigmoidf(bfhi(ua.y)) * inv_sigmoidf(bfhi(ub.y));
;       });
	v_mov_b64_e32 v[2:3], v[200:201]
	global_load_dwordx2 v[200:201], v[246:247], off offset:2048
	v_mov_b32_e32 v135, v1
	v_mov_b32_e32 v172, v196
	s_movk_i32 s1, 0x3c0
	s_movk_i32 s96, 0x1518
	s_nop 0
	v_lshlrev_b32_e32 v130, 16, v4
	v_and_b32_e32 v4, 0xffff0000, v4
	s_nop 0
	v_lshlrev_b32_e32 v131, 16, v2
	v_and_b32_e32 v2, 0xffff0000, v2
	v_mul_f32_e32 v2, 0xbfb8aa3b, v2
	v_exp_f32_e32 v133, v2
	v_lshlrev_b32_e32 v2, 16, v5
	v_mul_f32_e32 v4, 0xbfb8aa3b, v4
	v_mul_f32_e32 v2, 0xbfb8aa3b, v2
	v_exp_f32_e32 v4, v4
	v_exp_f32_e32 v2, v2
	v_and_b32_e32 v5, 0xffff0000, v5
	v_mul_f32_e32 v130, 0xbfb8aa3b, v130
	v_mul_f32_e32 v5, 0xbfb8aa3b, v5
	v_exp_f32_e32 v130, v130
	v_exp_f32_e32 v5, v5
	v_mul_f32_e32 v131, 0xbfb8aa3b, v131
	v_add_f32_e32 v4, 1.0, v4
	v_add_f32_e32 v2, 1.0, v2
	v_exp_f32_e32 v132, v131
	v_rcp_f32_e32 v131, v4
	v_rcp_f32_e32 v4, v2
	v_lshlrev_b32_e32 v2, 16, v3
	v_and_b32_e32 v3, 0xffff0000, v3
	v_mul_f32_e32 v2, 0xbfb8aa3b, v2
	v_mul_f32_e32 v3, 0xbfb8aa3b, v3
	v_add_f32_e32 v130, 1.0, v130
	v_exp_f32_e32 v2, v2
	v_add_f32_e32 v5, 1.0, v5
	v_exp_f32_e32 v3, v3
	v_rcp_f32_e32 v130, v130
	v_rcp_f32_e32 v5, v5
	v_pk_add_f32 v[132:133], v[132:133], 1.0 op_sel_hi:[1,0]
	v_pk_add_f32 v[2:3], v[2:3], 1.0 op_sel_hi:[1,0]
	v_pk_mul_f32 v[130:131], v[130:131], v[132:133]
	v_pk_mul_f32 v[2:3], v[4:5], v[2:3]
	v_lshl_add_u64 v[132:133], v[140:141], 0, v[134:135]
	v_pk_mul_f32 v[4:5], v[160:161], v[2:3]
	v_pk_mul_f32 v[2:3], v[158:159], v[130:131]
	v_lshl_add_u64 v[130:131], v[138:139], 0, v[134:135]
	s_waitcnt vmcnt(23)
	v_mov_b64_e32 v[130:131], v[202:203]
	global_load_dwordx2 v[202:203], v[246:247], off offset:32
	s_nop 0
	s_waitcnt vmcnt(23)
	v_mov_b64_e32 v[132:133], v[204:205]
	global_load_dwordx2 v[204:205], v[246:247], off offset:2080
	s_nop 0
	v_lshlrev_b32_e32 v143, 16, v130
	v_and_b32_e32 v130, 0xffff0000, v130
	v_mul_f32_e32 v130, 0xbfb8aa3b, v130
	v_exp_f32_e32 v130, v130
	v_mul_f32_e32 v143, 0xbfb8aa3b, v143
	v_exp_f32_e32 v143, v143
	v_add_f32_e32 v130, 1.0, v130
	v_rcp_f32_e32 v145, v130
	s_nop 0
	v_and_b32_e32 v130, 0xffff0000, v132
	v_mul_f32_e32 v130, 0xbfb8aa3b, v130
	v_exp_f32_e32 v147, v130
	v_lshlrev_b32_e32 v130, 16, v131
	v_and_b32_e32 v131, 0xffff0000, v131
	v_mul_f32_e32 v130, 0xbfb8aa3b, v130
	v_mul_f32_e32 v131, 0xbfb8aa3b, v131
	v_exp_f32_e32 v130, v130
	v_exp_f32_e32 v131, v131
	v_add_f32_e32 v143, 1.0, v143
	v_rcp_f32_e32 v144, v143
	v_lshlrev_b32_e32 v143, 16, v132
	v_lshlrev_b32_e32 v132, 16, v133
	v_and_b32_e32 v133, 0xffff0000, v133
	v_mul_f32_e32 v132, 0xbfb8aa3b, v132
	v_mul_f32_e32 v133, 0xbfb8aa3b, v133
	v_add_f32_e32 v130, 1.0, v130
	v_exp_f32_e32 v132, v132
	v_add_f32_e32 v131, 1.0, v131
	v_exp_f32_e32 v133, v133
	v_rcp_f32_e32 v130, v130
	v_rcp_f32_e32 v131, v131
	v_mul_f32_e32 v143, 0xbfb8aa3b, v143
	v_pk_add_f32 v[132:133], v[132:133], 1.0 op_sel_hi:[1,0]
	v_exp_f32_e32 v146, v143
	v_pk_mul_f32 v[130:131], v[130:131], v[132:133]
	v_or_b32_e32 v132, 64, v0
	v_mov_b32_e32 v133, v1
	v_pk_mul_f32 v[8:9], v[8:9], v[130:131]
	v_lshl_add_u64 v[130:131], v[138:139], 0, v[132:133]
	s_waitcnt vmcnt(23)
	v_mov_b64_e32 v[130:131], v[206:207]
	global_load_dwordx2 v[206:207], v[246:247], off offset:64
	v_pk_add_f32 v[146:147], v[146:147], 1.0 op_sel_hi:[1,0]
	s_nop 0
	v_pk_mul_f32 v[144:145], v[144:145], v[146:147]
	s_nop 0
	v_pk_mul_f32 v[6:7], v[6:7], v[144:145]
	v_lshl_add_u64 v[144:145], v[140:141], 0, v[132:133]
	s_waitcnt vmcnt(23)
	v_mov_b64_e32 v[144:145], v[208:209]
	global_load_dwordx2 v[208:209], v[246:247], off offset:2112
	s_nop 0
	v_lshlrev_b32_e32 v143, 16, v130
	v_and_b32_e32 v130, 0xffff0000, v130
	v_mul_f32_e32 v130, 0xbfb8aa3b, v130
	v_exp_f32_e32 v130, v130
	v_mul_f32_e32 v143, 0xbfb8aa3b, v143
	v_exp_f32_e32 v143, v143
	v_add_f32_e32 v130, 1.0, v130
	v_rcp_f32_e32 v147, v130
	s_nop 0
	v_and_b32_e32 v130, 0xffff0000, v144
	v_add_f32_e32 v143, 1.0, v143
	v_mul_f32_e32 v130, 0xbfb8aa3b, v130
	v_rcp_f32_e32 v146, v143
	v_lshlrev_b32_e32 v143, 16, v144
	v_exp_f32_e32 v149, v130
	v_lshlrev_b32_e32 v130, 16, v131
	v_and_b32_e32 v131, 0xffff0000, v131
	v_mul_f32_e32 v143, 0xbfb8aa3b, v143
	v_mul_f32_e32 v130, 0xbfb8aa3b, v130
	v_mul_f32_e32 v131, 0xbfb8aa3b, v131
	v_exp_f32_e32 v148, v143
	v_exp_f32_e32 v130, v130
	v_lshlrev_b32_e32 v143, 16, v145
	v_exp_f32_e32 v131, v131
	v_mul_f32_e32 v143, 0xbfb8aa3b, v143
	v_exp_f32_e32 v144, v143
	v_and_b32_e32 v143, 0xffff0000, v145
	v_mul_f32_e32 v143, 0xbfb8aa3b, v143
	v_add_f32_e32 v130, 1.0, v130
	v_add_f32_e32 v131, 1.0, v131
	v_exp_f32_e32 v145, v143
	v_rcp_f32_e32 v130, v130
	v_rcp_f32_e32 v131, v131
	v_pk_add_f32 v[148:149], v[148:149], 1.0 op_sel_hi:[1,0]
	v_pk_add_f32 v[144:145], v[144:145], 1.0 op_sel_hi:[1,0]
	v_pk_mul_f32 v[146:147], v[146:147], v[148:149]
	v_pk_mul_f32 v[130:131], v[130:131], v[144:145]
	v_pk_mul_f32 v[10:11], v[10:11], v[146:147]
	v_pk_mul_f32 v[12:13], v[12:13], v[130:131]
	v_or_b32_e32 v130, 0x60, v0
	v_mov_b32_e32 v131, v1
	v_lshl_add_u64 v[138:139], v[138:139], 0, v[130:131]
	s_waitcnt vmcnt(23)
	v_mov_b64_e32 v[138:139], v[210:211]
	global_load_dwordx2 v[210:211], v[246:247], off offset:96
	v_lshl_add_u64 v[140:141], v[140:141], 0, v[130:131]
	s_waitcnt vmcnt(23)
; DI float bflo(unsigned u) { return __uint_as_float(u << 16); }
; DI float bfhi(unsigned u) { return __uint_as_float(u & 0xffff0000u); }
; DI float sigmoidf(float x) { return __builtin_amdgcn_rcpf(1.f + __expf(-x)); }
; DI float inv_sigmoidf(float x) { return 1.f + __expf(-x); }
; __global__ void __launch_bounds__(512, 2) mega(Params p) {
;     ...
;       gemm8_epi(acc8, m0, n0, [&](int m, int n, f32x4& a) {
;         uint2 ua = *(const uint2*)(z + (size_t)m * ZS + C_MA + n);
;         uint2 ub = *(const uint2*)(z + (size_t)m * ZS + C_MB + n);
;         a[0] *= sigmoidf(bflo(ua.x)) * inv_sigmoidf(bflo(ub.x));
;         a[1] *= sigmoidf(bfhi(ua.x)) * inv_sigmoidf(bfhi(ub.x));
;         a[2] *= sigmoidf(bflo(ua.y)) * inv_sigmoidf(bflo(ub.y));
;         a[3] *= sigmoidf(bfhi(ua.y)) * inv_sigmoidf(bfhi(ub.y));
;       });
	v_mov_b64_e32 v[140:141], v[212:213]
	global_load_dwordx2 v[212:213], v[246:247], off offset:2144
	s_nop 0
	v_lshlrev_b32_e32 v143, 16, v138
	v_and_b32_e32 v138, 0xffff0000, v138
	v_mul_f32_e32 v138, 0xbfb8aa3b, v138
	v_exp_f32_e32 v138, v138
	v_mul_f32_e32 v143, 0xbfb8aa3b, v143
	v_exp_f32_e32 v143, v143
	v_add_f32_e32 v138, 1.0, v138
	v_rcp_f32_e32 v145, v138
	s_nop 0
	v_and_b32_e32 v138, 0xffff0000, v140
	v_mul_f32_e32 v138, 0xbfb8aa3b, v138
	v_exp_f32_e32 v147, v138
	v_lshlrev_b32_e32 v138, 16, v139
	v_and_b32_e32 v139, 0xffff0000, v139
	v_mul_f32_e32 v138, 0xbfb8aa3b, v138
	v_mul_f32_e32 v139, 0xbfb8aa3b, v139
	v_exp_f32_e32 v138, v138
	v_exp_f32_e32 v139, v139
	v_add_f32_e32 v143, 1.0, v143
	v_rcp_f32_e32 v144, v143
	v_lshlrev_b32_e32 v143, 16, v140
	v_lshlrev_b32_e32 v140, 16, v141
	v_and_b32_e32 v141, 0xffff0000, v141
	v_mul_f32_e32 v140, 0xbfb8aa3b, v140
	v_mul_f32_e32 v141, 0xbfb8aa3b, v141
	v_add_f32_e32 v138, 1.0, v138
	v_exp_f32_e32 v140, v140
	v_add_f32_e32 v139, 1.0, v139
	v_exp_f32_e32 v141, v141
	v_rcp_f32_e32 v138, v138
	v_rcp_f32_e32 v139, v139
	v_mul_f32_e32 v143, 0xbfb8aa3b, v143
	v_exp_f32_e32 v146, v143
	v_pk_add_f32 v[140:141], v[140:141], 1.0 op_sel_hi:[1,0]
	v_pk_add_f32 v[146:147], v[146:147], 1.0 op_sel_hi:[1,0]
	v_pk_mul_f32 v[138:139], v[138:139], v[140:141]
	v_pk_mul_f32 v[144:145], v[144:145], v[146:147]
	v_pk_mul_f32 v[16:17], v[16:17], v[138:139]
	v_or_b32_e32 v138, 16, v142
	v_mad_i64_i32 v[140:141], s[26:27], v138, s35, v[136:137]
	v_lshl_add_u64 v[138:139], v[140:141], 0, s[30:31]
	v_pk_mul_f32 v[14:15], v[14:15], v[144:145]
	v_lshl_add_u64 v[144:145], v[138:139], 0, v[0:1]
	s_waitcnt vmcnt(23)
	v_mov_b64_e32 v[144:145], v[214:215]
	v_lshl_add_u64 v[246:247], v[246:247], 0, s[88:89]
	global_load_dwordx2 v[214:215], v[246:247], off
	v_lshl_add_u64 v[140:141], v[140:141], 0, s[42:43]
	v_lshl_add_u64 v[146:147], v[140:141], 0, v[0:1]
	s_waitcnt vmcnt(23)
	v_mov_b64_e32 v[146:147], v[216:217]
	global_load_dwordx2 v[216:217], v[246:247], off offset:2048
	s_nop 0
	v_lshlrev_b32_e32 v143, 16, v144
	v_mul_f32_e32 v143, 0xbfb8aa3b, v143
	v_exp_f32_e32 v143, v143
	s_nop 0
	v_add_f32_e32 v143, 1.0, v143
	v_rcp_f32_e32 v148, v143
	s_nop 0
	v_lshlrev_b32_e32 v143, 16, v146
	v_mul_f32_e32 v143, 0xbfb8aa3b, v143
	v_exp_f32_e32 v150, v143
	v_and_b32_e32 v143, 0xffff0000, v144
	v_mul_f32_e32 v143, 0xbfb8aa3b, v143
	v_exp_f32_e32 v143, v143
	s_nop 0
	v_add_f32_e32 v143, 1.0, v143
	v_rcp_f32_e32 v149, v143
	v_and_b32_e32 v143, 0xffff0000, v146
	v_mul_f32_e32 v143, 0xbfb8aa3b, v143
	v_exp_f32_e32 v151, v143
	v_lshlrev_b32_e32 v143, 16, v145
	v_mul_f32_e32 v143, 0xbfb8aa3b, v143
	v_exp_f32_e32 v143, v143
	v_pk_add_f32 v[150:151], v[150:151], 1.0 op_sel_hi:[1,0]
	v_add_f32_e32 v143, 1.0, v143
	v_rcp_f32_e32 v144, v143
	v_lshlrev_b32_e32 v143, 16, v147
	v_mul_f32_e32 v143, 0xbfb8aa3b, v143
	v_exp_f32_e32 v146, v143
	v_and_b32_e32 v143, 0xffff0000, v145
	v_mul_f32_e32 v143, 0xbfb8aa3b, v143
	v_exp_f32_e32 v143, v143
	v_pk_mul_f32 v[148:149], v[148:149], v[150:151]
	v_add_f32_e32 v143, 1.0, v143
	v_rcp_f32_e32 v145, v143
	v_and_b32_e32 v143, 0xffff0000, v147
	v_mul_f32_e32 v143, 0xbfb8aa3b, v143
	v_exp_f32_e32 v147, v143
	v_pk_mul_f32 v[22:23], v[22:23], v[148:149]
	v_pk_add_f32 v[146:147], v[146:147], 1.0 op_sel_hi:[1,0]
	s_nop 0
	v_pk_mul_f32 v[144:145], v[144:145], v[146:147]
	v_lshl_add_u64 v[146:147], v[140:141], 0, v[134:135]
	v_pk_mul_f32 v[24:25], v[24:25], v[144:145]
	v_lshl_add_u64 v[144:145], v[138:139], 0, v[134:135]
	s_waitcnt vmcnt(23)
	v_mov_b64_e32 v[144:145], v[218:219]
	global_load_dwordx2 v[218:219], v[246:247], off offset:32
	s_nop 0
	s_waitcnt vmcnt(23)
	v_mov_b64_e32 v[146:147], v[220:221]
	global_load_dwordx2 v[220:221], v[246:247], off offset:2080
	s_nop 0
	v_lshlrev_b32_e32 v143, 16, v144
	v_mul_f32_e32 v143, 0xbfb8aa3b, v143
	v_exp_f32_e32 v143, v143
	s_nop 0
	v_add_f32_e32 v143, 1.0, v143
	v_rcp_f32_e32 v148, v143
	s_nop 0
	v_lshlrev_b32_e32 v143, 16, v146
	v_mul_f32_e32 v143, 0xbfb8aa3b, v143
	v_exp_f32_e32 v150, v143
	v_and_b32_e32 v143, 0xffff0000, v144
	v_mul_f32_e32 v143, 0xbfb8aa3b, v143
	v_exp_f32_e32 v143, v143
	s_nop 0
	v_add_f32_e32 v143, 1.0, v143
	v_rcp_f32_e32 v149, v143
	v_and_b32_e32 v143, 0xffff0000, v146
	v_mul_f32_e32 v143, 0xbfb8aa3b, v143
	v_exp_f32_e32 v151, v143
	v_lshlrev_b32_e32 v143, 16, v145
	v_mul_f32_e32 v143, 0xbfb8aa3b, v143
	v_exp_f32_e32 v143, v143
	v_pk_add_f32 v[150:151], v[150:151], 1.0 op_sel_hi:[1,0]
	v_add_f32_e32 v143, 1.0, v143
	v_rcp_f32_e32 v144, v143
	v_lshlrev_b32_e32 v143, 16, v147
	v_mul_f32_e32 v143, 0xbfb8aa3b, v143
	v_exp_f32_e32 v146, v143
	v_and_b32_e32 v143, 0xffff0000, v145
	v_mul_f32_e32 v143, 0xbfb8aa3b, v143
	v_exp_f32_e32 v143, v143
	v_pk_mul_f32 v[148:149], v[148:149], v[150:151]
	v_add_f32_e32 v143, 1.0, v143
	v_rcp_f32_e32 v145, v143
	v_and_b32_e32 v143, 0xffff0000, v147
	v_mul_f32_e32 v143, 0xbfb8aa3b, v143
	v_exp_f32_e32 v147, v143
	v_pk_mul_f32 v[30:31], v[30:31], v[148:149]
	v_pk_add_f32 v[146:147], v[146:147], 1.0 op_sel_hi:[1,0]
	s_nop 0
	v_pk_mul_f32 v[144:145], v[144:145], v[146:147]
	v_lshl_add_u64 v[146:147], v[140:141], 0, v[132:133]
	v_pk_mul_f32 v[32:33], v[32:33], v[144:145]
	v_lshl_add_u64 v[144:145], v[138:139], 0, v[132:133]
	s_waitcnt vmcnt(23)
	v_mov_b64_e32 v[144:145], v[222:223]
	global_load_dwordx2 v[222:223], v[246:247], off offset:64
	v_lshl_add_u64 v[138:139], v[138:139], 0, v[130:131]
	s_waitcnt vmcnt(23)
	v_mov_b64_e32 v[146:147], v[224:225]
	global_load_dwordx2 v[224:225], v[246:247], off offset:2112
	v_lshl_add_u64 v[140:141], v[140:141], 0, v[130:131]
	s_waitcnt vmcnt(23)
; DI float bflo(unsigned u) { return __uint_as_float(u << 16); }
; DI float bfhi(unsigned u) { return __uint_as_float(u & 0xffff0000u); }
; DI float sigmoidf(float x) { return __builtin_amdgcn_rcpf(1.f + __expf(-x)); }
; DI float inv_sigmoidf(float x) { return 1.f + __expf(-x); }
; __global__ void __launch_bounds__(512, 2) mega(Params p) {
;     ...
;       gemm8_epi(acc8, m0, n0, [&](int m, int n, f32x4& a) {
;         uint2 ua = *(const uint2*)(z + (size_t)m * ZS + C_MA + n);
;         uint2 ub = *(const uint2*)(z + (size_t)m * ZS + C_MB + n);
;         a[0] *= sigmoidf(bflo(ua.x)) * inv_sigmoidf(bflo(ub.x));
;         a[1] *= sigmoidf(bfhi(ua.x)) * inv_sigmoidf(bfhi(ub.x));
;         a[2] *= sigmoidf(bflo(ua.y)) * inv_sigmoidf(bflo(ub.y));
;         a[3] *= sigmoidf(bfhi(ua.y)) * inv_sigmoidf(bfhi(ub.y));
;       });
	v_mov_b64_e32 v[138:139], v[226:227]
	global_load_dwordx2 v[226:227], v[246:247], off offset:96
	s_nop 0
	s_waitcnt vmcnt(23)
	v_mov_b64_e32 v[140:141], v[228:229]
	global_load_dwordx2 v[228:229], v[246:247], off offset:2144
	s_nop 0
	v_lshlrev_b32_e32 v143, 16, v144
	v_mul_f32_e32 v143, 0xbfb8aa3b, v143
	v_exp_f32_e32 v143, v143
	s_nop 0
	v_add_f32_e32 v143, 1.0, v143
	v_rcp_f32_e32 v148, v143
	s_nop 0
	v_lshlrev_b32_e32 v143, 16, v146
	v_mul_f32_e32 v143, 0xbfb8aa3b, v143
	v_exp_f32_e32 v150, v143
	v_and_b32_e32 v143, 0xffff0000, v144
	v_mul_f32_e32 v143, 0xbfb8aa3b, v143
	v_exp_f32_e32 v143, v143
	s_nop 0
	v_add_f32_e32 v143, 1.0, v143
	v_rcp_f32_e32 v149, v143
	v_and_b32_e32 v143, 0xffff0000, v146
	v_mul_f32_e32 v143, 0xbfb8aa3b, v143
	v_exp_f32_e32 v151, v143
	v_lshlrev_b32_e32 v143, 16, v145
	v_mul_f32_e32 v143, 0xbfb8aa3b, v143
	v_exp_f32_e32 v143, v143
	v_pk_add_f32 v[150:151], v[150:151], 1.0 op_sel_hi:[1,0]
	v_add_f32_e32 v143, 1.0, v143
	v_rcp_f32_e32 v144, v143
	v_lshlrev_b32_e32 v143, 16, v147
	v_mul_f32_e32 v143, 0xbfb8aa3b, v143
	v_exp_f32_e32 v146, v143
	v_and_b32_e32 v143, 0xffff0000, v145
	v_mul_f32_e32 v143, 0xbfb8aa3b, v143
	v_exp_f32_e32 v143, v143
	v_pk_mul_f32 v[148:149], v[148:149], v[150:151]
	v_add_f32_e32 v143, 1.0, v143
	v_rcp_f32_e32 v145, v143
	v_and_b32_e32 v143, 0xffff0000, v147
	v_mul_f32_e32 v143, 0xbfb8aa3b, v143
	v_exp_f32_e32 v147, v143
	s_nop 0
	v_lshlrev_b32_e32 v143, 16, v138
	v_and_b32_e32 v138, 0xffff0000, v138
	v_mul_f32_e32 v138, 0xbfb8aa3b, v138
	v_exp_f32_e32 v138, v138
	v_pk_add_f32 v[146:147], v[146:147], 1.0 op_sel_hi:[1,0]
	v_mul_f32_e32 v143, 0xbfb8aa3b, v143
	v_pk_mul_f32 v[144:145], v[144:145], v[146:147]
	v_add_f32_e32 v138, 1.0, v138
	v_pk_mul_f32 v[40:41], v[40:41], v[144:145]
	v_rcp_f32_e32 v145, v138
	s_nop 0
	v_and_b32_e32 v138, 0xffff0000, v140
	v_exp_f32_e32 v143, v143
	v_mul_f32_e32 v138, 0xbfb8aa3b, v138
	v_exp_f32_e32 v147, v138
	v_lshlrev_b32_e32 v138, 16, v139
	v_and_b32_e32 v139, 0xffff0000, v139
	v_mul_f32_e32 v138, 0xbfb8aa3b, v138
	v_mul_f32_e32 v139, 0xbfb8aa3b, v139
	v_exp_f32_e32 v138, v138
	v_exp_f32_e32 v139, v139
	v_add_f32_e32 v143, 1.0, v143
	v_rcp_f32_e32 v144, v143
	v_lshlrev_b32_e32 v143, 16, v140
	v_lshlrev_b32_e32 v140, 16, v141
	v_and_b32_e32 v141, 0xffff0000, v141
	v_mul_f32_e32 v140, 0xbfb8aa3b, v140
	v_mul_f32_e32 v141, 0xbfb8aa3b, v141
	v_add_f32_e32 v138, 1.0, v138
	v_exp_f32_e32 v140, v140
	v_add_f32_e32 v139, 1.0, v139
	v_exp_f32_e32 v141, v141
	v_rcp_f32_e32 v138, v138
	v_rcp_f32_e32 v139, v139
	v_mul_f32_e32 v143, 0xbfb8aa3b, v143
	v_exp_f32_e32 v146, v143
	v_pk_add_f32 v[140:141], v[140:141], 1.0 op_sel_hi:[1,0]
	v_pk_mul_f32 v[38:39], v[38:39], v[148:149]
	v_pk_mul_f32 v[138:139], v[138:139], v[140:141]
	v_pk_add_f32 v[146:147], v[146:147], 1.0 op_sel_hi:[1,0]
	v_pk_mul_f32 v[48:49], v[48:49], v[138:139]
	v_or_b32_e32 v138, 32, v142
	v_mad_i64_i32 v[140:141], s[26:27], v138, s35, v[136:137]
	v_pk_mul_f32 v[144:145], v[144:145], v[146:147]
	v_lshl_add_u64 v[138:139], v[140:141], 0, s[30:31]
	v_pk_mul_f32 v[46:47], v[46:47], v[144:145]
	v_lshl_add_u64 v[144:145], v[138:139], 0, v[0:1]
	s_waitcnt vmcnt(23)
	v_mov_b64_e32 v[144:145], v[230:231]
	v_lshl_add_u64 v[246:247], v[246:247], 0, s[88:89]
	global_load_dwordx2 v[230:231], v[246:247], off
	v_lshl_add_u64 v[140:141], v[140:141], 0, s[42:43]
	v_lshl_add_u64 v[146:147], v[140:141], 0, v[0:1]
	s_waitcnt vmcnt(23)
	v_mov_b64_e32 v[146:147], v[232:233]
	global_load_dwordx2 v[232:233], v[246:247], off offset:2048
	s_nop 0
	v_lshlrev_b32_e32 v143, 16, v144
	v_mul_f32_e32 v143, 0xbfb8aa3b, v143
	v_exp_f32_e32 v143, v143
	s_nop 0
	v_add_f32_e32 v143, 1.0, v143
	v_rcp_f32_e32 v148, v143
	s_nop 0
	v_lshlrev_b32_e32 v143, 16, v146
	v_mul_f32_e32 v143, 0xbfb8aa3b, v143
	v_exp_f32_e32 v150, v143
	v_and_b32_e32 v143, 0xffff0000, v144
	v_mul_f32_e32 v143, 0xbfb8aa3b, v143
	v_exp_f32_e32 v143, v143
	s_nop 0
	v_add_f32_e32 v143, 1.0, v143
	v_rcp_f32_e32 v149, v143
	v_and_b32_e32 v143, 0xffff0000, v146
	v_mul_f32_e32 v143, 0xbfb8aa3b, v143
	v_exp_f32_e32 v151, v143
	v_lshlrev_b32_e32 v143, 16, v145
	v_mul_f32_e32 v143, 0xbfb8aa3b, v143
	v_exp_f32_e32 v143, v143
	v_pk_add_f32 v[150:151], v[150:151], 1.0 op_sel_hi:[1,0]
	v_add_f32_e32 v143, 1.0, v143
	v_rcp_f32_e32 v144, v143
	v_lshlrev_b32_e32 v143, 16, v147
	v_mul_f32_e32 v143, 0xbfb8aa3b, v143
	v_exp_f32_e32 v146, v143
	v_and_b32_e32 v143, 0xffff0000, v145
	v_mul_f32_e32 v143, 0xbfb8aa3b, v143
	v_exp_f32_e32 v143, v143
	v_pk_mul_f32 v[148:149], v[148:149], v[150:151]
	v_add_f32_e32 v143, 1.0, v143
	v_rcp_f32_e32 v145, v143
	v_and_b32_e32 v143, 0xffff0000, v147
	v_mul_f32_e32 v143, 0xbfb8aa3b, v143
	v_exp_f32_e32 v147, v143
	v_pk_mul_f32 v[54:55], v[54:55], v[148:149]
	v_pk_add_f32 v[146:147], v[146:147], 1.0 op_sel_hi:[1,0]
	s_nop 0
	v_pk_mul_f32 v[144:145], v[144:145], v[146:147]
	v_lshl_add_u64 v[146:147], v[140:141], 0, v[134:135]
	v_pk_mul_f32 v[56:57], v[56:57], v[144:145]
	v_lshl_add_u64 v[144:145], v[138:139], 0, v[134:135]
	s_waitcnt vmcnt(23)
	v_mov_b64_e32 v[144:145], v[234:235]
	global_load_dwordx2 v[234:235], v[246:247], off offset:32
	s_nop 0
	s_waitcnt vmcnt(23)
; DI float bflo(unsigned u) { return __uint_as_float(u << 16); }
; DI float bfhi(unsigned u) { return __uint_as_float(u & 0xffff0000u); }
; DI float sigmoidf(float x) { return __builtin_amdgcn_rcpf(1.f + __expf(-x)); }
; DI float inv_sigmoidf(float x) { return 1.f + __expf(-x); }
; DI int TID8() { int t = threadIdx.x; asm volatile("" : "+v"(t)); return t; }
; template <class E>
; DI void gemm8_epi(f32x4 (&acc)[8][4], int m0, int n0, E e) {
;   const int tid = TID8(), lane = tid & 63, w = tid >> 6;
;   const int wm = w >> 2, wn = w & 3;
; #pragma unroll
;   for (int i = 0; i < 8; ++i)
; #pragma unroll
;     for (int j = 0; j < 4; ++j) {
;       const int m = m0 + wm * 128 + i * 16 + (lane & 15);
;       const int n = n0 + wn * 64 + j * 16 + (lane >> 4) * 4;
;       e(m, n, acc[i][j]);
;     }
; }
; __global__ void __launch_bounds__(512, 2) mega(Params p) {
;     ...
;       gemm8_epi(acc8, m0, n0, [&](int m, int n, f32x4& a) {
;         uint2 ua = *(const uint2*)(z + (size_t)m * ZS + C_MA + n);
;         uint2 ub = *(const uint2*)(z + (size_t)m * ZS + C_MB + n);
;         a[0] *= sigmoidf(bflo(ua.x)) * inv_sigmoidf(bflo(ub.x));
;         a[1] *= sigmoidf(bfhi(ua.x)) * inv_sigmoidf(bfhi(ub.x));
;         a[2] *= sigmoidf(bflo(ua.y)) * inv_sigmoidf(bflo(ub.y));
;         a[3] *= sigmoidf(bfhi(ua.y)) * inv_sigmoidf(bfhi(ub.y));
;       });
	v_mov_b64_e32 v[146:147], v[236:237]
	global_load_dwordx2 v[236:237], v[246:247], off offset:2080
	s_nop 0
	v_lshlrev_b32_e32 v143, 16, v144
	v_mul_f32_e32 v143, 0xbfb8aa3b, v143
	v_exp_f32_e32 v143, v143
	s_nop 0
	v_add_f32_e32 v143, 1.0, v143
	v_rcp_f32_e32 v148, v143
	s_nop 0
	v_lshlrev_b32_e32 v143, 16, v146
	v_mul_f32_e32 v143, 0xbfb8aa3b, v143
	v_exp_f32_e32 v150, v143
	v_and_b32_e32 v143, 0xffff0000, v144
	v_mul_f32_e32 v143, 0xbfb8aa3b, v143
	v_exp_f32_e32 v143, v143
	s_nop 0
	v_add_f32_e32 v143, 1.0, v143
	v_rcp_f32_e32 v149, v143
	v_and_b32_e32 v143, 0xffff0000, v146
	v_mul_f32_e32 v143, 0xbfb8aa3b, v143
	v_exp_f32_e32 v151, v143
	v_lshlrev_b32_e32 v143, 16, v145
	v_mul_f32_e32 v143, 0xbfb8aa3b, v143
	v_exp_f32_e32 v143, v143
	v_pk_add_f32 v[150:151], v[150:151], 1.0 op_sel_hi:[1,0]
	v_add_f32_e32 v143, 1.0, v143
	v_rcp_f32_e32 v144, v143
	v_lshlrev_b32_e32 v143, 16, v147
	v_mul_f32_e32 v143, 0xbfb8aa3b, v143
	v_exp_f32_e32 v146, v143
	v_and_b32_e32 v143, 0xffff0000, v145
	v_mul_f32_e32 v143, 0xbfb8aa3b, v143
	v_exp_f32_e32 v143, v143
	v_pk_mul_f32 v[148:149], v[148:149], v[150:151]
	v_add_f32_e32 v143, 1.0, v143
	v_rcp_f32_e32 v145, v143
	v_and_b32_e32 v143, 0xffff0000, v147
	v_mul_f32_e32 v143, 0xbfb8aa3b, v143
	v_exp_f32_e32 v147, v143
	v_pk_mul_f32 v[62:63], v[62:63], v[148:149]
	v_pk_add_f32 v[146:147], v[146:147], 1.0 op_sel_hi:[1,0]
	s_nop 0
	v_pk_mul_f32 v[144:145], v[144:145], v[146:147]
	v_lshl_add_u64 v[146:147], v[140:141], 0, v[132:133]
	v_pk_mul_f32 v[64:65], v[64:65], v[144:145]
	v_lshl_add_u64 v[144:145], v[138:139], 0, v[132:133]
	s_waitcnt vmcnt(23)
	v_mov_b64_e32 v[144:145], v[238:239]
	global_load_dwordx2 v[238:239], v[246:247], off offset:64
	v_lshl_add_u64 v[138:139], v[138:139], 0, v[130:131]
	s_waitcnt vmcnt(23)
	v_mov_b64_e32 v[146:147], v[240:241]
	global_load_dwordx2 v[240:241], v[246:247], off offset:2112
	v_lshl_add_u64 v[140:141], v[140:141], 0, v[130:131]
	s_waitcnt vmcnt(23)
	v_mov_b64_e32 v[138:139], v[242:243]
	global_load_dwordx2 v[242:243], v[246:247], off offset:96
	s_nop 0
	s_waitcnt vmcnt(23)
	v_mov_b64_e32 v[140:141], v[244:245]
	global_load_dwordx2 v[244:245], v[246:247], off offset:2144
	s_nop 0
	v_lshlrev_b32_e32 v143, 16, v144
	v_mul_f32_e32 v143, 0xbfb8aa3b, v143
	v_exp_f32_e32 v143, v143
	s_nop 0
	v_add_f32_e32 v143, 1.0, v143
	v_rcp_f32_e32 v148, v143
	s_nop 0
	v_lshlrev_b32_e32 v143, 16, v146
	v_mul_f32_e32 v143, 0xbfb8aa3b, v143
	v_exp_f32_e32 v150, v143
	v_and_b32_e32 v143, 0xffff0000, v144
	v_mul_f32_e32 v143, 0xbfb8aa3b, v143
	v_exp_f32_e32 v143, v143
	s_nop 0
	v_add_f32_e32 v143, 1.0, v143
	v_rcp_f32_e32 v149, v143
	v_and_b32_e32 v143, 0xffff0000, v146
	v_mul_f32_e32 v143, 0xbfb8aa3b, v143
	v_exp_f32_e32 v151, v143
	v_lshlrev_b32_e32 v143, 16, v145
	v_mul_f32_e32 v143, 0xbfb8aa3b, v143
	v_exp_f32_e32 v143, v143
	v_pk_add_f32 v[150:151], v[150:151], 1.0 op_sel_hi:[1,0]
	v_add_f32_e32 v143, 1.0, v143
	v_rcp_f32_e32 v144, v143
	v_lshlrev_b32_e32 v143, 16, v147
	v_mul_f32_e32 v143, 0xbfb8aa3b, v143
	v_exp_f32_e32 v146, v143
	v_and_b32_e32 v143, 0xffff0000, v145
	v_mul_f32_e32 v143, 0xbfb8aa3b, v143
	v_exp_f32_e32 v143, v143
	v_pk_mul_f32 v[148:149], v[148:149], v[150:151]
	v_add_f32_e32 v143, 1.0, v143
	v_rcp_f32_e32 v145, v143
	v_and_b32_e32 v143, 0xffff0000, v147
	v_mul_f32_e32 v143, 0xbfb8aa3b, v143
	v_exp_f32_e32 v147, v143
	s_nop 0
	v_lshlrev_b32_e32 v143, 16, v138
	v_and_b32_e32 v138, 0xffff0000, v138
	v_mul_f32_e32 v138, 0xbfb8aa3b, v138
	v_exp_f32_e32 v138, v138
	v_pk_add_f32 v[146:147], v[146:147], 1.0 op_sel_hi:[1,0]
	v_mul_f32_e32 v143, 0xbfb8aa3b, v143
	v_pk_mul_f32 v[144:145], v[144:145], v[146:147]
	v_add_f32_e32 v138, 1.0, v138
	v_pk_mul_f32 v[72:73], v[72:73], v[144:145]
	v_rcp_f32_e32 v145, v138
	s_nop 0
	v_and_b32_e32 v138, 0xffff0000, v140
	v_exp_f32_e32 v143, v143
	v_mul_f32_e32 v138, 0xbfb8aa3b, v138
	v_exp_f32_e32 v147, v138
	v_lshlrev_b32_e32 v138, 16, v139
	v_and_b32_e32 v139, 0xffff0000, v139
	v_mul_f32_e32 v138, 0xbfb8aa3b, v138
	v_mul_f32_e32 v139, 0xbfb8aa3b, v139
	v_exp_f32_e32 v138, v138
	v_exp_f32_e32 v139, v139
	v_add_f32_e32 v143, 1.0, v143
	v_rcp_f32_e32 v144, v143
	v_lshlrev_b32_e32 v143, 16, v140
	v_lshlrev_b32_e32 v140, 16, v141
	v_and_b32_e32 v141, 0xffff0000, v141
	v_mul_f32_e32 v140, 0xbfb8aa3b, v140
	v_mul_f32_e32 v141, 0xbfb8aa3b, v141
	v_add_f32_e32 v138, 1.0, v138
	v_exp_f32_e32 v140, v140
	v_add_f32_e32 v139, 1.0, v139
	v_exp_f32_e32 v141, v141
	v_rcp_f32_e32 v138, v138
	v_rcp_f32_e32 v139, v139
	v_mul_f32_e32 v143, 0xbfb8aa3b, v143
	v_exp_f32_e32 v146, v143
	v_pk_add_f32 v[140:141], v[140:141], 1.0 op_sel_hi:[1,0]
	v_pk_mul_f32 v[70:71], v[70:71], v[148:149]
	v_pk_mul_f32 v[138:139], v[138:139], v[140:141]
	v_pk_add_f32 v[146:147], v[146:147], 1.0 op_sel_hi:[1,0]
	v_pk_mul_f32 v[80:81], v[80:81], v[138:139]
	v_or_b32_e32 v138, 48, v142
	v_mad_i64_i32 v[140:141], s[26:27], v138, s35, v[136:137]
	v_pk_mul_f32 v[144:145], v[144:145], v[146:147]
	v_lshl_add_u64 v[138:139], v[140:141], 0, s[30:31]
	v_pk_mul_f32 v[78:79], v[78:79], v[144:145]
	v_lshl_add_u64 v[144:145], v[138:139], 0, v[0:1]
	s_waitcnt vmcnt(23)
	v_mov_b64_e32 v[144:145], v[198:199]
	v_lshl_add_u64 v[246:247], v[246:247], 0, s[88:89]
	global_load_dwordx2 v[198:199], v[246:247], off
	v_lshl_add_u64 v[140:141], v[140:141], 0, s[42:43]
	v_lshl_add_u64 v[146:147], v[140:141], 0, v[0:1]
	s_waitcnt vmcnt(23)
; DI float bflo(unsigned u) { return __uint_as_float(u << 16); }
; DI float bfhi(unsigned u) { return __uint_as_float(u & 0xffff0000u); }
; DI float sigmoidf(float x) { return __builtin_amdgcn_rcpf(1.f + __expf(-x)); }
; DI float inv_sigmoidf(float x) { return 1.f + __expf(-x); }
; DI int TID8() { int t = threadIdx.x; asm volatile("" : "+v"(t)); return t; }
; template <class E>
; DI void gemm8_epi(f32x4 (&acc)[8][4], int m0, int n0, E e) {
;   const int tid = TID8(), lane = tid & 63, w = tid >> 6;
;   const int wm = w >> 2, wn = w & 3;
; #pragma unroll
;   for (int i = 0; i < 8; ++i)
; #pragma unroll
;     for (int j = 0; j < 4; ++j) {
;       const int m = m0 + wm * 128 + i * 16 + (lane & 15);
;       const int n = n0 + wn * 64 + j * 16 + (lane >> 4) * 4;
;       e(m, n, acc[i][j]);
;     }
; }
; __global__ void __launch_bounds__(512, 2) mega(Params p) {
;     ...
;       gemm8_epi(acc8, m0, n0, [&](int m, int n, f32x4& a) {
;         uint2 ua = *(const uint2*)(z + (size_t)m * ZS + C_MA + n);
;         uint2 ub = *(const uint2*)(z + (size_t)m * ZS + C_MB + n);
;         a[0] *= sigmoidf(bflo(ua.x)) * inv_sigmoidf(bflo(ub.x));
;         a[1] *= sigmoidf(bfhi(ua.x)) * inv_sigmoidf(bfhi(ub.x));
;         a[2] *= sigmoidf(bflo(ua.y)) * inv_sigmoidf(bflo(ub.y));
;         a[3] *= sigmoidf(bfhi(ua.y)) * inv_sigmoidf(bfhi(ub.y));
;       });
	v_mov_b64_e32 v[146:147], v[200:201]
	global_load_dwordx2 v[200:201], v[246:247], off offset:2048
	s_nop 0
	v_lshlrev_b32_e32 v143, 16, v144
	v_mul_f32_e32 v143, 0xbfb8aa3b, v143
	v_exp_f32_e32 v143, v143
	s_nop 0
	v_add_f32_e32 v143, 1.0, v143
	v_rcp_f32_e32 v148, v143
	s_nop 0
	v_lshlrev_b32_e32 v143, 16, v146
	v_mul_f32_e32 v143, 0xbfb8aa3b, v143
	v_exp_f32_e32 v150, v143
	v_and_b32_e32 v143, 0xffff0000, v144
	v_mul_f32_e32 v143, 0xbfb8aa3b, v143
	v_exp_f32_e32 v143, v143
	s_nop 0
	v_add_f32_e32 v143, 1.0, v143
	v_rcp_f32_e32 v149, v143
	v_and_b32_e32 v143, 0xffff0000, v146
	v_mul_f32_e32 v143, 0xbfb8aa3b, v143
	v_exp_f32_e32 v151, v143
	v_lshlrev_b32_e32 v143, 16, v145
	v_mul_f32_e32 v143, 0xbfb8aa3b, v143
	v_exp_f32_e32 v143, v143
	v_pk_add_f32 v[150:151], v[150:151], 1.0 op_sel_hi:[1,0]
	v_add_f32_e32 v143, 1.0, v143
	v_rcp_f32_e32 v144, v143
	v_lshlrev_b32_e32 v143, 16, v147
	v_mul_f32_e32 v143, 0xbfb8aa3b, v143
	v_exp_f32_e32 v146, v143
	v_and_b32_e32 v143, 0xffff0000, v145
	v_mul_f32_e32 v143, 0xbfb8aa3b, v143
	v_exp_f32_e32 v143, v143
	v_pk_mul_f32 v[148:149], v[148:149], v[150:151]
	v_add_f32_e32 v143, 1.0, v143
	v_rcp_f32_e32 v145, v143
	v_and_b32_e32 v143, 0xffff0000, v147
	v_mul_f32_e32 v143, 0xbfb8aa3b, v143
	v_exp_f32_e32 v147, v143
	v_pk_mul_f32 v[86:87], v[86:87], v[148:149]
	v_pk_add_f32 v[146:147], v[146:147], 1.0 op_sel_hi:[1,0]
	s_nop 0
	v_pk_mul_f32 v[144:145], v[144:145], v[146:147]
	v_lshl_add_u64 v[146:147], v[140:141], 0, v[134:135]
	v_pk_mul_f32 v[88:89], v[88:89], v[144:145]
	v_lshl_add_u64 v[144:145], v[138:139], 0, v[134:135]
	s_waitcnt vmcnt(23)
	v_mov_b64_e32 v[144:145], v[202:203]
	global_load_dwordx2 v[202:203], v[246:247], off offset:32
	s_nop 0
	s_waitcnt vmcnt(23)
	v_mov_b64_e32 v[146:147], v[204:205]
	global_load_dwordx2 v[204:205], v[246:247], off offset:2080
	s_nop 0
	v_lshlrev_b32_e32 v143, 16, v144
	v_mul_f32_e32 v143, 0xbfb8aa3b, v143
	v_exp_f32_e32 v143, v143
	s_nop 0
	v_add_f32_e32 v143, 1.0, v143
	v_rcp_f32_e32 v148, v143
	s_nop 0
	v_lshlrev_b32_e32 v143, 16, v146
	v_mul_f32_e32 v143, 0xbfb8aa3b, v143
	v_exp_f32_e32 v150, v143
	v_and_b32_e32 v143, 0xffff0000, v144
	v_mul_f32_e32 v143, 0xbfb8aa3b, v143
	v_exp_f32_e32 v143, v143
	s_nop 0
	v_add_f32_e32 v143, 1.0, v143
	v_rcp_f32_e32 v149, v143
	v_and_b32_e32 v143, 0xffff0000, v146
	v_mul_f32_e32 v143, 0xbfb8aa3b, v143
	v_exp_f32_e32 v151, v143
	v_lshlrev_b32_e32 v143, 16, v145
	v_mul_f32_e32 v143, 0xbfb8aa3b, v143
	v_exp_f32_e32 v143, v143
	v_pk_add_f32 v[150:151], v[150:151], 1.0 op_sel_hi:[1,0]
	v_add_f32_e32 v143, 1.0, v143
	v_rcp_f32_e32 v144, v143
	v_lshlrev_b32_e32 v143, 16, v147
	v_mul_f32_e32 v143, 0xbfb8aa3b, v143
	v_exp_f32_e32 v146, v143
	v_and_b32_e32 v143, 0xffff0000, v145
	v_mul_f32_e32 v143, 0xbfb8aa3b, v143
	v_exp_f32_e32 v143, v143
	v_pk_mul_f32 v[148:149], v[148:149], v[150:151]
	v_add_f32_e32 v143, 1.0, v143
	v_rcp_f32_e32 v145, v143
	v_and_b32_e32 v143, 0xffff0000, v147
	v_mul_f32_e32 v143, 0xbfb8aa3b, v143
	v_exp_f32_e32 v147, v143
	v_pk_mul_f32 v[94:95], v[94:95], v[148:149]
	v_pk_add_f32 v[146:147], v[146:147], 1.0 op_sel_hi:[1,0]
	s_nop 0
	v_pk_mul_f32 v[144:145], v[144:145], v[146:147]
	v_lshl_add_u64 v[146:147], v[140:141], 0, v[132:133]
	v_pk_mul_f32 v[96:97], v[96:97], v[144:145]
	v_lshl_add_u64 v[144:145], v[138:139], 0, v[132:133]
	s_waitcnt vmcnt(23)
	v_mov_b64_e32 v[144:145], v[206:207]
	global_load_dwordx2 v[206:207], v[246:247], off offset:64
	v_lshl_add_u64 v[138:139], v[138:139], 0, v[130:131]
	s_waitcnt vmcnt(23)
	v_mov_b64_e32 v[146:147], v[208:209]
	global_load_dwordx2 v[208:209], v[246:247], off offset:2112
	v_lshl_add_u64 v[140:141], v[140:141], 0, v[130:131]
	s_waitcnt vmcnt(23)
	v_mov_b64_e32 v[138:139], v[210:211]
	global_load_dwordx2 v[210:211], v[246:247], off offset:96
	s_nop 0
	s_waitcnt vmcnt(23)
	v_mov_b64_e32 v[140:141], v[212:213]
	global_load_dwordx2 v[212:213], v[246:247], off offset:2144
	s_nop 0
	v_lshlrev_b32_e32 v143, 16, v144
	v_mul_f32_e32 v143, 0xbfb8aa3b, v143
	v_exp_f32_e32 v143, v143
	s_nop 0
	v_add_f32_e32 v143, 1.0, v143
	v_rcp_f32_e32 v148, v143
	s_nop 0
	v_lshlrev_b32_e32 v143, 16, v146
	v_mul_f32_e32 v143, 0xbfb8aa3b, v143
	v_exp_f32_e32 v150, v143
	v_and_b32_e32 v143, 0xffff0000, v144
	v_mul_f32_e32 v143, 0xbfb8aa3b, v143
	v_exp_f32_e32 v143, v143
	s_nop 0
	v_add_f32_e32 v143, 1.0, v143
	v_rcp_f32_e32 v149, v143
	v_and_b32_e32 v143, 0xffff0000, v146
	v_mul_f32_e32 v143, 0xbfb8aa3b, v143
	v_exp_f32_e32 v151, v143
	v_lshlrev_b32_e32 v143, 16, v145
	v_mul_f32_e32 v143, 0xbfb8aa3b, v143
	v_exp_f32_e32 v143, v143
	v_pk_add_f32 v[150:151], v[150:151], 1.0 op_sel_hi:[1,0]
	v_add_f32_e32 v143, 1.0, v143
	v_rcp_f32_e32 v144, v143
	v_lshlrev_b32_e32 v143, 16, v147
	v_mul_f32_e32 v143, 0xbfb8aa3b, v143
	v_exp_f32_e32 v146, v143
	v_and_b32_e32 v143, 0xffff0000, v145
	v_mul_f32_e32 v143, 0xbfb8aa3b, v143
	v_exp_f32_e32 v143, v143
	v_pk_mul_f32 v[148:149], v[148:149], v[150:151]
	v_add_f32_e32 v143, 1.0, v143
	v_rcp_f32_e32 v145, v143
	v_and_b32_e32 v143, 0xffff0000, v147
	v_mul_f32_e32 v143, 0xbfb8aa3b, v143
	v_exp_f32_e32 v147, v143
	s_nop 0
	v_lshlrev_b32_e32 v143, 16, v138
	v_and_b32_e32 v138, 0xffff0000, v138
	v_mul_f32_e32 v138, 0xbfb8aa3b, v138
	v_exp_f32_e32 v138, v138
	v_pk_add_f32 v[146:147], v[146:147], 1.0 op_sel_hi:[1,0]
	v_mul_f32_e32 v143, 0xbfb8aa3b, v143
	v_pk_mul_f32 v[144:145], v[144:145], v[146:147]
	v_add_f32_e32 v138, 1.0, v138
	v_pk_mul_f32 v[104:105], v[104:105], v[144:145]
	v_rcp_f32_e32 v145, v138
	s_nop 0
	v_and_b32_e32 v138, 0xffff0000, v140
	v_exp_f32_e32 v143, v143
	v_mul_f32_e32 v138, 0xbfb8aa3b, v138
	v_exp_f32_e32 v147, v138
	v_lshlrev_b32_e32 v138, 16, v139
	v_and_b32_e32 v139, 0xffff0000, v139
	v_mul_f32_e32 v138, 0xbfb8aa3b, v138
	v_mul_f32_e32 v139, 0xbfb8aa3b, v139
	v_exp_f32_e32 v138, v138
	v_exp_f32_e32 v139, v139
	v_add_f32_e32 v143, 1.0, v143
	v_rcp_f32_e32 v144, v143
	v_lshlrev_b32_e32 v143, 16, v140
	v_lshlrev_b32_e32 v140, 16, v141
	v_and_b32_e32 v141, 0xffff0000, v141
	v_mul_f32_e32 v140, 0xbfb8aa3b, v140
	v_mul_f32_e32 v141, 0xbfb8aa3b, v141
	v_add_f32_e32 v138, 1.0, v138
	v_exp_f32_e32 v140, v140
	v_add_f32_e32 v139, 1.0, v139
	v_exp_f32_e32 v141, v141
	v_rcp_f32_e32 v138, v138
	v_rcp_f32_e32 v139, v139
	v_mul_f32_e32 v143, 0xbfb8aa3b, v143
	v_exp_f32_e32 v146, v143
	v_pk_add_f32 v[140:141], v[140:141], 1.0 op_sel_hi:[1,0]
	v_pk_mul_f32 v[102:103], v[102:103], v[148:149]
	v_pk_mul_f32 v[138:139], v[138:139], v[140:141]
	v_pk_add_f32 v[146:147], v[146:147], 1.0 op_sel_hi:[1,0]
	v_pk_mul_f32 v[112:113], v[112:113], v[138:139]
	v_or_b32_e32 v138, 64, v142
	v_mad_i64_i32 v[140:141], s[26:27], v138, s35, v[136:137]
	v_pk_mul_f32 v[144:145], v[144:145], v[146:147]
	v_lshl_add_u64 v[138:139], v[140:141], 0, s[30:31]
	v_pk_mul_f32 v[110:111], v[110:111], v[144:145]
	v_lshl_add_u64 v[144:145], v[138:139], 0, v[0:1]
	s_waitcnt vmcnt(23)
; DI float bflo(unsigned u) { return __uint_as_float(u << 16); }
; DI float bfhi(unsigned u) { return __uint_as_float(u & 0xffff0000u); }
; DI float sigmoidf(float x) { return __builtin_amdgcn_rcpf(1.f + __expf(-x)); }
; DI float inv_sigmoidf(float x) { return 1.f + __expf(-x); }
; DI int TID8() { int t = threadIdx.x; asm volatile("" : "+v"(t)); return t; }
; template <class E>
; DI void gemm8_epi(f32x4 (&acc)[8][4], int m0, int n0, E e) {
;   const int tid = TID8(), lane = tid & 63, w = tid >> 6;
;   const int wm = w >> 2, wn = w & 3;
; #pragma unroll
;   for (int i = 0; i < 8; ++i)
; #pragma unroll
;     for (int j = 0; j < 4; ++j) {
;       const int m = m0 + wm * 128 + i * 16 + (lane & 15);
;       const int n = n0 + wn * 64 + j * 16 + (lane >> 4) * 4;
;       e(m, n, acc[i][j]);
;     }
; }
; __global__ void __launch_bounds__(512, 2) mega(Params p) {
;     ...
;       gemm8_epi(acc8, m0, n0, [&](int m, int n, f32x4& a) {
;         uint2 ua = *(const uint2*)(z + (size_t)m * ZS + C_MA + n);
;         uint2 ub = *(const uint2*)(z + (size_t)m * ZS + C_MB + n);
;         a[0] *= sigmoidf(bflo(ua.x)) * inv_sigmoidf(bflo(ub.x));
;         a[1] *= sigmoidf(bfhi(ua.x)) * inv_sigmoidf(bfhi(ub.x));
;         a[2] *= sigmoidf(bflo(ua.y)) * inv_sigmoidf(bflo(ub.y));
;         a[3] *= sigmoidf(bfhi(ua.y)) * inv_sigmoidf(bfhi(ub.y));
;       });
	v_mov_b64_e32 v[144:145], v[214:215]
	v_lshl_add_u64 v[246:247], v[246:247], 0, s[88:89]
	global_load_dwordx2 v[214:215], v[246:247], off
	v_lshl_add_u64 v[140:141], v[140:141], 0, s[42:43]
	v_lshl_add_u64 v[146:147], v[140:141], 0, v[0:1]
	s_waitcnt vmcnt(23)
	v_mov_b64_e32 v[146:147], v[216:217]
	global_load_dwordx2 v[216:217], v[246:247], off offset:2048
	s_nop 0
	v_lshlrev_b32_e32 v143, 16, v144
	v_mul_f32_e32 v143, 0xbfb8aa3b, v143
	v_exp_f32_e32 v143, v143
	s_nop 0
	v_add_f32_e32 v143, 1.0, v143
	v_rcp_f32_e32 v148, v143
	s_nop 0
	v_lshlrev_b32_e32 v143, 16, v146
	v_mul_f32_e32 v143, 0xbfb8aa3b, v143
	v_exp_f32_e32 v150, v143
	v_and_b32_e32 v143, 0xffff0000, v144
	v_mul_f32_e32 v143, 0xbfb8aa3b, v143
	v_exp_f32_e32 v143, v143
	s_nop 0
	v_add_f32_e32 v143, 1.0, v143
	v_rcp_f32_e32 v149, v143
	v_and_b32_e32 v143, 0xffff0000, v146
	v_mul_f32_e32 v143, 0xbfb8aa3b, v143
	v_exp_f32_e32 v151, v143
	v_lshlrev_b32_e32 v143, 16, v145
	v_mul_f32_e32 v143, 0xbfb8aa3b, v143
	v_exp_f32_e32 v143, v143
	v_pk_add_f32 v[150:151], v[150:151], 1.0 op_sel_hi:[1,0]
	v_add_f32_e32 v143, 1.0, v143
	v_rcp_f32_e32 v144, v143
	v_lshlrev_b32_e32 v143, 16, v147
	v_mul_f32_e32 v143, 0xbfb8aa3b, v143
	v_exp_f32_e32 v146, v143
	v_and_b32_e32 v143, 0xffff0000, v145
	v_mul_f32_e32 v143, 0xbfb8aa3b, v143
	v_exp_f32_e32 v143, v143
	v_pk_mul_f32 v[148:149], v[148:149], v[150:151]
	v_add_f32_e32 v143, 1.0, v143
	v_rcp_f32_e32 v145, v143
	v_and_b32_e32 v143, 0xffff0000, v147
	v_mul_f32_e32 v143, 0xbfb8aa3b, v143
	v_exp_f32_e32 v147, v143
	v_pk_mul_f32 v[118:119], v[118:119], v[148:149]
	v_pk_add_f32 v[146:147], v[146:147], 1.0 op_sel_hi:[1,0]
	s_nop 0
	v_pk_mul_f32 v[144:145], v[144:145], v[146:147]
	v_lshl_add_u64 v[146:147], v[140:141], 0, v[134:135]
	v_pk_mul_f32 v[120:121], v[120:121], v[144:145]
	v_lshl_add_u64 v[144:145], v[138:139], 0, v[134:135]
	s_waitcnt vmcnt(23)
	v_mov_b64_e32 v[144:145], v[218:219]
	global_load_dwordx2 v[218:219], v[246:247], off offset:32
	s_nop 0
	s_waitcnt vmcnt(23)
	v_mov_b64_e32 v[146:147], v[220:221]
	global_load_dwordx2 v[220:221], v[246:247], off offset:2080
	s_nop 0
	v_lshlrev_b32_e32 v143, 16, v144
	v_mul_f32_e32 v143, 0xbfb8aa3b, v143
	v_exp_f32_e32 v143, v143
	s_nop 0
	v_add_f32_e32 v143, 1.0, v143
	v_rcp_f32_e32 v148, v143
	s_nop 0
	v_lshlrev_b32_e32 v143, 16, v146
	v_mul_f32_e32 v143, 0xbfb8aa3b, v143
	v_exp_f32_e32 v150, v143
	v_and_b32_e32 v143, 0xffff0000, v144
	v_mul_f32_e32 v143, 0xbfb8aa3b, v143
	v_exp_f32_e32 v143, v143
	s_nop 0
	v_add_f32_e32 v143, 1.0, v143
	v_rcp_f32_e32 v149, v143
	v_and_b32_e32 v143, 0xffff0000, v146
	v_mul_f32_e32 v143, 0xbfb8aa3b, v143
	v_exp_f32_e32 v151, v143
	v_lshlrev_b32_e32 v143, 16, v145
	v_mul_f32_e32 v143, 0xbfb8aa3b, v143
	v_exp_f32_e32 v143, v143
	v_pk_add_f32 v[150:151], v[150:151], 1.0 op_sel_hi:[1,0]
	v_add_f32_e32 v143, 1.0, v143
	v_rcp_f32_e32 v144, v143
	v_lshlrev_b32_e32 v143, 16, v147
	v_mul_f32_e32 v143, 0xbfb8aa3b, v143
	v_exp_f32_e32 v146, v143
	v_and_b32_e32 v143, 0xffff0000, v145
	v_mul_f32_e32 v143, 0xbfb8aa3b, v143
	v_exp_f32_e32 v143, v143
	v_pk_mul_f32 v[148:149], v[148:149], v[150:151]
	v_add_f32_e32 v143, 1.0, v143
	v_rcp_f32_e32 v145, v143
	v_and_b32_e32 v143, 0xffff0000, v147
	v_mul_f32_e32 v143, 0xbfb8aa3b, v143
	v_exp_f32_e32 v147, v143
	v_pk_mul_f32 v[126:127], v[126:127], v[148:149]
	v_pk_add_f32 v[146:147], v[146:147], 1.0 op_sel_hi:[1,0]
	s_nop 0
	v_pk_mul_f32 v[144:145], v[144:145], v[146:147]
	v_lshl_add_u64 v[146:147], v[140:141], 0, v[132:133]
	v_pk_mul_f32 v[128:129], v[128:129], v[144:145]
	v_lshl_add_u64 v[144:145], v[138:139], 0, v[132:133]
	s_waitcnt vmcnt(23)
	v_mov_b64_e32 v[144:145], v[222:223]
	global_load_dwordx2 v[222:223], v[246:247], off offset:64
	v_lshl_add_u64 v[138:139], v[138:139], 0, v[130:131]
	s_waitcnt vmcnt(23)
	v_mov_b64_e32 v[146:147], v[224:225]
	global_load_dwordx2 v[224:225], v[246:247], off offset:2112
	v_lshl_add_u64 v[140:141], v[140:141], 0, v[130:131]
	s_waitcnt vmcnt(23)
	v_mov_b64_e32 v[138:139], v[226:227]
	global_load_dwordx2 v[226:227], v[246:247], off offset:96
	s_nop 0
	s_waitcnt vmcnt(23)
	v_mov_b64_e32 v[140:141], v[228:229]
	global_load_dwordx2 v[228:229], v[246:247], off offset:2144
	s_nop 0
	v_lshlrev_b32_e32 v143, 16, v144
	v_mul_f32_e32 v143, 0xbfb8aa3b, v143
	v_exp_f32_e32 v143, v143
	s_nop 0
	v_add_f32_e32 v143, 1.0, v143
	v_rcp_f32_e32 v148, v143
	s_nop 0
	v_lshlrev_b32_e32 v143, 16, v146
	v_mul_f32_e32 v143, 0xbfb8aa3b, v143
	v_exp_f32_e32 v150, v143
	v_and_b32_e32 v143, 0xffff0000, v144
	v_mul_f32_e32 v143, 0xbfb8aa3b, v143
	v_exp_f32_e32 v143, v143
	s_nop 0
	v_add_f32_e32 v143, 1.0, v143
	v_rcp_f32_e32 v149, v143
	v_and_b32_e32 v143, 0xffff0000, v146
	v_mul_f32_e32 v143, 0xbfb8aa3b, v143
	v_exp_f32_e32 v151, v143
	v_lshlrev_b32_e32 v143, 16, v145
	v_mul_f32_e32 v143, 0xbfb8aa3b, v143
	v_exp_f32_e32 v143, v143
	v_pk_add_f32 v[150:151], v[150:151], 1.0 op_sel_hi:[1,0]
	v_add_f32_e32 v143, 1.0, v143
	v_rcp_f32_e32 v144, v143
	v_lshlrev_b32_e32 v143, 16, v147
	v_mul_f32_e32 v143, 0xbfb8aa3b, v143
	v_exp_f32_e32 v146, v143
	v_and_b32_e32 v143, 0xffff0000, v145
	v_mul_f32_e32 v143, 0xbfb8aa3b, v143
	v_exp_f32_e32 v143, v143
	v_pk_mul_f32 v[148:149], v[148:149], v[150:151]
	v_add_f32_e32 v143, 1.0, v143
	v_rcp_f32_e32 v145, v143
	v_and_b32_e32 v143, 0xffff0000, v147
	v_mul_f32_e32 v143, 0xbfb8aa3b, v143
	v_exp_f32_e32 v147, v143
	s_nop 0
	v_lshlrev_b32_e32 v143, 16, v138
	v_and_b32_e32 v138, 0xffff0000, v138
	v_mul_f32_e32 v138, 0xbfb8aa3b, v138
	v_exp_f32_e32 v138, v138
	v_pk_add_f32 v[146:147], v[146:147], 1.0 op_sel_hi:[1,0]
	v_mul_f32_e32 v143, 0xbfb8aa3b, v143
	v_pk_mul_f32 v[144:145], v[144:145], v[146:147]
; DI float bflo(unsigned u) { return __uint_as_float(u << 16); }
; DI float bfhi(unsigned u) { return __uint_as_float(u & 0xffff0000u); }
; DI float sigmoidf(float x) { return __builtin_amdgcn_rcpf(1.f + __expf(-x)); }
; DI float inv_sigmoidf(float x) { return 1.f + __expf(-x); }
; DI int TID8() { int t = threadIdx.x; asm volatile("" : "+v"(t)); return t; }
; template <class E>
; DI void gemm8_epi(f32x4 (&acc)[8][4], int m0, int n0, E e) {
;   const int tid = TID8(), lane = tid & 63, w = tid >> 6;
;   const int wm = w >> 2, wn = w & 3;
; #pragma unroll
;   for (int i = 0; i < 8; ++i)
; #pragma unroll
;     for (int j = 0; j < 4; ++j) {
;       const int m = m0 + wm * 128 + i * 16 + (lane & 15);
;       const int n = n0 + wn * 64 + j * 16 + (lane >> 4) * 4;
;       e(m, n, acc[i][j]);
;     }
; }
; __global__ void __launch_bounds__(512, 2) mega(Params p) {
;     ...
;       gemm8_epi(acc8, m0, n0, [&](int m, int n, f32x4& a) {
;         uint2 ua = *(const uint2*)(z + (size_t)m * ZS + C_MA + n);
;         uint2 ub = *(const uint2*)(z + (size_t)m * ZS + C_MB + n);
;         a[0] *= sigmoidf(bflo(ua.x)) * inv_sigmoidf(bflo(ub.x));
;         a[1] *= sigmoidf(bfhi(ua.x)) * inv_sigmoidf(bfhi(ub.x));
;         a[2] *= sigmoidf(bflo(ua.y)) * inv_sigmoidf(bflo(ub.y));
;         a[3] *= sigmoidf(bfhi(ua.y)) * inv_sigmoidf(bfhi(ub.y));
;       });
	v_add_f32_e32 v138, 1.0, v138
	v_pk_mul_f32 v[124:125], v[124:125], v[144:145]
	v_rcp_f32_e32 v145, v138
	s_nop 0
	v_and_b32_e32 v138, 0xffff0000, v140
	v_exp_f32_e32 v143, v143
	v_mul_f32_e32 v138, 0xbfb8aa3b, v138
	v_exp_f32_e32 v147, v138
	v_lshlrev_b32_e32 v138, 16, v139
	v_and_b32_e32 v139, 0xffff0000, v139
	v_mul_f32_e32 v138, 0xbfb8aa3b, v138
	v_mul_f32_e32 v139, 0xbfb8aa3b, v139
	v_exp_f32_e32 v138, v138
	v_exp_f32_e32 v139, v139
	v_add_f32_e32 v143, 1.0, v143
	v_rcp_f32_e32 v144, v143
	v_lshlrev_b32_e32 v143, 16, v140
	v_lshlrev_b32_e32 v140, 16, v141
	v_and_b32_e32 v141, 0xffff0000, v141
	v_mul_f32_e32 v140, 0xbfb8aa3b, v140
	v_mul_f32_e32 v141, 0xbfb8aa3b, v141
	v_add_f32_e32 v138, 1.0, v138
	v_exp_f32_e32 v140, v140
	v_add_f32_e32 v139, 1.0, v139
	v_exp_f32_e32 v141, v141
	v_rcp_f32_e32 v138, v138
	v_rcp_f32_e32 v139, v139
	v_mul_f32_e32 v143, 0xbfb8aa3b, v143
	v_exp_f32_e32 v146, v143
	v_pk_add_f32 v[140:141], v[140:141], 1.0 op_sel_hi:[1,0]
	v_pk_mul_f32 v[122:123], v[122:123], v[148:149]
	v_pk_mul_f32 v[138:139], v[138:139], v[140:141]
	v_pk_add_f32 v[146:147], v[146:147], 1.0 op_sel_hi:[1,0]
	v_pk_mul_f32 v[116:117], v[116:117], v[138:139]
	v_or_b32_e32 v138, 0x50, v142
	v_mad_i64_i32 v[140:141], s[26:27], v138, s35, v[136:137]
	v_pk_mul_f32 v[144:145], v[144:145], v[146:147]
	v_lshl_add_u64 v[138:139], v[140:141], 0, s[30:31]
	v_pk_mul_f32 v[114:115], v[114:115], v[144:145]
	v_lshl_add_u64 v[144:145], v[138:139], 0, v[0:1]
	s_waitcnt vmcnt(23)
	v_mov_b64_e32 v[144:145], v[230:231]
	v_lshl_add_u64 v[140:141], v[140:141], 0, s[42:43]
	v_lshl_add_u64 v[146:147], v[140:141], 0, v[0:1]
	s_waitcnt vmcnt(22)
	v_mov_b64_e32 v[146:147], v[232:233]
	s_nop 0
	v_lshlrev_b32_e32 v143, 16, v144
	v_mul_f32_e32 v143, 0xbfb8aa3b, v143
	v_exp_f32_e32 v143, v143
	s_nop 0
	v_add_f32_e32 v143, 1.0, v143
	v_rcp_f32_e32 v148, v143
	s_nop 0
	v_lshlrev_b32_e32 v143, 16, v146
	v_mul_f32_e32 v143, 0xbfb8aa3b, v143
	v_exp_f32_e32 v150, v143
	v_and_b32_e32 v143, 0xffff0000, v144
	v_mul_f32_e32 v143, 0xbfb8aa3b, v143
	v_exp_f32_e32 v143, v143
	s_nop 0
	v_add_f32_e32 v143, 1.0, v143
	v_rcp_f32_e32 v149, v143
	v_and_b32_e32 v143, 0xffff0000, v146
	v_mul_f32_e32 v143, 0xbfb8aa3b, v143
	v_exp_f32_e32 v151, v143
	v_lshlrev_b32_e32 v143, 16, v145
	v_mul_f32_e32 v143, 0xbfb8aa3b, v143
	v_exp_f32_e32 v143, v143
	v_pk_add_f32 v[150:151], v[150:151], 1.0 op_sel_hi:[1,0]
	v_add_f32_e32 v143, 1.0, v143
	v_rcp_f32_e32 v144, v143
	v_lshlrev_b32_e32 v143, 16, v147
	v_mul_f32_e32 v143, 0xbfb8aa3b, v143
	v_exp_f32_e32 v146, v143
	v_and_b32_e32 v143, 0xffff0000, v145
	v_mul_f32_e32 v143, 0xbfb8aa3b, v143
	v_exp_f32_e32 v143, v143
	v_pk_mul_f32 v[148:149], v[148:149], v[150:151]
	v_add_f32_e32 v143, 1.0, v143
	v_rcp_f32_e32 v145, v143
	v_and_b32_e32 v143, 0xffff0000, v147
	v_mul_f32_e32 v143, 0xbfb8aa3b, v143
	v_exp_f32_e32 v147, v143
	v_pk_mul_f32 v[106:107], v[106:107], v[148:149]
	v_pk_add_f32 v[146:147], v[146:147], 1.0 op_sel_hi:[1,0]
	s_nop 0
	v_pk_mul_f32 v[144:145], v[144:145], v[146:147]
	v_lshl_add_u64 v[146:147], v[140:141], 0, v[134:135]
	v_pk_mul_f32 v[108:109], v[108:109], v[144:145]
	v_lshl_add_u64 v[144:145], v[138:139], 0, v[134:135]
	s_waitcnt vmcnt(21)
	v_mov_b64_e32 v[144:145], v[234:235]
	s_nop 0
	s_waitcnt vmcnt(20)
	v_mov_b64_e32 v[146:147], v[236:237]
	s_nop 0
	v_lshlrev_b32_e32 v143, 16, v144
	v_mul_f32_e32 v143, 0xbfb8aa3b, v143
	v_exp_f32_e32 v143, v143
	s_nop 0
	v_add_f32_e32 v143, 1.0, v143
	v_rcp_f32_e32 v148, v143
	s_nop 0
	v_lshlrev_b32_e32 v143, 16, v146
	v_mul_f32_e32 v143, 0xbfb8aa3b, v143
	v_exp_f32_e32 v150, v143
	v_and_b32_e32 v143, 0xffff0000, v144
	v_mul_f32_e32 v143, 0xbfb8aa3b, v143
	v_exp_f32_e32 v143, v143
	s_nop 0
	v_add_f32_e32 v143, 1.0, v143
	v_rcp_f32_e32 v149, v143
	v_and_b32_e32 v143, 0xffff0000, v146
	v_mul_f32_e32 v143, 0xbfb8aa3b, v143
	v_exp_f32_e32 v151, v143
	v_lshlrev_b32_e32 v143, 16, v145
	v_mul_f32_e32 v143, 0xbfb8aa3b, v143
	v_exp_f32_e32 v143, v143
	v_pk_add_f32 v[150:151], v[150:151], 1.0 op_sel_hi:[1,0]
	v_add_f32_e32 v143, 1.0, v143
	v_rcp_f32_e32 v144, v143
	v_lshlrev_b32_e32 v143, 16, v147
	v_mul_f32_e32 v143, 0xbfb8aa3b, v143
	v_exp_f32_e32 v146, v143
	v_and_b32_e32 v143, 0xffff0000, v145
	v_mul_f32_e32 v143, 0xbfb8aa3b, v143
	v_exp_f32_e32 v143, v143
	v_pk_mul_f32 v[148:149], v[148:149], v[150:151]
	v_add_f32_e32 v143, 1.0, v143
	v_rcp_f32_e32 v145, v143
	v_and_b32_e32 v143, 0xffff0000, v147
	v_mul_f32_e32 v143, 0xbfb8aa3b, v143
	v_exp_f32_e32 v147, v143
	v_pk_mul_f32 v[98:99], v[98:99], v[148:149]
	v_pk_add_f32 v[146:147], v[146:147], 1.0 op_sel_hi:[1,0]
	s_nop 0
	v_pk_mul_f32 v[144:145], v[144:145], v[146:147]
	v_lshl_add_u64 v[146:147], v[140:141], 0, v[132:133]
	v_pk_mul_f32 v[100:101], v[100:101], v[144:145]
	v_lshl_add_u64 v[144:145], v[138:139], 0, v[132:133]
	s_waitcnt vmcnt(19)
	v_mov_b64_e32 v[144:145], v[238:239]
	v_lshl_add_u64 v[138:139], v[138:139], 0, v[130:131]
	s_waitcnt vmcnt(18)
	v_mov_b64_e32 v[146:147], v[240:241]
	v_lshl_add_u64 v[140:141], v[140:141], 0, v[130:131]
	s_waitcnt vmcnt(17)
	v_mov_b64_e32 v[138:139], v[242:243]
	s_nop 0
	s_waitcnt vmcnt(16)
; DI float bflo(unsigned u) { return __uint_as_float(u << 16); }
; DI float bfhi(unsigned u) { return __uint_as_float(u & 0xffff0000u); }
; DI float sigmoidf(float x) { return __builtin_amdgcn_rcpf(1.f + __expf(-x)); }
; DI float inv_sigmoidf(float x) { return 1.f + __expf(-x); }
; DI int TID8() { int t = threadIdx.x; asm volatile("" : "+v"(t)); return t; }
; template <class E>
; DI void gemm8_epi(f32x4 (&acc)[8][4], int m0, int n0, E e) {
;   const int tid = TID8(), lane = tid & 63, w = tid >> 6;
;   const int wm = w >> 2, wn = w & 3;
; #pragma unroll
;   for (int i = 0; i < 8; ++i)
; #pragma unroll
;     for (int j = 0; j < 4; ++j) {
;       const int m = m0 + wm * 128 + i * 16 + (lane & 15);
;       const int n = n0 + wn * 64 + j * 16 + (lane >> 4) * 4;
;       e(m, n, acc[i][j]);
;     }
; }
; __global__ void __launch_bounds__(512, 2) mega(Params p) {
;     ...
;       gemm8_epi(acc8, m0, n0, [&](int m, int n, f32x4& a) {
;         uint2 ua = *(const uint2*)(z + (size_t)m * ZS + C_MA + n);
;         uint2 ub = *(const uint2*)(z + (size_t)m * ZS + C_MB + n);
;         a[0] *= sigmoidf(bflo(ua.x)) * inv_sigmoidf(bflo(ub.x));
;         a[1] *= sigmoidf(bfhi(ua.x)) * inv_sigmoidf(bfhi(ub.x));
;         a[2] *= sigmoidf(bflo(ua.y)) * inv_sigmoidf(bflo(ub.y));
;         a[3] *= sigmoidf(bfhi(ua.y)) * inv_sigmoidf(bfhi(ub.y));
;       });
	v_mov_b64_e32 v[140:141], v[244:245]
	s_nop 0
	v_lshlrev_b32_e32 v143, 16, v144
	v_mul_f32_e32 v143, 0xbfb8aa3b, v143
	v_exp_f32_e32 v143, v143
	s_nop 0
	v_add_f32_e32 v143, 1.0, v143
	v_rcp_f32_e32 v148, v143
	s_nop 0
	v_lshlrev_b32_e32 v143, 16, v146
	v_mul_f32_e32 v143, 0xbfb8aa3b, v143
	v_exp_f32_e32 v150, v143
	v_and_b32_e32 v143, 0xffff0000, v144
	v_mul_f32_e32 v143, 0xbfb8aa3b, v143
	v_exp_f32_e32 v143, v143
	s_nop 0
	v_add_f32_e32 v143, 1.0, v143
	v_rcp_f32_e32 v149, v143
	v_and_b32_e32 v143, 0xffff0000, v146
	v_mul_f32_e32 v143, 0xbfb8aa3b, v143
	v_exp_f32_e32 v151, v143
	v_lshlrev_b32_e32 v143, 16, v145
	v_mul_f32_e32 v143, 0xbfb8aa3b, v143
	v_exp_f32_e32 v143, v143
	v_pk_add_f32 v[150:151], v[150:151], 1.0 op_sel_hi:[1,0]
	v_add_f32_e32 v143, 1.0, v143
	v_rcp_f32_e32 v144, v143
	v_lshlrev_b32_e32 v143, 16, v147
	v_mul_f32_e32 v143, 0xbfb8aa3b, v143
	v_exp_f32_e32 v146, v143
	v_and_b32_e32 v143, 0xffff0000, v145
	v_mul_f32_e32 v143, 0xbfb8aa3b, v143
	v_exp_f32_e32 v143, v143
	v_pk_mul_f32 v[148:149], v[148:149], v[150:151]
	v_add_f32_e32 v143, 1.0, v143
	v_rcp_f32_e32 v145, v143
	v_and_b32_e32 v143, 0xffff0000, v147
	v_mul_f32_e32 v143, 0xbfb8aa3b, v143
	v_exp_f32_e32 v147, v143
	s_nop 0
	v_lshlrev_b32_e32 v143, 16, v138
	v_and_b32_e32 v138, 0xffff0000, v138
	v_mul_f32_e32 v138, 0xbfb8aa3b, v138
	v_exp_f32_e32 v138, v138
	v_pk_add_f32 v[146:147], v[146:147], 1.0 op_sel_hi:[1,0]
	v_mul_f32_e32 v143, 0xbfb8aa3b, v143
	v_pk_mul_f32 v[144:145], v[144:145], v[146:147]
	v_add_f32_e32 v138, 1.0, v138
	v_pk_mul_f32 v[92:93], v[92:93], v[144:145]
	v_rcp_f32_e32 v145, v138
	s_nop 0
	v_and_b32_e32 v138, 0xffff0000, v140
	v_exp_f32_e32 v143, v143
	v_mul_f32_e32 v138, 0xbfb8aa3b, v138
	v_exp_f32_e32 v147, v138
	v_lshlrev_b32_e32 v138, 16, v139
	v_and_b32_e32 v139, 0xffff0000, v139
	v_mul_f32_e32 v138, 0xbfb8aa3b, v138
	v_mul_f32_e32 v139, 0xbfb8aa3b, v139
	v_exp_f32_e32 v138, v138
	v_exp_f32_e32 v139, v139
	v_add_f32_e32 v143, 1.0, v143
	v_rcp_f32_e32 v144, v143
	v_lshlrev_b32_e32 v143, 16, v140
	v_lshlrev_b32_e32 v140, 16, v141
	v_and_b32_e32 v141, 0xffff0000, v141
	v_mul_f32_e32 v140, 0xbfb8aa3b, v140
	v_mul_f32_e32 v141, 0xbfb8aa3b, v141
	v_add_f32_e32 v138, 1.0, v138
	v_exp_f32_e32 v140, v140
	v_add_f32_e32 v139, 1.0, v139
	v_exp_f32_e32 v141, v141
	v_rcp_f32_e32 v138, v138
	v_rcp_f32_e32 v139, v139
	v_mul_f32_e32 v143, 0xbfb8aa3b, v143
	v_exp_f32_e32 v146, v143
	v_pk_add_f32 v[140:141], v[140:141], 1.0 op_sel_hi:[1,0]
	v_pk_mul_f32 v[90:91], v[90:91], v[148:149]
	v_pk_mul_f32 v[138:139], v[138:139], v[140:141]
	v_pk_add_f32 v[146:147], v[146:147], 1.0 op_sel_hi:[1,0]
	v_pk_mul_f32 v[84:85], v[84:85], v[138:139]
	v_or_b32_e32 v138, 0x60, v142
	v_mad_i64_i32 v[140:141], s[26:27], v138, s35, v[136:137]
	v_pk_mul_f32 v[144:145], v[144:145], v[146:147]
	v_lshl_add_u64 v[138:139], v[140:141], 0, s[30:31]
	v_pk_mul_f32 v[82:83], v[82:83], v[144:145]
	v_lshl_add_u64 v[144:145], v[138:139], 0, v[0:1]
	s_waitcnt vmcnt(15)
	v_mov_b64_e32 v[144:145], v[198:199]
	v_lshl_add_u64 v[140:141], v[140:141], 0, s[42:43]
	v_lshl_add_u64 v[146:147], v[140:141], 0, v[0:1]
	s_waitcnt vmcnt(14)
	v_mov_b64_e32 v[146:147], v[200:201]
	s_nop 0
	v_lshlrev_b32_e32 v143, 16, v144
	v_mul_f32_e32 v143, 0xbfb8aa3b, v143
	v_exp_f32_e32 v143, v143
	s_nop 0
	v_add_f32_e32 v143, 1.0, v143
	v_rcp_f32_e32 v148, v143
	s_nop 0
	v_lshlrev_b32_e32 v143, 16, v146
	v_mul_f32_e32 v143, 0xbfb8aa3b, v143
	v_exp_f32_e32 v150, v143
	v_and_b32_e32 v143, 0xffff0000, v144
	v_mul_f32_e32 v143, 0xbfb8aa3b, v143
	v_exp_f32_e32 v143, v143
	s_nop 0
	v_add_f32_e32 v143, 1.0, v143
	v_rcp_f32_e32 v149, v143
	v_and_b32_e32 v143, 0xffff0000, v146
	v_mul_f32_e32 v143, 0xbfb8aa3b, v143
	v_exp_f32_e32 v151, v143
	v_lshlrev_b32_e32 v143, 16, v145
	v_mul_f32_e32 v143, 0xbfb8aa3b, v143
	v_exp_f32_e32 v143, v143
	v_pk_add_f32 v[150:151], v[150:151], 1.0 op_sel_hi:[1,0]
	v_add_f32_e32 v143, 1.0, v143
	v_rcp_f32_e32 v144, v143
	v_lshlrev_b32_e32 v143, 16, v147
	v_mul_f32_e32 v143, 0xbfb8aa3b, v143
	v_exp_f32_e32 v146, v143
	v_and_b32_e32 v143, 0xffff0000, v145
	v_mul_f32_e32 v143, 0xbfb8aa3b, v143
	v_exp_f32_e32 v143, v143
	v_pk_mul_f32 v[148:149], v[148:149], v[150:151]
	v_add_f32_e32 v143, 1.0, v143
	v_rcp_f32_e32 v145, v143
	v_and_b32_e32 v143, 0xffff0000, v147
	v_mul_f32_e32 v143, 0xbfb8aa3b, v143
	v_exp_f32_e32 v147, v143
	v_pk_mul_f32 v[74:75], v[74:75], v[148:149]
	v_pk_add_f32 v[146:147], v[146:147], 1.0 op_sel_hi:[1,0]
	s_nop 0
	v_pk_mul_f32 v[144:145], v[144:145], v[146:147]
	v_lshl_add_u64 v[146:147], v[140:141], 0, v[134:135]
	v_pk_mul_f32 v[76:77], v[76:77], v[144:145]
	v_lshl_add_u64 v[144:145], v[138:139], 0, v[134:135]
	s_waitcnt vmcnt(13)
	v_mov_b64_e32 v[144:145], v[202:203]
	s_nop 0
	s_waitcnt vmcnt(12)
	v_mov_b64_e32 v[146:147], v[204:205]
	s_nop 0
	v_lshlrev_b32_e32 v143, 16, v144
	v_mul_f32_e32 v143, 0xbfb8aa3b, v143
	v_exp_f32_e32 v143, v143
	s_nop 0
	v_add_f32_e32 v143, 1.0, v143
	v_rcp_f32_e32 v148, v143
	s_nop 0
	v_lshlrev_b32_e32 v143, 16, v146
	v_mul_f32_e32 v143, 0xbfb8aa3b, v143
	v_exp_f32_e32 v150, v143
	v_and_b32_e32 v143, 0xffff0000, v144
	v_mul_f32_e32 v143, 0xbfb8aa3b, v143
	v_exp_f32_e32 v143, v143
	s_nop 0
	v_add_f32_e32 v143, 1.0, v143
	v_rcp_f32_e32 v149, v143
	v_and_b32_e32 v143, 0xffff0000, v146
	v_mul_f32_e32 v143, 0xbfb8aa3b, v143
	v_exp_f32_e32 v151, v143
	v_lshlrev_b32_e32 v143, 16, v145
	v_mul_f32_e32 v143, 0xbfb8aa3b, v143
	v_exp_f32_e32 v143, v143
	v_pk_add_f32 v[150:151], v[150:151], 1.0 op_sel_hi:[1,0]
	v_add_f32_e32 v143, 1.0, v143
	v_rcp_f32_e32 v144, v143
	v_lshlrev_b32_e32 v143, 16, v147
	v_mul_f32_e32 v143, 0xbfb8aa3b, v143
	v_exp_f32_e32 v146, v143
	v_and_b32_e32 v143, 0xffff0000, v145
	v_mul_f32_e32 v143, 0xbfb8aa3b, v143
	v_exp_f32_e32 v143, v143
	v_pk_mul_f32 v[148:149], v[148:149], v[150:151]
	v_add_f32_e32 v143, 1.0, v143
	v_rcp_f32_e32 v145, v143
	v_and_b32_e32 v143, 0xffff0000, v147
	v_mul_f32_e32 v143, 0xbfb8aa3b, v143
	v_exp_f32_e32 v147, v143
	v_pk_mul_f32 v[66:67], v[66:67], v[148:149]
	v_pk_add_f32 v[146:147], v[146:147], 1.0 op_sel_hi:[1,0]
	s_nop 0
	v_pk_mul_f32 v[144:145], v[144:145], v[146:147]
	v_lshl_add_u64 v[146:147], v[140:141], 0, v[132:133]
	v_pk_mul_f32 v[68:69], v[68:69], v[144:145]
	v_lshl_add_u64 v[144:145], v[138:139], 0, v[132:133]
	s_waitcnt vmcnt(11)
; DI float bflo(unsigned u) { return __uint_as_float(u << 16); }
; DI float bfhi(unsigned u) { return __uint_as_float(u & 0xffff0000u); }
; DI float sigmoidf(float x) { return __builtin_amdgcn_rcpf(1.f + __expf(-x)); }
; DI float inv_sigmoidf(float x) { return 1.f + __expf(-x); }
; DI int TID8() { int t = threadIdx.x; asm volatile("" : "+v"(t)); return t; }
; template <class E>
; DI void gemm8_epi(f32x4 (&acc)[8][4], int m0, int n0, E e) {
;   const int tid = TID8(), lane = tid & 63, w = tid >> 6;
;   const int wm = w >> 2, wn = w & 3;
; #pragma unroll
;   for (int i = 0; i < 8; ++i)
; #pragma unroll
;     for (int j = 0; j < 4; ++j) {
;       const int m = m0 + wm * 128 + i * 16 + (lane & 15);
;       const int n = n0 + wn * 64 + j * 16 + (lane >> 4) * 4;
;       e(m, n, acc[i][j]);
;     }
; }
; __global__ void __launch_bounds__(512, 2) mega(Params p) {
;     ...
;       gemm8_epi(acc8, m0, n0, [&](int m, int n, f32x4& a) {
;         uint2 ua = *(const uint2*)(z + (size_t)m * ZS + C_MA + n);
;         uint2 ub = *(const uint2*)(z + (size_t)m * ZS + C_MB + n);
;         a[0] *= sigmoidf(bflo(ua.x)) * inv_sigmoidf(bflo(ub.x));
;         a[1] *= sigmoidf(bfhi(ua.x)) * inv_sigmoidf(bfhi(ub.x));
;         a[2] *= sigmoidf(bflo(ua.y)) * inv_sigmoidf(bflo(ub.y));
;         a[3] *= sigmoidf(bfhi(ua.y)) * inv_sigmoidf(bfhi(ub.y));
;       });
	v_mov_b64_e32 v[144:145], v[206:207]
	v_lshl_add_u64 v[138:139], v[138:139], 0, v[130:131]
	s_waitcnt vmcnt(10)
	v_mov_b64_e32 v[146:147], v[208:209]
	v_lshl_add_u64 v[140:141], v[140:141], 0, v[130:131]
	s_waitcnt vmcnt(9)
	v_mov_b64_e32 v[138:139], v[210:211]
	s_nop 0
	s_waitcnt vmcnt(8)
	v_mov_b64_e32 v[140:141], v[212:213]
	s_nop 0
	v_lshlrev_b32_e32 v143, 16, v144
	v_mul_f32_e32 v143, 0xbfb8aa3b, v143
	v_exp_f32_e32 v143, v143
	s_nop 0
	v_add_f32_e32 v143, 1.0, v143
	v_rcp_f32_e32 v148, v143
	s_nop 0
	v_lshlrev_b32_e32 v143, 16, v146
	v_mul_f32_e32 v143, 0xbfb8aa3b, v143
	v_exp_f32_e32 v150, v143
	v_and_b32_e32 v143, 0xffff0000, v144
	v_mul_f32_e32 v143, 0xbfb8aa3b, v143
	v_exp_f32_e32 v143, v143
	s_nop 0
	v_add_f32_e32 v143, 1.0, v143
	v_rcp_f32_e32 v149, v143
	v_and_b32_e32 v143, 0xffff0000, v146
	v_mul_f32_e32 v143, 0xbfb8aa3b, v143
	v_exp_f32_e32 v151, v143
	v_lshlrev_b32_e32 v143, 16, v145
	v_mul_f32_e32 v143, 0xbfb8aa3b, v143
	v_exp_f32_e32 v143, v143
	v_pk_add_f32 v[150:151], v[150:151], 1.0 op_sel_hi:[1,0]
	v_add_f32_e32 v143, 1.0, v143
	v_rcp_f32_e32 v144, v143
	v_lshlrev_b32_e32 v143, 16, v147
	v_mul_f32_e32 v143, 0xbfb8aa3b, v143
	v_exp_f32_e32 v146, v143
	v_and_b32_e32 v143, 0xffff0000, v145
	v_mul_f32_e32 v143, 0xbfb8aa3b, v143
	v_exp_f32_e32 v143, v143
	v_pk_mul_f32 v[148:149], v[148:149], v[150:151]
	v_add_f32_e32 v143, 1.0, v143
	v_rcp_f32_e32 v145, v143
	v_and_b32_e32 v143, 0xffff0000, v147
	v_mul_f32_e32 v143, 0xbfb8aa3b, v143
	v_exp_f32_e32 v147, v143
	s_nop 0
	v_lshlrev_b32_e32 v143, 16, v138
	v_and_b32_e32 v138, 0xffff0000, v138
	v_mul_f32_e32 v138, 0xbfb8aa3b, v138
	v_exp_f32_e32 v138, v138
	v_pk_add_f32 v[146:147], v[146:147], 1.0 op_sel_hi:[1,0]
	v_mul_f32_e32 v143, 0xbfb8aa3b, v143
	v_pk_mul_f32 v[144:145], v[144:145], v[146:147]
	v_add_f32_e32 v138, 1.0, v138
	v_pk_mul_f32 v[60:61], v[60:61], v[144:145]
	v_rcp_f32_e32 v145, v138
	s_nop 0
	v_and_b32_e32 v138, 0xffff0000, v140
	v_exp_f32_e32 v143, v143
	v_mul_f32_e32 v138, 0xbfb8aa3b, v138
	v_exp_f32_e32 v147, v138
	v_lshlrev_b32_e32 v138, 16, v139
	v_and_b32_e32 v139, 0xffff0000, v139
	v_mul_f32_e32 v138, 0xbfb8aa3b, v138
	v_mul_f32_e32 v139, 0xbfb8aa3b, v139
	v_exp_f32_e32 v138, v138
	v_exp_f32_e32 v139, v139
	v_add_f32_e32 v143, 1.0, v143
	v_rcp_f32_e32 v144, v143
	v_lshlrev_b32_e32 v143, 16, v140
	v_lshlrev_b32_e32 v140, 16, v141
	v_and_b32_e32 v141, 0xffff0000, v141
	v_mul_f32_e32 v140, 0xbfb8aa3b, v140
	v_mul_f32_e32 v141, 0xbfb8aa3b, v141
	v_add_f32_e32 v138, 1.0, v138
	v_exp_f32_e32 v140, v140
	v_add_f32_e32 v139, 1.0, v139
	v_exp_f32_e32 v141, v141
	v_rcp_f32_e32 v138, v138
	v_rcp_f32_e32 v139, v139
	v_mul_f32_e32 v143, 0xbfb8aa3b, v143
	v_pk_add_f32 v[140:141], v[140:141], 1.0 op_sel_hi:[1,0]
	v_exp_f32_e32 v146, v143
	v_pk_mul_f32 v[138:139], v[138:139], v[140:141]
	v_pk_mul_f32 v[58:59], v[58:59], v[148:149]
	v_pk_mul_f32 v[52:53], v[52:53], v[138:139]
	v_or_b32_e32 v138, 0x70, v142
	v_mad_i64_i32 v[138:139], s[26:27], v138, s35, v[136:137]
	v_lshl_add_u64 v[136:137], v[138:139], 0, s[30:31]
	v_lshl_add_u64 v[140:141], v[136:137], 0, v[0:1]
	s_waitcnt vmcnt(7)
	v_mov_b64_e32 v[140:141], v[214:215]
	v_lshl_add_u64 v[138:139], v[138:139], 0, s[42:43]
	v_lshl_add_u64 v[142:143], v[138:139], 0, v[0:1]
	s_waitcnt vmcnt(6)
	v_mov_b64_e32 v[142:143], v[216:217]
	v_pk_add_f32 v[146:147], v[146:147], 1.0 op_sel_hi:[1,0]
	s_nop 0
	v_lshlrev_b32_e32 v0, 16, v140
	v_mul_f32_e32 v0, 0xbfb8aa3b, v0
	v_exp_f32_e32 v0, v0
	v_pk_mul_f32 v[144:145], v[144:145], v[146:147]
	v_add_f32_e32 v0, 1.0, v0
	v_pk_mul_f32 v[50:51], v[50:51], v[144:145]
	v_rcp_f32_e32 v144, v0
	s_nop 0
	v_lshlrev_b32_e32 v0, 16, v142
	v_mul_f32_e32 v0, 0xbfb8aa3b, v0
	v_exp_f32_e32 v146, v0
	v_and_b32_e32 v0, 0xffff0000, v140
	v_mul_f32_e32 v0, 0xbfb8aa3b, v0
	v_exp_f32_e32 v0, v0
	s_nop 0
	v_add_f32_e32 v0, 1.0, v0
	v_rcp_f32_e32 v145, v0
	v_and_b32_e32 v0, 0xffff0000, v142
	v_mul_f32_e32 v0, 0xbfb8aa3b, v0
	v_exp_f32_e32 v147, v0
	v_lshlrev_b32_e32 v0, 16, v141
	v_mul_f32_e32 v0, 0xbfb8aa3b, v0
	v_exp_f32_e32 v0, v0
	v_pk_add_f32 v[146:147], v[146:147], 1.0 op_sel_hi:[1,0]
	v_add_f32_e32 v0, 1.0, v0
	v_rcp_f32_e32 v140, v0
	v_lshlrev_b32_e32 v0, 16, v143
	v_mul_f32_e32 v0, 0xbfb8aa3b, v0
	v_exp_f32_e32 v142, v0
	v_and_b32_e32 v0, 0xffff0000, v141
	v_mul_f32_e32 v0, 0xbfb8aa3b, v0
	v_exp_f32_e32 v0, v0
	v_pk_mul_f32 v[144:145], v[144:145], v[146:147]
	v_add_f32_e32 v0, 1.0, v0
	v_rcp_f32_e32 v141, v0
	v_and_b32_e32 v0, 0xffff0000, v143
	v_mul_f32_e32 v0, 0xbfb8aa3b, v0
	v_exp_f32_e32 v143, v0
	v_pk_mul_f32 v[42:43], v[42:43], v[144:145]
	v_pk_add_f32 v[142:143], v[142:143], 1.0 op_sel_hi:[1,0]
	s_nop 0
	v_pk_mul_f32 v[140:141], v[140:141], v[142:143]
	s_nop 0
	v_pk_mul_f32 v[44:45], v[44:45], v[140:141]
	v_lshl_add_u64 v[140:141], v[136:137], 0, v[134:135]
	s_waitcnt vmcnt(5)
	v_mov_b64_e32 v[140:141], v[218:219]
	v_lshl_add_u64 v[134:135], v[138:139], 0, v[134:135]
	s_waitcnt vmcnt(4)
; DI float bflo(unsigned u) { return __uint_as_float(u << 16); }
; DI float bfhi(unsigned u) { return __uint_as_float(u & 0xffff0000u); }
; DI float sigmoidf(float x) { return __builtin_amdgcn_rcpf(1.f + __expf(-x)); }
; DI float inv_sigmoidf(float x) { return 1.f + __expf(-x); }
; __global__ void __launch_bounds__(512, 2) mega(Params p) {
;     ...
;       gemm8_epi(acc8, m0, n0, [&](int m, int n, f32x4& a) {
;         uint2 ua = *(const uint2*)(z + (size_t)m * ZS + C_MA + n);
;         uint2 ub = *(const uint2*)(z + (size_t)m * ZS + C_MB + n);
;         a[0] *= sigmoidf(bflo(ua.x)) * inv_sigmoidf(bflo(ub.x));
;         a[1] *= sigmoidf(bfhi(ua.x)) * inv_sigmoidf(bfhi(ub.x));
;         a[2] *= sigmoidf(bflo(ua.y)) * inv_sigmoidf(bflo(ub.y));
;         a[3] *= sigmoidf(bfhi(ua.y)) * inv_sigmoidf(bfhi(ub.y));
;       });
	v_mov_b64_e32 v[134:135], v[220:221]
	s_nop 0
	v_lshlrev_b32_e32 v0, 16, v140
	v_mul_f32_e32 v0, 0xbfb8aa3b, v0
	v_exp_f32_e32 v0, v0
	s_nop 0
	v_add_f32_e32 v0, 1.0, v0
	v_rcp_f32_e32 v142, v0
	s_nop 0
	v_lshlrev_b32_e32 v0, 16, v134
	v_mul_f32_e32 v0, 0xbfb8aa3b, v0
	v_exp_f32_e32 v144, v0
	v_and_b32_e32 v0, 0xffff0000, v140
	v_mul_f32_e32 v0, 0xbfb8aa3b, v0
	v_exp_f32_e32 v0, v0
	s_nop 0
	v_add_f32_e32 v0, 1.0, v0
	v_rcp_f32_e32 v143, v0
	v_and_b32_e32 v0, 0xffff0000, v134
	v_mul_f32_e32 v0, 0xbfb8aa3b, v0
	v_exp_f32_e32 v145, v0
	v_lshlrev_b32_e32 v0, 16, v141
	v_mul_f32_e32 v0, 0xbfb8aa3b, v0
	v_exp_f32_e32 v0, v0
	v_pk_add_f32 v[144:145], v[144:145], 1.0 op_sel_hi:[1,0]
	v_add_f32_e32 v0, 1.0, v0
	v_rcp_f32_e32 v140, v0
	v_lshlrev_b32_e32 v0, 16, v135
	v_mul_f32_e32 v0, 0xbfb8aa3b, v0
	v_exp_f32_e32 v134, v0
	v_and_b32_e32 v0, 0xffff0000, v141
	v_mul_f32_e32 v0, 0xbfb8aa3b, v0
	v_exp_f32_e32 v0, v0
	v_pk_mul_f32 v[142:143], v[142:143], v[144:145]
	v_mov_b32_e32 v145, v1
	v_pk_mul_f32 v[34:35], v[34:35], v[142:143]
	v_add_f32_e32 v0, 1.0, v0
	v_rcp_f32_e32 v141, v0
	v_and_b32_e32 v0, 0xffff0000, v135
	v_mul_f32_e32 v0, 0xbfb8aa3b, v0
	v_exp_f32_e32 v135, v0
	s_nop 0
	v_pk_add_f32 v[134:135], v[134:135], 1.0 op_sel_hi:[1,0]
	s_nop 0
	v_pk_mul_f32 v[134:135], v[140:141], v[134:135]
	s_nop 0
	v_pk_mul_f32 v[36:37], v[36:37], v[134:135]
	v_lshl_add_u64 v[134:135], v[136:137], 0, v[132:133]
	s_waitcnt vmcnt(3)
	v_mov_b64_e32 v[134:135], v[222:223]
	v_lshl_add_u64 v[132:133], v[138:139], 0, v[132:133]
	s_waitcnt vmcnt(2)
	v_mov_b64_e32 v[132:133], v[224:225]
	s_nop 0
	v_lshlrev_b32_e32 v0, 16, v134
	v_mul_f32_e32 v0, 0xbfb8aa3b, v0
	v_exp_f32_e32 v0, v0
	s_nop 0
	v_add_f32_e32 v0, 1.0, v0
	v_rcp_f32_e32 v140, v0
	s_nop 0
	v_lshlrev_b32_e32 v0, 16, v132
	v_mul_f32_e32 v0, 0xbfb8aa3b, v0
	v_exp_f32_e32 v142, v0
	v_and_b32_e32 v0, 0xffff0000, v134
	v_mul_f32_e32 v0, 0xbfb8aa3b, v0
	v_exp_f32_e32 v0, v0
	s_nop 0
	v_add_f32_e32 v0, 1.0, v0
	v_rcp_f32_e32 v141, v0
	v_and_b32_e32 v0, 0xffff0000, v132
	v_mul_f32_e32 v0, 0xbfb8aa3b, v0
	v_exp_f32_e32 v143, v0
	v_lshlrev_b32_e32 v0, 16, v135
	v_mul_f32_e32 v0, 0xbfb8aa3b, v0
	v_exp_f32_e32 v0, v0
	v_pk_add_f32 v[142:143], v[142:143], 1.0 op_sel_hi:[1,0]
	v_add_f32_e32 v0, 1.0, v0
	v_rcp_f32_e32 v134, v0
	v_lshlrev_b32_e32 v0, 16, v133
	v_mul_f32_e32 v0, 0xbfb8aa3b, v0
	v_exp_f32_e32 v132, v0
	v_and_b32_e32 v0, 0xffff0000, v135
	v_mul_f32_e32 v0, 0xbfb8aa3b, v0
	v_exp_f32_e32 v0, v0
	v_pk_mul_f32 v[140:141], v[140:141], v[142:143]
	v_mov_b32_e32 v143, v1
	v_pk_mul_f32 v[26:27], v[26:27], v[140:141]
	v_add_f32_e32 v0, 1.0, v0
	v_rcp_f32_e32 v135, v0
	v_and_b32_e32 v0, 0xffff0000, v133
	v_mul_f32_e32 v0, 0xbfb8aa3b, v0
	v_exp_f32_e32 v133, v0
	s_nop 0
	v_pk_add_f32 v[132:133], v[132:133], 1.0 op_sel_hi:[1,0]
	s_nop 0
	v_pk_mul_f32 v[132:133], v[134:135], v[132:133]
	s_nop 0
	v_pk_mul_f32 v[28:29], v[28:29], v[132:133]
	v_lshl_add_u64 v[132:133], v[136:137], 0, v[130:131]
	s_waitcnt vmcnt(1)
	v_mov_b64_e32 v[132:133], v[226:227]
	v_lshl_add_u64 v[130:131], v[138:139], 0, v[130:131]
	s_waitcnt vmcnt(0)
; DI float bflo(unsigned u) { return __uint_as_float(u << 16); }
; DI float bfhi(unsigned u) { return __uint_as_float(u & 0xffff0000u); }
; DI float sigmoidf(float x) { return __builtin_amdgcn_rcpf(1.f + __expf(-x)); }
; DI float inv_sigmoidf(float x) { return 1.f + __expf(-x); }
; DI int TID8() { int t = threadIdx.x; asm volatile("" : "+v"(t)); return t; }
; DI void gemm8_accum(f32x4 (&acc)[8][4], const bf16_t* a, size_t lda, const bf16_t* b, size_t ldb, int nkb, bf16_t* L,
;                     const bool pre, const bf16_t* an, size_t ldan, const bf16_t* bn, size_t ldbn) {
;   const int tid = TID8(), lane = tid & 63, w = tid >> 6;
;   const int wm = w >> 2, wn = w & 3;
;   const int lrow = tid >> 3, lch = tid & 7;
;   u32x4 ra[4], rb[4];
;   unsigned offa[4], offb[4];
; #pragma unroll
;   for (int i = 0; i < 4; ++i) {
;     offa[i] = (unsigned)(lrow + 64 * i) * (unsigned)lda + (unsigned)(lch * 8);
;     offb[i] = (unsigned)(lrow + 64 * i) * (unsigned)ldb + (unsigned)(lch * 8);
;   }
;   if (!pre) {
;     g8_load1o(ra, a, offa);
;     g8_load1o(rb, b, offb);
;     __syncthreads();
;     g8_store(L, ra, rb, lrow, lch);
;   }
;   g8_load1o(ra, a + 64, offa);
;   g8_load1o(rb, b + 64, offb);
; __global__ void __launch_bounds__(512, 2) mega(Params p) {
;     ...
;       gemm8_epi(acc8, m0, n0, [&](int m, int n, f32x4& a) {
;         uint2 ua = *(const uint2*)(z + (size_t)m * ZS + C_MA + n);
;         uint2 ub = *(const uint2*)(z + (size_t)m * ZS + C_MB + n);
;         a[0] *= sigmoidf(bflo(ua.x)) * inv_sigmoidf(bflo(ub.x));
;         a[1] *= sigmoidf(bfhi(ua.x)) * inv_sigmoidf(bfhi(ub.x));
;         a[2] *= sigmoidf(bflo(ua.y)) * inv_sigmoidf(bflo(ub.y));
;         a[3] *= sigmoidf(bfhi(ua.y)) * inv_sigmoidf(bfhi(ub.y));
;       });
	v_mov_b64_e32 v[130:131], v[228:229]
	v_mov_b32_e32 v139, v1
	v_ashrrev_i32_e32 v173, 3, v172
	v_lshrrev_b32_e32 v140, 1, v173
	v_xor_b32_e32 v140, v140, v172
	v_lshlrev_b32_e32 v140, 3, v140
	v_and_b32_e32 v174, 56, v140
	v_lshrrev_b32_e32 v175, 1, v172
	v_bfe_u32 v176, v172, 1, 3
	v_lshlrev_b32_e32 v191, 1, v174
	v_lshlrev_b32_e32 v163, 6, v173
	s_nop 0
	v_lshlrev_b32_e32 v0, 16, v132
	v_mul_f32_e32 v0, 0xbfb8aa3b, v0
	v_exp_f32_e32 v0, v0
	s_nop 0
	v_add_f32_e32 v0, 1.0, v0
	v_rcp_f32_e32 v134, v0
	s_nop 0
	v_lshlrev_b32_e32 v0, 16, v130
	v_mul_f32_e32 v0, 0xbfb8aa3b, v0
	v_exp_f32_e32 v136, v0
	v_and_b32_e32 v0, 0xffff0000, v132
	v_mul_f32_e32 v0, 0xbfb8aa3b, v0
	v_exp_f32_e32 v0, v0
	s_nop 0
	v_add_f32_e32 v0, 1.0, v0
	v_rcp_f32_e32 v135, v0
	v_and_b32_e32 v0, 0xffff0000, v130
	v_mul_f32_e32 v0, 0xbfb8aa3b, v0
	v_exp_f32_e32 v137, v0
	v_lshlrev_b32_e32 v0, 16, v133
	v_mul_f32_e32 v0, 0xbfb8aa3b, v0
	v_exp_f32_e32 v0, v0
	v_pk_add_f32 v[136:137], v[136:137], 1.0 op_sel_hi:[1,0]
	v_add_f32_e32 v0, 1.0, v0
	v_rcp_f32_e32 v132, v0
	v_lshlrev_b32_e32 v0, 16, v131
	v_mul_f32_e32 v0, 0xbfb8aa3b, v0
	v_exp_f32_e32 v130, v0
	v_and_b32_e32 v0, 0xffff0000, v133
	v_mul_f32_e32 v0, 0xbfb8aa3b, v0
	v_exp_f32_e32 v0, v0
	v_pk_mul_f32 v[134:135], v[134:135], v[136:137]
	v_mov_b32_e32 v137, v1
	v_pk_mul_f32 v[18:19], v[18:19], v[134:135]
	v_add_f32_e32 v0, 1.0, v0
	v_rcp_f32_e32 v133, v0
	v_and_b32_e32 v0, 0xffff0000, v131
	v_mul_f32_e32 v0, 0xbfb8aa3b, v0
	v_exp_f32_e32 v131, v0
	v_lshlrev_b32_e32 v0, 3, v172
	v_and_b32_e32 v0, 56, v0
	v_mov_b32_e32 v135, v1
	v_pk_add_f32 v[130:131], v[130:131], 1.0 op_sel_hi:[1,0]
	s_nop 0
	v_pk_mul_f32 v[130:131], v[132:133], v[130:131]
	v_lshl_or_b32 v132, v173, 9, v0
	v_pk_mul_f32 v[20:21], v[20:21], v[130:131]
	v_mad_u64_u32 v[130:131], s[26:27], v173, s25, v[0:1]
	v_mov_b32_e32 v131, v1
	v_add_u32_e32 v144, 0x18000, v132
	v_add_u32_e32 v0, 0x54600, v130
	v_add_u32_e32 v142, 0x10000, v132
	v_lshlrev_b64 v[186:187], 1, v[130:131]
	v_lshlrev_b64 v[170:171], 1, v[144:145]
	v_add_u32_e32 v136, 0xa8c00, v130
	v_add_u32_e32 v138, 0xfd200, v130
	v_lshl_add_u64 v[130:131], s[2:3], 0, v[186:187]
	v_lshlrev_b64 v[184:185], 1, v[0:1]
	v_lshlrev_b64 v[168:169], 1, v[142:143]
	v_lshl_add_u64 v[142:143], s[6:7], 0, v[170:171]
	global_load_dwordx4 v[146:149], v[130:131], off offset:2736
	v_lshlrev_b64 v[182:183], 1, v[136:137]
	global_load_dwordx4 v[142:145], v[142:143], off offset:128
	v_lshl_add_u64 v[130:131], s[2:3], 0, v[184:185]
	v_add_u32_e32 v134, 0x8000, v132
	v_mov_b32_e32 v133, v1
	global_load_dwordx4 v[150:153], v[130:131], off offset:2736
	v_lshl_add_u64 v[130:131], s[2:3], 0, v[182:183]
	v_lshlrev_b64 v[180:181], 1, v[138:139]
	global_load_dwordx4 v[154:157], v[130:131], off offset:2736
	v_lshl_add_u64 v[130:131], s[2:3], 0, v[180:181]
	v_lshlrev_b64 v[164:165], 1, v[132:133]
	v_lshlrev_b64 v[166:167], 1, v[134:135]
	global_load_dwordx4 v[158:161], v[130:131], off offset:2736
	v_lshl_add_u64 v[130:131], s[6:7], 0, v[164:165]
	v_lshl_add_u64 v[134:135], s[6:7], 0, v[166:167]
	global_load_dwordx4 v[130:133], v[130:131], off offset:128
	v_bfe_u32 v0, v172, 4, 2
	global_load_dwordx4 v[138:141], v[134:135], off offset:128
	v_lshl_add_u64 v[134:135], s[6:7], 0, v[168:169]
	global_load_dwordx4 v[134:137], v[134:135], off offset:128
	v_bitop3_b32 v175, v175, v0, 7 bitop3:0x6c
	v_lshlrev_b32_e32 v192, 3, v175
	v_lshlrev_b32_e32 v175, 5, v172
	v_and_b32_e32 v175, 0xffffe000, v175
	v_lshlrev_b32_e32 v172, 6, v172
	v_and_or_b32 v188, v172, s1, v175
	v_readlane_b32 s1, v254, 20
	s_add_u32 s2, s1, s21
	v_readlane_b32 s1, v254, 21
	s_addc_u32 s3, s1, 0
	v_readlane_b32 s1, v254, 22
	v_bitop3_b32 v0, v0, v176, 4 bitop3:0x36
	s_add_u32 s0, s1, s0
	v_readlane_b32 s1, v254, 23
	v_and_b32_e32 v193, 0x33c0, v172
	v_lshlrev_b32_e32 v190, 3, v0
	v_lshlrev_b32_e32 v0, 7, v173
	s_addc_u32 s1, s1, 0
	v_add3_u32 v0, 0, v191, v0
	v_lshl_add_u64 v[172:173], s[2:3], 0, v[170:171]
	v_lshl_add_u64 v[174:175], s[2:3], 0, v[168:169]
	v_lshl_add_u64 v[176:177], s[2:3], 0, v[166:167]
	v_lshl_add_u64 v[178:179], s[2:3], 0, v[164:165]
	v_lshl_add_u64 v[180:181], s[0:1], 0, v[180:181]
	v_lshl_add_u64 v[182:183], s[0:1], 0, v[182:183]
	v_lshl_add_u64 v[184:185], s[0:1], 0, v[184:185]
	v_lshl_add_u64 v[186:187], s[0:1], 0, v[186:187]
	s_mov_b64 s[0:1], 0
	s_mov_b32 s2, 0
	v_lshlrev_b32_e32 v189, 1, v188
	v_lshlrev_b32_e32 v188, 1, v193
	v_readfirstlane_b32 s52, v186
	v_readfirstlane_b32 s53, v187
	s_sub_u32 s52, s52, 0x40000000
	s_subb_u32 s53, s53, 0
	v_readfirstlane_b32 s56, v178
	v_readfirstlane_b32 s57, v179
	s_sub_u32 s56, s56, 0x40000000
	s_subb_u32 s57, s57, 0
	v_subrev_u32_e32 v187, s52, v186
	v_subrev_u32_e32 v185, s52, v184
	v_subrev_u32_e32 v183, s52, v182
	v_subrev_u32_e32 v181, s52, v180
	v_subrev_u32_e32 v179, s56, v178
	v_subrev_u32_e32 v177, s56, v176
	v_subrev_u32_e32 v175, s56, v174
	v_subrev_u32_e32 v173, s56, v172

; DI f32x4 mfma16(bf16x8 a, bf16x8 b, f32x4 c) { return __builtin_amdgcn_mfma_f32_16x16x32_bf16(a, b, c, 0, 0, 0); }
; #pragma unroll
;   for (int ks = KS0; ks < KS1; ++ks) {
;     bf16x8 af[8], bfr[4];
; #pragma unroll
;     for (int i = 0; i < 8; ++i) {
;       const int r = wm * 128 + i * 16 + (lane & 15);
;       af[i] = *(const bf16x8*)(S + r * 64 + (((ks * 4 + (lane >> 4)) ^ ((r >> 1) & 7)) << 3));
;     }
; #pragma unroll
;     for (int j = 0; j < 4; ++j) {
;       const int r = wn * 64 + j * 16 + (lane & 15);
;       bfr[j] = *(const bf16x8*)(S + 16384 + r * 64 + (((ks * 4 + (lane >> 4)) ^ ((r >> 1) & 7)) << 3));
;     }
;     __builtin_amdgcn_s_setprio(1);
; #pragma unroll
;     for (int i = 0; i < 8; ++i)
; #pragma unroll
;       for (int j = 0; j < 4; ++j) acc[i][j] = mfma16(bfr[j], af[i], acc[i][j]);
;     __builtin_amdgcn_s_setprio(0);
;   }
; }
; DI void gemm8_accum(f32x4 (&acc)[8][4], const bf16_t* a, size_t lda, const bf16_t* b, size_t ldb, int nkb, bf16_t* L,
;                     const bool pre, const bf16_t* an, size_t ldan, const bf16_t* bn, size_t ldbn) {
;     ...
;   for (int kb = 0; kb + 2 < nkb; ++kb) {
;     __syncthreads();
;     g8_store1(L + ((kb + 1) & 1) * 32768, ra, lrow, lch);
;     g8_load1o(ra, a + (kb + 2) * 64, offa);
;     __builtin_amdgcn_sched_barrier(0);
;     g8_compute<0, 1>(acc, L + (kb & 1) * 32768, wm, wn, lane);
;     __builtin_amdgcn_sched_barrier(0);
;     g8_store1(L + ((kb + 1) & 1) * 32768 + 16384, rb, lrow, lch);
;     g8_load1o(rb, b + (kb + 2) * 64, offb);
;     __builtin_amdgcn_sched_barrier(0);
;     g8_compute<1, 2>(acc, L + (kb & 1) * 32768, wm, wn, lane);
;   }
.Lstg_780_a:
	s_waitcnt vmcnt(7)
	ds_write_b128 v193, v[146:149]
	s_waitcnt vmcnt(5)
	ds_write_b128 v193, v[150:153] offset:8192
	s_waitcnt vmcnt(4)
	ds_write_b128 v193, v[154:157] offset:16384
	s_waitcnt vmcnt(3)
	ds_write_b128 v193, v[158:161] offset:24576
	s_add_u32 s54, s52, s0
	s_addc_u32 s55, s53, s1
	global_load_dwordx4 v[146:149], v187, s[54:55]
	s_nop 0
	global_load_dwordx4 v[150:153], v185, s[54:55]
	s_nop 0
	global_load_dwordx4 v[154:157], v183, s[54:55]
	s_nop 0
	global_load_dwordx4 v[158:161], v181, s[54:55]
	s_and_b32 s2, s2, 0x8000
	s_lshl_b32 s2, s2, 1
	s_add_i32 s2, s2, 0
	v_lshl_add_u32 v194, v192, 1, s2
	v_add_u32_e32 v195, v194, v189
	ds_read_b128 v[198:201], v195
	ds_read_b128 v[206:209], v195 offset:2048
	ds_read_b128 v[210:213], v195 offset:4096
	ds_read_b128 v[214:217], v195 offset:6144
	ds_read_b128 v[218:221], v195 offset:8192
	ds_read_b128 v[222:225], v195 offset:10240
	ds_read_b128 v[226:229], v195 offset:12288
	ds_read_b128 v[230:233], v195 offset:14336
	v_add_u32_e32 v194, v194, v188
	ds_read_b128 v[234:237], v194 offset:32768
	ds_read_b128 v[238:241], v194 offset:34816
	ds_read_b128 v[242:245], v194 offset:36864
	ds_read_b128 v[246:249], v194 offset:38912
	s_waitcnt lgkmcnt(3)
	v_mfma_f32_16x16x32_bf16 v[2:5], v[234:237], v[198:201], v[2:5]
	s_waitcnt lgkmcnt(2)
	v_mfma_f32_16x16x32_bf16 v[6:9], v[238:241], v[198:201], v[6:9]
	s_waitcnt lgkmcnt(1)
	v_mfma_f32_16x16x32_bf16 v[10:13], v[242:245], v[198:201], v[10:13]
	s_waitcnt lgkmcnt(0)
	v_mfma_f32_16x16x32_bf16 v[14:17], v[246:249], v[198:201], v[14:17]
	v_mfma_f32_16x16x32_bf16 v[22:25], v[234:237], v[206:209], v[22:25]
	v_mfma_f32_16x16x32_bf16 v[30:33], v[238:241], v[206:209], v[30:33]
	v_mfma_f32_16x16x32_bf16 v[38:41], v[242:245], v[206:209], v[38:41]
	v_mfma_f32_16x16x32_bf16 v[46:49], v[246:249], v[206:209], v[46:49]
	v_mfma_f32_16x16x32_bf16 v[54:57], v[234:237], v[210:213], v[54:57]
	v_mfma_f32_16x16x32_bf16 v[62:65], v[238:241], v[210:213], v[62:65]
	v_mfma_f32_16x16x32_bf16 v[70:73], v[242:245], v[210:213], v[70:73]
	v_mfma_f32_16x16x32_bf16 v[78:81], v[246:249], v[210:213], v[78:81]
	v_mfma_f32_16x16x32_bf16 v[86:89], v[234:237], v[214:217], v[86:89]
	v_mfma_f32_16x16x32_bf16 v[94:97], v[238:241], v[214:217], v[94:97]
	v_mfma_f32_16x16x32_bf16 v[102:105], v[242:245], v[214:217], v[102:105]
	v_mfma_f32_16x16x32_bf16 v[110:113], v[246:249], v[214:217], v[110:113]
	v_mfma_f32_16x16x32_bf16 v[118:121], v[234:237], v[218:221], v[118:121]
	v_mfma_f32_16x16x32_bf16 v[126:129], v[238:241], v[218:221], v[126:129]
	v_mfma_f32_16x16x32_bf16 v[122:125], v[242:245], v[218:221], v[122:125]
	v_mfma_f32_16x16x32_bf16 v[114:117], v[246:249], v[218:221], v[114:117]
	v_mfma_f32_16x16x32_bf16 v[106:109], v[234:237], v[222:225], v[106:109]
	v_mfma_f32_16x16x32_bf16 v[98:101], v[238:241], v[222:225], v[98:101]
	v_mfma_f32_16x16x32_bf16 v[90:93], v[242:245], v[222:225], v[90:93]
	v_mfma_f32_16x16x32_bf16 v[82:85], v[246:249], v[222:225], v[82:85]
	v_mfma_f32_16x16x32_bf16 v[74:77], v[234:237], v[226:229], v[74:77]
	v_mfma_f32_16x16x32_bf16 v[66:69], v[238:241], v[226:229], v[66:69]
	v_mfma_f32_16x16x32_bf16 v[58:61], v[242:245], v[226:229], v[58:61]
	v_mfma_f32_16x16x32_bf16 v[50:53], v[246:249], v[226:229], v[50:53]
	v_mfma_f32_16x16x32_bf16 v[42:45], v[234:237], v[230:233], v[42:45]
	v_mfma_f32_16x16x32_bf16 v[34:37], v[238:241], v[230:233], v[34:37]
	v_mfma_f32_16x16x32_bf16 v[26:29], v[242:245], v[230:233], v[26:29]
	v_mfma_f32_16x16x32_bf16 v[18:21], v[246:249], v[230:233], v[18:21]
	s_waitcnt vmcnt(6)
	ds_write_b128 v193, v[130:133] offset:32768
	s_waitcnt vmcnt(5)
	ds_write_b128 v193, v[138:141] offset:40960
	s_waitcnt vmcnt(4)
	ds_write_b128 v193, v[134:137] offset:49152
	ds_write_b128 v193, v[142:145] offset:57344
	s_add_u32 s58, s56, s0
	s_addc_u32 s59, s57, s1
	global_load_dwordx4 v[130:133], v179, s[58:59]
	s_nop 0
	global_load_dwordx4 v[138:141], v177, s[58:59]
	global_load_dwordx4 v[134:137], v175, s[58:59]
	s_nop 0
	global_load_dwordx4 v[142:145], v173, s[58:59]
	v_lshl_add_u32 v193, v190, 1, s2
	v_add_u32_e32 v194, v193, v189
	ds_read_b128 v[198:201], v194
	ds_read_b128 v[206:209], v194 offset:2048
	ds_read_b128 v[210:213], v194 offset:4096
	ds_read_b128 v[214:217], v194 offset:6144
	ds_read_b128 v[218:221], v194 offset:8192
	ds_read_b128 v[222:225], v194 offset:10240
	ds_read_b128 v[226:229], v194 offset:12288
	ds_read_b128 v[230:233], v194 offset:14336
	v_add_u32_e32 v193, v193, v188
	ds_read_b128 v[234:237], v193 offset:32768
	ds_read_b128 v[238:241], v193 offset:34816
	ds_read_b128 v[242:245], v193 offset:36864
	ds_read_b128 v[246:249], v193 offset:38912
	s_cmp_lg_u32 s101, 0
	s_cbranch_scc1 .Lstg_780_b
	s_waitcnt lgkmcnt(3)
	v_mfma_f32_16x16x32_bf16 v[2:5], v[234:237], v[198:201], v[2:5]
	s_waitcnt lgkmcnt(2)
	v_mfma_f32_16x16x32_bf16 v[6:9], v[238:241], v[198:201], v[6:9]
	s_waitcnt lgkmcnt(1)
	v_mfma_f32_16x16x32_bf16 v[10:13], v[242:245], v[198:201], v[10:13]
	s_waitcnt lgkmcnt(0)
	v_mfma_f32_16x16x32_bf16 v[14:17], v[246:249], v[198:201], v[14:17]
	v_mfma_f32_16x16x32_bf16 v[22:25], v[234:237], v[206:209], v[22:25]
	v_mfma_f32_16x16x32_bf16 v[30:33], v[238:241], v[206:209], v[30:33]
	v_mfma_f32_16x16x32_bf16 v[38:41], v[242:245], v[206:209], v[38:41]
	v_mfma_f32_16x16x32_bf16 v[46:49], v[246:249], v[206:209], v[46:49]
	v_mfma_f32_16x16x32_bf16 v[54:57], v[234:237], v[210:213], v[54:57]
	v_mfma_f32_16x16x32_bf16 v[62:65], v[238:241], v[210:213], v[62:65]
	v_mfma_f32_16x16x32_bf16 v[70:73], v[242:245], v[210:213], v[70:73]
	v_mfma_f32_16x16x32_bf16 v[78:81], v[246:249], v[210:213], v[78:81]
	v_mfma_f32_16x16x32_bf16 v[86:89], v[234:237], v[214:217], v[86:89]
	v_mfma_f32_16x16x32_bf16 v[94:97], v[238:241], v[214:217], v[94:97]
	v_mfma_f32_16x16x32_bf16 v[102:105], v[242:245], v[214:217], v[102:105]
	v_mfma_f32_16x16x32_bf16 v[110:113], v[246:249], v[214:217], v[110:113]
	v_mfma_f32_16x16x32_bf16 v[118:121], v[234:237], v[218:221], v[118:121]
	v_mfma_f32_16x16x32_bf16 v[126:129], v[238:241], v[218:221], v[126:129]
	v_mfma_f32_16x16x32_bf16 v[122:125], v[242:245], v[218:221], v[122:125]
	v_mfma_f32_16x16x32_bf16 v[114:117], v[246:249], v[218:221], v[114:117]
	v_mfma_f32_16x16x32_bf16 v[106:109], v[234:237], v[222:225], v[106:109]
	v_mfma_f32_16x16x32_bf16 v[98:101], v[238:241], v[222:225], v[98:101]
	v_mfma_f32_16x16x32_bf16 v[90:93], v[242:245], v[222:225], v[90:93]
	v_mfma_f32_16x16x32_bf16 v[82:85], v[246:249], v[222:225], v[82:85]
	v_mfma_f32_16x16x32_bf16 v[74:77], v[234:237], v[226:229], v[74:77]
	v_mfma_f32_16x16x32_bf16 v[66:69], v[238:241], v[226:229], v[66:69]
	v_mfma_f32_16x16x32_bf16 v[58:61], v[242:245], v[226:229], v[58:61]
	v_mfma_f32_16x16x32_bf16 v[50:53], v[246:249], v[226:229], v[50:53]
	v_mfma_f32_16x16x32_bf16 v[42:45], v[234:237], v[230:233], v[42:45]
	v_mfma_f32_16x16x32_bf16 v[34:37], v[238:241], v[230:233], v[34:37]
	v_mfma_f32_16x16x32_bf16 v[26:29], v[242:245], v[230:233], v[26:29]
	v_mfma_f32_16x16x32_bf16 v[18:21], v[246:249], v[230:233], v[18:21]

; DI f32x4 mfma16(bf16x8 a, bf16x8 b, f32x4 c) { return __builtin_amdgcn_mfma_f32_16x16x32_bf16(a, b, c, 0, 0, 0); }
; #pragma unroll
;   for (int ks = KS0; ks < KS1; ++ks) {
;     bf16x8 af[8], bfr[4];
; #pragma unroll
;     for (int i = 0; i < 8; ++i) {
;       const int r = wm * 128 + i * 16 + (lane & 15);
;       af[i] = *(const bf16x8*)(S + r * 64 + (((ks * 4 + (lane >> 4)) ^ ((r >> 1) & 7)) << 3));
;     }
; #pragma unroll
;     for (int j = 0; j < 4; ++j) {
;       const int r = wn * 64 + j * 16 + (lane & 15);
;       bfr[j] = *(const bf16x8*)(S + 16384 + r * 64 + (((ks * 4 + (lane >> 4)) ^ ((r >> 1) & 7)) << 3));
;     }
;     __builtin_amdgcn_s_setprio(1);
; #pragma unroll
;     for (int i = 0; i < 8; ++i)
; #pragma unroll
;       for (int j = 0; j < 4; ++j) acc[i][j] = mfma16(bfr[j], af[i], acc[i][j]);
;     __builtin_amdgcn_s_setprio(0);
;   }
; }
; DI void gemm8_accum(f32x4 (&acc)[8][4], const bf16_t* a, size_t lda, const bf16_t* b, size_t ldb, int nkb, bf16_t* L,
;                     const bool pre, const bf16_t* an, size_t ldan, const bf16_t* bn, size_t ldbn) {
;     ...
;   for (int kb = 0; kb + 2 < nkb; ++kb) {
;     __syncthreads();
;     g8_store1(L + ((kb + 1) & 1) * 32768, ra, lrow, lch);
;     g8_load1o(ra, a + (kb + 2) * 64, offa);
;     __builtin_amdgcn_sched_barrier(0);
;     g8_compute<0, 1>(acc, L + (kb & 1) * 32768, wm, wn, lane);
;     __builtin_amdgcn_sched_barrier(0);
;     g8_store1(L + ((kb + 1) & 1) * 32768 + 16384, rb, lrow, lch);
;     g8_load1o(rb, b + (kb + 2) * 64, offb);
;     __builtin_amdgcn_sched_barrier(0);
;     g8_compute<1, 2>(acc, L + (kb & 1) * 32768, wm, wn, lane);
;   }
.Lstg_830_a:
	s_waitcnt vmcnt(7)
	ds_write_b128 v171, v[18:21]
	s_waitcnt vmcnt(6)
	ds_write_b128 v171, v[22:25] offset:8192
	s_waitcnt vmcnt(5)
	ds_write_b128 v171, v[26:29] offset:16384
	s_waitcnt vmcnt(4)
	ds_write_b128 v171, v[30:33] offset:24576
	s_add_u32 s54, s52, s0
	s_addc_u32 s55, s53, s1
	global_load_dwordx4 v[18:21], v193, s[54:55]
	s_nop 0
	global_load_dwordx4 v[22:25], v191, s[54:55]
	s_nop 0
	global_load_dwordx4 v[26:29], v189, s[54:55]
	s_nop 0
	global_load_dwordx4 v[30:33], v187, s[54:55]
	s_and_b32 s2, s2, 0x8000
	s_lshl_b32 s2, s2, 1
	s_add_i32 s2, s2, 0
	v_lshl_add_u32 v173, v169, 1, s2
	v_add_u32_e32 v175, v173, v195
	ds_read_b128 v[198:201], v175
	ds_read_b128 v[206:209], v175 offset:2048
	ds_read_b128 v[210:213], v175 offset:4096
	ds_read_b128 v[214:217], v175 offset:6144
	ds_read_b128 v[218:221], v175 offset:8192
	ds_read_b128 v[222:225], v175 offset:10240
	ds_read_b128 v[226:229], v175 offset:12288
	ds_read_b128 v[230:233], v175 offset:14336
	v_add_u32_e32 v173, v173, v194
	ds_read_b128 v[234:237], v173 offset:32768
	ds_read_b128 v[238:241], v173 offset:34816
	ds_read_b128 v[242:245], v173 offset:36864
	ds_read_b128 v[246:249], v173 offset:38912
	s_waitcnt lgkmcnt(3)
	v_mfma_f32_16x16x32_bf16 v[158:161], v[234:237], v[198:201], v[158:161]
	s_waitcnt lgkmcnt(2)
	v_mfma_f32_16x16x32_bf16 v[154:157], v[238:241], v[198:201], v[154:157]
	s_waitcnt lgkmcnt(1)
	v_mfma_f32_16x16x32_bf16 v[150:153], v[242:245], v[198:201], v[150:153]
	s_waitcnt lgkmcnt(0)
	v_mfma_f32_16x16x32_bf16 v[146:149], v[246:249], v[198:201], v[146:149]
	v_mfma_f32_16x16x32_bf16 v[142:145], v[234:237], v[206:209], v[142:145]
	v_mfma_f32_16x16x32_bf16 v[138:141], v[238:241], v[206:209], v[138:141]
	v_mfma_f32_16x16x32_bf16 v[134:137], v[242:245], v[206:209], v[134:137]
	v_mfma_f32_16x16x32_bf16 v[130:133], v[246:249], v[206:209], v[130:133]
	v_mfma_f32_16x16x32_bf16 v[126:129], v[234:237], v[210:213], v[126:129]
	v_mfma_f32_16x16x32_bf16 v[122:125], v[238:241], v[210:213], v[122:125]
	v_mfma_f32_16x16x32_bf16 v[118:121], v[242:245], v[210:213], v[118:121]
	v_mfma_f32_16x16x32_bf16 v[114:117], v[246:249], v[210:213], v[114:117]
	v_mfma_f32_16x16x32_bf16 v[110:113], v[234:237], v[214:217], v[110:113]
	v_mfma_f32_16x16x32_bf16 v[106:109], v[238:241], v[214:217], v[106:109]
	v_mfma_f32_16x16x32_bf16 v[102:105], v[242:245], v[214:217], v[102:105]
	v_mfma_f32_16x16x32_bf16 v[98:101], v[246:249], v[214:217], v[98:101]
	v_mfma_f32_16x16x32_bf16 v[94:97], v[234:237], v[218:221], v[94:97]
	v_mfma_f32_16x16x32_bf16 v[90:93], v[238:241], v[218:221], v[90:93]
	v_mfma_f32_16x16x32_bf16 v[86:89], v[242:245], v[218:221], v[86:89]
	v_mfma_f32_16x16x32_bf16 v[82:85], v[246:249], v[218:221], v[82:85]
	v_mfma_f32_16x16x32_bf16 v[78:81], v[234:237], v[222:225], v[78:81]
	v_mfma_f32_16x16x32_bf16 v[74:77], v[238:241], v[222:225], v[74:77]
	v_mfma_f32_16x16x32_bf16 v[70:73], v[242:245], v[222:225], v[70:73]
	v_mfma_f32_16x16x32_bf16 v[66:69], v[246:249], v[222:225], v[66:69]
	v_mfma_f32_16x16x32_bf16 v[62:65], v[234:237], v[226:229], v[62:65]
	v_mfma_f32_16x16x32_bf16 v[58:61], v[238:241], v[226:229], v[58:61]
	v_mfma_f32_16x16x32_bf16 v[54:57], v[242:245], v[226:229], v[54:57]
	v_mfma_f32_16x16x32_bf16 v[50:53], v[246:249], v[226:229], v[50:53]
	v_mfma_f32_16x16x32_bf16 v[46:49], v[234:237], v[230:233], v[46:49]
	v_mfma_f32_16x16x32_bf16 v[42:45], v[238:241], v[230:233], v[42:45]
	v_mfma_f32_16x16x32_bf16 v[38:41], v[242:245], v[230:233], v[38:41]
	v_mfma_f32_16x16x32_bf16 v[34:37], v[246:249], v[230:233], v[34:37]
	s_waitcnt vmcnt(7)
	ds_write_b128 v171, v[14:17] offset:32768
	s_waitcnt vmcnt(6)
	ds_write_b128 v171, v[2:5] offset:40960
	s_waitcnt vmcnt(5)
	ds_write_b128 v171, v[6:9] offset:49152
	s_waitcnt vmcnt(4)
	ds_write_b128 v171, v[10:13] offset:57344
	s_add_u32 s58, s56, s0
	s_addc_u32 s59, s57, s1
	global_load_dwordx4 v[14:17], v185, s[58:59]
	s_nop 0
	global_load_dwordx4 v[2:5], v183, s[58:59]
	s_nop 0
	global_load_dwordx4 v[6:9], v181, s[58:59]
	s_nop 0
	global_load_dwordx4 v[10:13], v179, s[58:59]
	v_lshl_add_u32 v171, v205, 1, s2
	v_add_u32_e32 v173, v171, v195
	ds_read_b128 v[198:201], v173
	ds_read_b128 v[206:209], v173 offset:2048
	ds_read_b128 v[210:213], v173 offset:4096
	ds_read_b128 v[214:217], v173 offset:6144
	ds_read_b128 v[218:221], v173 offset:8192
	ds_read_b128 v[222:225], v173 offset:10240
	ds_read_b128 v[226:229], v173 offset:12288
	ds_read_b128 v[230:233], v173 offset:14336
	v_add_u32_e32 v171, v171, v194
	ds_read_b128 v[234:237], v171 offset:32768
	ds_read_b128 v[238:241], v171 offset:34816
	ds_read_b128 v[242:245], v171 offset:36864
	ds_read_b128 v[246:249], v171 offset:38912
	s_cmp_lg_u32 s101, 0
	s_cbranch_scc1 .Lstg_830_b
; DI f32x4 mfma16(bf16x8 a, bf16x8 b, f32x4 c) { return __builtin_amdgcn_mfma_f32_16x16x32_bf16(a, b, c, 0, 0, 0); }
; #pragma unroll
;   for (int ks = KS0; ks < KS1; ++ks) {
;     bf16x8 af[8], bfr[4];
; #pragma unroll
;     for (int i = 0; i < 8; ++i) {
;       const int r = wm * 128 + i * 16 + (lane & 15);
;       af[i] = *(const bf16x8*)(S + r * 64 + (((ks * 4 + (lane >> 4)) ^ ((r >> 1) & 7)) << 3));
;     }
; #pragma unroll
;     for (int j = 0; j < 4; ++j) {
;       const int r = wn * 64 + j * 16 + (lane & 15);
;       bfr[j] = *(const bf16x8*)(S + 16384 + r * 64 + (((ks * 4 + (lane >> 4)) ^ ((r >> 1) & 7)) << 3));
;     }
;     __builtin_amdgcn_s_setprio(1);
; #pragma unroll
;     for (int i = 0; i < 8; ++i)
; #pragma unroll
;       for (int j = 0; j < 4; ++j) acc[i][j] = mfma16(bfr[j], af[i], acc[i][j]);
;     __builtin_amdgcn_s_setprio(0);
;   }
; }
	s_waitcnt lgkmcnt(3)
	v_mfma_f32_16x16x32_bf16 v[158:161], v[234:237], v[198:201], v[158:161]
	s_waitcnt lgkmcnt(2)
	v_mfma_f32_16x16x32_bf16 v[154:157], v[238:241], v[198:201], v[154:157]
	s_waitcnt lgkmcnt(1)
	v_mfma_f32_16x16x32_bf16 v[150:153], v[242:245], v[198:201], v[150:153]
	s_waitcnt lgkmcnt(0)
	v_mfma_f32_16x16x32_bf16 v[146:149], v[246:249], v[198:201], v[146:149]
	v_mfma_f32_16x16x32_bf16 v[142:145], v[234:237], v[206:209], v[142:145]
	v_mfma_f32_16x16x32_bf16 v[138:141], v[238:241], v[206:209], v[138:141]
	v_mfma_f32_16x16x32_bf16 v[134:137], v[242:245], v[206:209], v[134:137]
	v_mfma_f32_16x16x32_bf16 v[130:133], v[246:249], v[206:209], v[130:133]
	v_mfma_f32_16x16x32_bf16 v[126:129], v[234:237], v[210:213], v[126:129]
	v_mfma_f32_16x16x32_bf16 v[122:125], v[238:241], v[210:213], v[122:125]
	v_mfma_f32_16x16x32_bf16 v[118:121], v[242:245], v[210:213], v[118:121]
	v_mfma_f32_16x16x32_bf16 v[114:117], v[246:249], v[210:213], v[114:117]
	v_mfma_f32_16x16x32_bf16 v[110:113], v[234:237], v[214:217], v[110:113]
	v_mfma_f32_16x16x32_bf16 v[106:109], v[238:241], v[214:217], v[106:109]
	v_mfma_f32_16x16x32_bf16 v[102:105], v[242:245], v[214:217], v[102:105]
	v_mfma_f32_16x16x32_bf16 v[98:101], v[246:249], v[214:217], v[98:101]
	v_mfma_f32_16x16x32_bf16 v[94:97], v[234:237], v[218:221], v[94:97]
	v_mfma_f32_16x16x32_bf16 v[90:93], v[238:241], v[218:221], v[90:93]
	v_mfma_f32_16x16x32_bf16 v[86:89], v[242:245], v[218:221], v[86:89]
	v_mfma_f32_16x16x32_bf16 v[82:85], v[246:249], v[218:221], v[82:85]
	v_mfma_f32_16x16x32_bf16 v[78:81], v[234:237], v[222:225], v[78:81]
	v_mfma_f32_16x16x32_bf16 v[74:77], v[238:241], v[222:225], v[74:77]
	v_mfma_f32_16x16x32_bf16 v[70:73], v[242:245], v[222:225], v[70:73]
	v_mfma_f32_16x16x32_bf16 v[66:69], v[246:249], v[222:225], v[66:69]
	v_mfma_f32_16x16x32_bf16 v[62:65], v[234:237], v[226:229], v[62:65]
	v_mfma_f32_16x16x32_bf16 v[58:61], v[238:241], v[226:229], v[58:61]
	v_mfma_f32_16x16x32_bf16 v[54:57], v[242:245], v[226:229], v[54:57]
	v_mfma_f32_16x16x32_bf16 v[50:53], v[246:249], v[226:229], v[50:53]
	v_mfma_f32_16x16x32_bf16 v[46:49], v[234:237], v[230:233], v[46:49]
	v_mfma_f32_16x16x32_bf16 v[42:45], v[238:241], v[230:233], v[42:45]
	v_mfma_f32_16x16x32_bf16 v[38:41], v[242:245], v[230:233], v[38:41]
	v_mfma_f32_16x16x32_bf16 v[34:37], v[246:249], v[230:233], v[34:37]

; DI f32x4 mfma16(bf16x8 a, bf16x8 b, f32x4 c) { return __builtin_amdgcn_mfma_f32_16x16x32_bf16(a, b, c, 0, 0, 0); }
; #pragma unroll
;   for (int ks = KS0; ks < KS1; ++ks) {
;     bf16x8 af[8], bfr[4];
; #pragma unroll
;     for (int i = 0; i < 8; ++i) {
;       const int r = wm * 128 + i * 16 + (lane & 15);
;       af[i] = *(const bf16x8*)(S + r * 64 + (((ks * 4 + (lane >> 4)) ^ ((r >> 1) & 7)) << 3));
;     }
; #pragma unroll
;     for (int j = 0; j < 4; ++j) {
;       const int r = wn * 64 + j * 16 + (lane & 15);
;       bfr[j] = *(const bf16x8*)(S + 16384 + r * 64 + (((ks * 4 + (lane >> 4)) ^ ((r >> 1) & 7)) << 3));
;     }
;     __builtin_amdgcn_s_setprio(1);
; #pragma unroll
;     for (int i = 0; i < 8; ++i)
; #pragma unroll
;       for (int j = 0; j < 4; ++j) acc[i][j] = mfma16(bfr[j], af[i], acc[i][j]);
;     __builtin_amdgcn_s_setprio(0);
;   }
; }
; DI void gemm8_accum(f32x4 (&acc)[8][4], const bf16_t* a, size_t lda, const bf16_t* b, size_t ldb, int nkb, bf16_t* L,
;                     const bool pre, const bf16_t* an, size_t ldan, const bf16_t* bn, size_t ldbn) {
;     ...
;   for (int kb = 0; kb + 2 < nkb; ++kb) {
;     __syncthreads();
;     g8_store1(L + ((kb + 1) & 1) * 32768, ra, lrow, lch);
;     g8_load1o(ra, a + (kb + 2) * 64, offa);
;     __builtin_amdgcn_sched_barrier(0);
;     g8_compute<0, 1>(acc, L + (kb & 1) * 32768, wm, wn, lane);
;     __builtin_amdgcn_sched_barrier(0);
;     g8_store1(L + ((kb + 1) & 1) * 32768 + 16384, rb, lrow, lch);
;     g8_load1o(rb, b + (kb + 2) * 64, offb);
;     __builtin_amdgcn_sched_barrier(0);
;     g8_compute<1, 2>(acc, L + (kb & 1) * 32768, wm, wn, lane);
;   }
.Lstg_892_a:
	s_waitcnt vmcnt(5)
	ds_write_b128 v167, v[22:25]
	ds_write_b128 v167, v[18:21] offset:8192
	ds_write_b128 v167, v[26:29] offset:16384
	s_waitcnt vmcnt(4)
	ds_write_b128 v167, v[30:33] offset:24576
	s_add_u32 s54, s52, s0
	s_addc_u32 s55, s53, s1
	global_load_dwordx4 v[22:25], v185, s[54:55]
	global_load_dwordx4 v[26:29], v181, s[54:55]
	global_load_dwordx4 v[18:21], v183, s[54:55]
	s_nop 0
	global_load_dwordx4 v[30:33], v179, s[54:55]
	s_and_b32 s2, s2, 0x8000
	s_lshl_b32 s2, s2, 1
	s_add_i32 s2, s2, 0
	v_lshl_add_u32 v169, v191, 1, s2
	v_add_u32_e32 v202, v169, v187
	ds_read_b128 v[192:195], v202
	ds_read_b128 v[198:201], v202 offset:2048
	ds_read_b128 v[206:209], v202 offset:4096
	ds_read_b128 v[210:213], v202 offset:6144
	ds_read_b128 v[214:217], v202 offset:8192
	ds_read_b128 v[218:221], v202 offset:10240
	ds_read_b128 v[222:225], v202 offset:12288
	ds_read_b128 v[226:229], v202 offset:14336
	v_add_u32_e32 v169, v169, v186
	ds_read_b128 v[230:233], v169 offset:32768
	ds_read_b128 v[234:237], v169 offset:34816
	ds_read_b128 v[238:241], v169 offset:36864
	ds_read_b128 v[242:245], v169 offset:38912
	s_waitcnt lgkmcnt(3)
	v_mfma_f32_16x16x32_bf16 v[158:161], v[230:233], v[192:195], v[158:161]
	s_waitcnt lgkmcnt(2)
	v_mfma_f32_16x16x32_bf16 v[154:157], v[234:237], v[192:195], v[154:157]
	s_waitcnt lgkmcnt(1)
	v_mfma_f32_16x16x32_bf16 v[150:153], v[238:241], v[192:195], v[150:153]
	s_waitcnt lgkmcnt(0)
	v_mfma_f32_16x16x32_bf16 v[146:149], v[242:245], v[192:195], v[146:149]
	v_mfma_f32_16x16x32_bf16 v[142:145], v[230:233], v[198:201], v[142:145]
	v_mfma_f32_16x16x32_bf16 v[138:141], v[234:237], v[198:201], v[138:141]
	v_mfma_f32_16x16x32_bf16 v[134:137], v[238:241], v[198:201], v[134:137]
	v_mfma_f32_16x16x32_bf16 v[130:133], v[242:245], v[198:201], v[130:133]
	v_mfma_f32_16x16x32_bf16 v[126:129], v[230:233], v[206:209], v[126:129]
	v_mfma_f32_16x16x32_bf16 v[122:125], v[234:237], v[206:209], v[122:125]
	v_mfma_f32_16x16x32_bf16 v[118:121], v[238:241], v[206:209], v[118:121]
	v_mfma_f32_16x16x32_bf16 v[114:117], v[242:245], v[206:209], v[114:117]
	v_mfma_f32_16x16x32_bf16 v[110:113], v[230:233], v[210:213], v[110:113]
	v_mfma_f32_16x16x32_bf16 v[106:109], v[234:237], v[210:213], v[106:109]
	v_mfma_f32_16x16x32_bf16 v[102:105], v[238:241], v[210:213], v[102:105]
	v_mfma_f32_16x16x32_bf16 v[98:101], v[242:245], v[210:213], v[98:101]
	v_mfma_f32_16x16x32_bf16 v[94:97], v[230:233], v[214:217], v[94:97]
	v_mfma_f32_16x16x32_bf16 v[90:93], v[234:237], v[214:217], v[90:93]
	v_mfma_f32_16x16x32_bf16 v[86:89], v[238:241], v[214:217], v[86:89]
	v_mfma_f32_16x16x32_bf16 v[82:85], v[242:245], v[214:217], v[82:85]
	v_mfma_f32_16x16x32_bf16 v[78:81], v[230:233], v[218:221], v[78:81]
	v_mfma_f32_16x16x32_bf16 v[74:77], v[234:237], v[218:221], v[74:77]
	v_mfma_f32_16x16x32_bf16 v[70:73], v[238:241], v[218:221], v[70:73]
	v_mfma_f32_16x16x32_bf16 v[66:69], v[242:245], v[218:221], v[66:69]
	v_mfma_f32_16x16x32_bf16 v[62:65], v[230:233], v[222:225], v[62:65]
	v_mfma_f32_16x16x32_bf16 v[58:61], v[234:237], v[222:225], v[58:61]
	v_mfma_f32_16x16x32_bf16 v[54:57], v[238:241], v[222:225], v[54:57]
	v_mfma_f32_16x16x32_bf16 v[50:53], v[242:245], v[222:225], v[50:53]
	v_mfma_f32_16x16x32_bf16 v[46:49], v[230:233], v[226:229], v[46:49]
	v_mfma_f32_16x16x32_bf16 v[42:45], v[234:237], v[226:229], v[42:45]
	v_mfma_f32_16x16x32_bf16 v[38:41], v[238:241], v[226:229], v[38:41]
	v_mfma_f32_16x16x32_bf16 v[34:37], v[242:245], v[226:229], v[34:37]
	s_waitcnt vmcnt(7)
	ds_write_b128 v167, v[14:17] offset:32768
	s_waitcnt vmcnt(6)
	ds_write_b128 v167, v[2:5] offset:40960
	s_waitcnt vmcnt(5)
	ds_write_b128 v167, v[6:9] offset:49152
	s_waitcnt vmcnt(4)
	ds_write_b128 v167, v[10:13] offset:57344
	s_add_u32 s58, s56, s0
	s_addc_u32 s59, s57, s1
	global_load_dwordx4 v[14:17], v177, s[58:59]
	s_nop 0
	global_load_dwordx4 v[2:5], v175, s[58:59]
	s_nop 0
	global_load_dwordx4 v[6:9], v173, s[58:59]
	s_nop 0
	global_load_dwordx4 v[10:13], v171, s[58:59]
	v_lshl_add_u32 v167, v188, 1, s2
	v_add_u32_e32 v169, v167, v187
	ds_read_b128 v[192:195], v169
	ds_read_b128 v[198:201], v169 offset:2048
	ds_read_b128 v[206:209], v169 offset:4096
	ds_read_b128 v[210:213], v169 offset:6144
	ds_read_b128 v[214:217], v169 offset:8192
	ds_read_b128 v[218:221], v169 offset:10240
	ds_read_b128 v[222:225], v169 offset:12288
	ds_read_b128 v[226:229], v169 offset:14336
	v_add_u32_e32 v167, v167, v186
	ds_read_b128 v[230:233], v167 offset:32768
	ds_read_b128 v[234:237], v167 offset:34816
	ds_read_b128 v[238:241], v167 offset:36864
	ds_read_b128 v[242:245], v167 offset:38912
	s_cmp_lg_u32 s101, 0
	s_cbranch_scc1 .Lstg_892_b
	s_waitcnt lgkmcnt(3)
	v_mfma_f32_16x16x32_bf16 v[158:161], v[230:233], v[192:195], v[158:161]
	s_waitcnt lgkmcnt(2)
	v_mfma_f32_16x16x32_bf16 v[154:157], v[234:237], v[192:195], v[154:157]
	s_waitcnt lgkmcnt(1)
	v_mfma_f32_16x16x32_bf16 v[150:153], v[238:241], v[192:195], v[150:153]
	s_waitcnt lgkmcnt(0)
	v_mfma_f32_16x16x32_bf16 v[146:149], v[242:245], v[192:195], v[146:149]
	v_mfma_f32_16x16x32_bf16 v[142:145], v[230:233], v[198:201], v[142:145]
	v_mfma_f32_16x16x32_bf16 v[138:141], v[234:237], v[198:201], v[138:141]
	v_mfma_f32_16x16x32_bf16 v[134:137], v[238:241], v[198:201], v[134:137]
	v_mfma_f32_16x16x32_bf16 v[130:133], v[242:245], v[198:201], v[130:133]
	v_mfma_f32_16x16x32_bf16 v[126:129], v[230:233], v[206:209], v[126:129]
	v_mfma_f32_16x16x32_bf16 v[122:125], v[234:237], v[206:209], v[122:125]
	v_mfma_f32_16x16x32_bf16 v[118:121], v[238:241], v[206:209], v[118:121]
	v_mfma_f32_16x16x32_bf16 v[114:117], v[242:245], v[206:209], v[114:117]
	v_mfma_f32_16x16x32_bf16 v[110:113], v[230:233], v[210:213], v[110:113]
	v_mfma_f32_16x16x32_bf16 v[106:109], v[234:237], v[210:213], v[106:109]
	v_mfma_f32_16x16x32_bf16 v[102:105], v[238:241], v[210:213], v[102:105]
	v_mfma_f32_16x16x32_bf16 v[98:101], v[242:245], v[210:213], v[98:101]
	v_mfma_f32_16x16x32_bf16 v[94:97], v[230:233], v[214:217], v[94:97]
	v_mfma_f32_16x16x32_bf16 v[90:93], v[234:237], v[214:217], v[90:93]
	v_mfma_f32_16x16x32_bf16 v[86:89], v[238:241], v[214:217], v[86:89]
	v_mfma_f32_16x16x32_bf16 v[82:85], v[242:245], v[214:217], v[82:85]
	v_mfma_f32_16x16x32_bf16 v[78:81], v[230:233], v[218:221], v[78:81]
	v_mfma_f32_16x16x32_bf16 v[74:77], v[234:237], v[218:221], v[74:77]
	v_mfma_f32_16x16x32_bf16 v[70:73], v[238:241], v[218:221], v[70:73]
	v_mfma_f32_16x16x32_bf16 v[66:69], v[242:245], v[218:221], v[66:69]
	v_mfma_f32_16x16x32_bf16 v[62:65], v[230:233], v[222:225], v[62:65]
	v_mfma_f32_16x16x32_bf16 v[58:61], v[234:237], v[222:225], v[58:61]
	v_mfma_f32_16x16x32_bf16 v[54:57], v[238:241], v[222:225], v[54:57]
	v_mfma_f32_16x16x32_bf16 v[50:53], v[242:245], v[222:225], v[50:53]
	v_mfma_f32_16x16x32_bf16 v[46:49], v[230:233], v[226:229], v[46:49]
	v_mfma_f32_16x16x32_bf16 v[42:45], v[234:237], v[226:229], v[42:45]
	v_mfma_f32_16x16x32_bf16 v[38:41], v[238:241], v[226:229], v[38:41]
	v_mfma_f32_16x16x32_bf16 v[34:37], v[242:245], v[226:229], v[34:37]

; DI f32x4 mfma16(bf16x8 a, bf16x8 b, f32x4 c) { return __builtin_amdgcn_mfma_f32_16x16x32_bf16(a, b, c, 0, 0, 0); }
; #pragma unroll
;   for (int ks = KS0; ks < KS1; ++ks) {
;     bf16x8 af[8], bfr[4];
; #pragma unroll
;     for (int i = 0; i < 8; ++i) {
;       const int r = wm * 128 + i * 16 + (lane & 15);
;       af[i] = *(const bf16x8*)(S + r * 64 + (((ks * 4 + (lane >> 4)) ^ ((r >> 1) & 7)) << 3));
;     }
; #pragma unroll
;     for (int j = 0; j < 4; ++j) {
;       const int r = wn * 64 + j * 16 + (lane & 15);
;       bfr[j] = *(const bf16x8*)(S + 16384 + r * 64 + (((ks * 4 + (lane >> 4)) ^ ((r >> 1) & 7)) << 3));
;     }
;     __builtin_amdgcn_s_setprio(1);
; #pragma unroll
;     for (int i = 0; i < 8; ++i)
; #pragma unroll
;       for (int j = 0; j < 4; ++j) acc[i][j] = mfma16(bfr[j], af[i], acc[i][j]);
;     __builtin_amdgcn_s_setprio(0);
;   }
; }
; DI void gemm8_accum(f32x4 (&acc)[8][4], const bf16_t* a, size_t lda, const bf16_t* b, size_t ldb, int nkb, bf16_t* L,
;                     const bool pre, const bf16_t* an, size_t ldan, const bf16_t* bn, size_t ldbn) {
;     ...
;   for (int kb = 0; kb + 2 < nkb; ++kb) {
;     __syncthreads();
;     g8_store1(L + ((kb + 1) & 1) * 32768, ra, lrow, lch);
;     g8_load1o(ra, a + (kb + 2) * 64, offa);
;     __builtin_amdgcn_sched_barrier(0);
;     g8_compute<0, 1>(acc, L + (kb & 1) * 32768, wm, wn, lane);
;     __builtin_amdgcn_sched_barrier(0);
;     g8_store1(L + ((kb + 1) & 1) * 32768 + 16384, rb, lrow, lch);
;     g8_load1o(rb, b + (kb + 2) * 64, offb);
;     __builtin_amdgcn_sched_barrier(0);
;     g8_compute<1, 2>(acc, L + (kb & 1) * 32768, wm, wn, lane);
;   }
.Lstg_942_a:
	s_waitcnt vmcnt(5)
	ds_write_b128 v167, v[22:25]
	ds_write_b128 v167, v[18:21] offset:8192
	ds_write_b128 v167, v[26:29] offset:16384
	s_waitcnt vmcnt(4)
	ds_write_b128 v167, v[30:33] offset:24576
	s_add_u32 s54, s52, s0
	s_addc_u32 s55, s53, s1
	global_load_dwordx4 v[22:25], v185, s[54:55]
	global_load_dwordx4 v[26:29], v181, s[54:55]
	global_load_dwordx4 v[18:21], v183, s[54:55]
	s_nop 0
	global_load_dwordx4 v[30:33], v179, s[54:55]
	s_and_b32 s2, s2, 0x8000
	s_lshl_b32 s2, s2, 1
	s_add_i32 s2, s2, 0
	v_lshl_add_u32 v169, v191, 1, s2
	v_add_u32_e32 v222, v169, v187
	ds_read_b128 v[192:195], v222
	ds_read_b128 v[198:201], v222 offset:2048
	ds_read_b128 v[202:205], v222 offset:4096
	ds_read_b128 v[206:209], v222 offset:6144
	ds_read_b128 v[210:213], v222 offset:8192
	ds_read_b128 v[214:217], v222 offset:10240
	ds_read_b128 v[218:221], v222 offset:12288
	ds_read_b128 v[222:225], v222 offset:14336
	v_add_u32_e32 v169, v169, v186
	ds_read_b128 v[226:229], v169 offset:32768
	ds_read_b128 v[230:233], v169 offset:34816
	ds_read_b128 v[234:237], v169 offset:36864
	ds_read_b128 v[238:241], v169 offset:38912
	s_waitcnt lgkmcnt(3)
	v_mfma_f32_16x16x32_bf16 v[158:161], v[226:229], v[192:195], v[158:161]
	s_waitcnt lgkmcnt(2)
	v_mfma_f32_16x16x32_bf16 v[154:157], v[230:233], v[192:195], v[154:157]
	s_waitcnt lgkmcnt(1)
	v_mfma_f32_16x16x32_bf16 v[150:153], v[234:237], v[192:195], v[150:153]
	s_waitcnt lgkmcnt(0)
	v_mfma_f32_16x16x32_bf16 v[146:149], v[238:241], v[192:195], v[146:149]
	v_mfma_f32_16x16x32_bf16 v[142:145], v[226:229], v[198:201], v[142:145]
	v_mfma_f32_16x16x32_bf16 v[138:141], v[230:233], v[198:201], v[138:141]
	v_mfma_f32_16x16x32_bf16 v[134:137], v[234:237], v[198:201], v[134:137]
	v_mfma_f32_16x16x32_bf16 v[130:133], v[238:241], v[198:201], v[130:133]
	v_mfma_f32_16x16x32_bf16 v[126:129], v[226:229], v[202:205], v[126:129]
	v_mfma_f32_16x16x32_bf16 v[122:125], v[230:233], v[202:205], v[122:125]
	v_mfma_f32_16x16x32_bf16 v[118:121], v[234:237], v[202:205], v[118:121]
	v_mfma_f32_16x16x32_bf16 v[114:117], v[238:241], v[202:205], v[114:117]
	v_mfma_f32_16x16x32_bf16 v[110:113], v[226:229], v[206:209], v[110:113]
	v_mfma_f32_16x16x32_bf16 v[106:109], v[230:233], v[206:209], v[106:109]
	v_mfma_f32_16x16x32_bf16 v[102:105], v[234:237], v[206:209], v[102:105]
	v_mfma_f32_16x16x32_bf16 v[98:101], v[238:241], v[206:209], v[98:101]
	v_mfma_f32_16x16x32_bf16 v[94:97], v[226:229], v[210:213], v[94:97]
	v_mfma_f32_16x16x32_bf16 v[90:93], v[230:233], v[210:213], v[90:93]
	v_mfma_f32_16x16x32_bf16 v[86:89], v[234:237], v[210:213], v[86:89]
	v_mfma_f32_16x16x32_bf16 v[82:85], v[238:241], v[210:213], v[82:85]
	v_mfma_f32_16x16x32_bf16 v[78:81], v[226:229], v[214:217], v[78:81]
	v_mfma_f32_16x16x32_bf16 v[74:77], v[230:233], v[214:217], v[74:77]
	v_mfma_f32_16x16x32_bf16 v[70:73], v[234:237], v[214:217], v[70:73]
	v_mfma_f32_16x16x32_bf16 v[66:69], v[238:241], v[214:217], v[66:69]
	v_mfma_f32_16x16x32_bf16 v[62:65], v[226:229], v[218:221], v[62:65]
	v_mfma_f32_16x16x32_bf16 v[58:61], v[230:233], v[218:221], v[58:61]
	v_mfma_f32_16x16x32_bf16 v[54:57], v[234:237], v[218:221], v[54:57]
	v_mfma_f32_16x16x32_bf16 v[50:53], v[238:241], v[218:221], v[50:53]
	v_mfma_f32_16x16x32_bf16 v[46:49], v[226:229], v[222:225], v[46:49]
	v_mfma_f32_16x16x32_bf16 v[42:45], v[230:233], v[222:225], v[42:45]
	v_mfma_f32_16x16x32_bf16 v[38:41], v[234:237], v[222:225], v[38:41]
	v_mfma_f32_16x16x32_bf16 v[34:37], v[238:241], v[222:225], v[34:37]
	s_waitcnt vmcnt(7)
	ds_write_b128 v167, v[14:17] offset:32768
	s_waitcnt vmcnt(6)
	ds_write_b128 v167, v[2:5] offset:40960
	s_waitcnt vmcnt(5)
	ds_write_b128 v167, v[6:9] offset:49152
	s_waitcnt vmcnt(4)
	ds_write_b128 v167, v[10:13] offset:57344
	s_add_u32 s58, s56, s0
	s_addc_u32 s59, s57, s1
	global_load_dwordx4 v[14:17], v177, s[58:59]
	s_nop 0
	global_load_dwordx4 v[2:5], v175, s[58:59]
	s_nop 0
	global_load_dwordx4 v[6:9], v173, s[58:59]
	s_nop 0
	global_load_dwordx4 v[10:13], v171, s[58:59]
	v_lshl_add_u32 v167, v188, 1, s2
	v_add_u32_e32 v169, v167, v187
	ds_read_b128 v[192:195], v169
	ds_read_b128 v[198:201], v169 offset:2048
	ds_read_b128 v[202:205], v169 offset:4096
	ds_read_b128 v[206:209], v169 offset:6144
	ds_read_b128 v[210:213], v169 offset:8192
	ds_read_b128 v[214:217], v169 offset:10240
	ds_read_b128 v[218:221], v169 offset:12288
	ds_read_b128 v[222:225], v169 offset:14336
	v_add_u32_e32 v167, v167, v186
	ds_read_b128 v[226:229], v167 offset:32768
	ds_read_b128 v[230:233], v167 offset:34816
	ds_read_b128 v[234:237], v167 offset:36864
	ds_read_b128 v[238:241], v167 offset:38912
	s_cmp_lg_u32 s101, 0
	s_cbranch_scc1 .Lstg_942_b
	s_waitcnt lgkmcnt(3)
	v_mfma_f32_16x16x32_bf16 v[158:161], v[226:229], v[192:195], v[158:161]
	s_waitcnt lgkmcnt(2)
	v_mfma_f32_16x16x32_bf16 v[154:157], v[230:233], v[192:195], v[154:157]
	s_waitcnt lgkmcnt(1)
	v_mfma_f32_16x16x32_bf16 v[150:153], v[234:237], v[192:195], v[150:153]
	s_waitcnt lgkmcnt(0)
	v_mfma_f32_16x16x32_bf16 v[146:149], v[238:241], v[192:195], v[146:149]
	v_mfma_f32_16x16x32_bf16 v[142:145], v[226:229], v[198:201], v[142:145]
	v_mfma_f32_16x16x32_bf16 v[138:141], v[230:233], v[198:201], v[138:141]
	v_mfma_f32_16x16x32_bf16 v[134:137], v[234:237], v[198:201], v[134:137]
	v_mfma_f32_16x16x32_bf16 v[130:133], v[238:241], v[198:201], v[130:133]
	v_mfma_f32_16x16x32_bf16 v[126:129], v[226:229], v[202:205], v[126:129]
	v_mfma_f32_16x16x32_bf16 v[122:125], v[230:233], v[202:205], v[122:125]
	v_mfma_f32_16x16x32_bf16 v[118:121], v[234:237], v[202:205], v[118:121]
	v_mfma_f32_16x16x32_bf16 v[114:117], v[238:241], v[202:205], v[114:117]
	v_mfma_f32_16x16x32_bf16 v[110:113], v[226:229], v[206:209], v[110:113]
	v_mfma_f32_16x16x32_bf16 v[106:109], v[230:233], v[206:209], v[106:109]
	v_mfma_f32_16x16x32_bf16 v[102:105], v[234:237], v[206:209], v[102:105]
	v_mfma_f32_16x16x32_bf16 v[98:101], v[238:241], v[206:209], v[98:101]
	v_mfma_f32_16x16x32_bf16 v[94:97], v[226:229], v[210:213], v[94:97]
	v_mfma_f32_16x16x32_bf16 v[90:93], v[230:233], v[210:213], v[90:93]
	v_mfma_f32_16x16x32_bf16 v[86:89], v[234:237], v[210:213], v[86:89]
	v_mfma_f32_16x16x32_bf16 v[82:85], v[238:241], v[210:213], v[82:85]
	v_mfma_f32_16x16x32_bf16 v[78:81], v[226:229], v[214:217], v[78:81]
	v_mfma_f32_16x16x32_bf16 v[74:77], v[230:233], v[214:217], v[74:77]
	v_mfma_f32_16x16x32_bf16 v[70:73], v[234:237], v[214:217], v[70:73]
	v_mfma_f32_16x16x32_bf16 v[66:69], v[238:241], v[214:217], v[66:69]
	v_mfma_f32_16x16x32_bf16 v[62:65], v[226:229], v[218:221], v[62:65]
	v_mfma_f32_16x16x32_bf16 v[58:61], v[230:233], v[218:221], v[58:61]
	v_mfma_f32_16x16x32_bf16 v[54:57], v[234:237], v[218:221], v[54:57]
	v_mfma_f32_16x16x32_bf16 v[50:53], v[238:241], v[218:221], v[50:53]
	v_mfma_f32_16x16x32_bf16 v[46:49], v[226:229], v[222:225], v[46:49]
	v_mfma_f32_16x16x32_bf16 v[42:45], v[230:233], v[222:225], v[42:45]
	v_mfma_f32_16x16x32_bf16 v[38:41], v[234:237], v[222:225], v[38:41]
	v_mfma_f32_16x16x32_bf16 v[34:37], v[238:241], v[222:225], v[34:37]

; DI f32x4 mfma16(bf16x8 a, bf16x8 b, f32x4 c) { return __builtin_amdgcn_mfma_f32_16x16x32_bf16(a, b, c, 0, 0, 0); }
; #pragma unroll
;   for (int ks = KS0; ks < KS1; ++ks) {
;     bf16x8 af[8], bfr[4];
; #pragma unroll
;     for (int i = 0; i < 8; ++i) {
;       const int r = wm * 128 + i * 16 + (lane & 15);
;       af[i] = *(const bf16x8*)(S + r * 64 + (((ks * 4 + (lane >> 4)) ^ ((r >> 1) & 7)) << 3));
;     }
; #pragma unroll
;     for (int j = 0; j < 4; ++j) {
;       const int r = wn * 64 + j * 16 + (lane & 15);
;       bfr[j] = *(const bf16x8*)(S + 16384 + r * 64 + (((ks * 4 + (lane >> 4)) ^ ((r >> 1) & 7)) << 3));
;     }
;     __builtin_amdgcn_s_setprio(1);
; #pragma unroll
;     for (int i = 0; i < 8; ++i)
; #pragma unroll
;       for (int j = 0; j < 4; ++j) acc[i][j] = mfma16(bfr[j], af[i], acc[i][j]);
;     __builtin_amdgcn_s_setprio(0);
;   }
; }
; DI void gemm8_accum(f32x4 (&acc)[8][4], const bf16_t* a, size_t lda, const bf16_t* b, size_t ldb, int nkb, bf16_t* L,
;                     const bool pre, const bf16_t* an, size_t ldan, const bf16_t* bn, size_t ldbn) {
;     ...
;   for (int kb = 0; kb + 2 < nkb; ++kb) {
;     __syncthreads();
;     g8_store1(L + ((kb + 1) & 1) * 32768, ra, lrow, lch);
;     g8_load1o(ra, a + (kb + 2) * 64, offa);
;     __builtin_amdgcn_sched_barrier(0);
;     g8_compute<0, 1>(acc, L + (kb & 1) * 32768, wm, wn, lane);
;     __builtin_amdgcn_sched_barrier(0);
;     g8_store1(L + ((kb + 1) & 1) * 32768 + 16384, rb, lrow, lch);
;     g8_load1o(rb, b + (kb + 2) * 64, offb);
;     __builtin_amdgcn_sched_barrier(0);
;     g8_compute<1, 2>(acc, L + (kb & 1) * 32768, wm, wn, lane);
;   }
.Lstg_1007_a:
	s_waitcnt vmcnt(7)
	ds_write_b128 v0, v[34:37]
	s_waitcnt vmcnt(6)
	ds_write_b128 v0, v[42:45] offset:8192
	s_waitcnt vmcnt(5)
	ds_write_b128 v0, v[54:57] offset:16384
	s_waitcnt vmcnt(4)
	ds_write_b128 v0, v[94:97] offset:24576
	s_add_u32 s54, s52, s0
	s_addc_u32 s55, s53, s1
	global_load_dwordx4 v[34:37], v179, s[54:55]
	s_nop 0
	global_load_dwordx4 v[42:45], v177, s[54:55]
	s_nop 0
	global_load_dwordx4 v[54:57], v175, s[54:55]
	s_nop 0
	global_load_dwordx4 v[94:97], v173, s[54:55]
	s_and_b32 s2, s2, 0x8000
	s_lshl_b32 s2, s2, 1
	s_add_i32 s2, s2, 0
	v_lshl_add_u32 v191, v186, 1, s2
	v_add_u32_e32 v222, v191, v181
	ds_read_b128 v[192:195], v222
	ds_read_b128 v[198:201], v222 offset:2048
	ds_read_b128 v[202:205], v222 offset:4096
	ds_read_b128 v[206:209], v222 offset:6144
	ds_read_b128 v[210:213], v222 offset:8192
	ds_read_b128 v[214:217], v222 offset:10240
	ds_read_b128 v[218:221], v222 offset:12288
	ds_read_b128 v[222:225], v222 offset:14336
	v_add_u32_e32 v191, v191, v180
	ds_read_b128 v[226:229], v191 offset:32768
	ds_read_b128 v[230:233], v191 offset:34816
	ds_read_b128 v[234:237], v191 offset:36864
	ds_read_b128 v[238:241], v191 offset:38912
	s_waitcnt lgkmcnt(3)
	v_mfma_f32_16x16x32_bf16 v[158:161], v[226:229], v[192:195], v[158:161]
	s_waitcnt lgkmcnt(2)
	v_mfma_f32_16x16x32_bf16 v[154:157], v[230:233], v[192:195], v[154:157]
	s_waitcnt lgkmcnt(1)
	v_mfma_f32_16x16x32_bf16 v[150:153], v[234:237], v[192:195], v[150:153]
	s_waitcnt lgkmcnt(0)
	v_mfma_f32_16x16x32_bf16 v[146:149], v[238:241], v[192:195], v[146:149]
	v_mfma_f32_16x16x32_bf16 v[142:145], v[226:229], v[198:201], v[142:145]
	v_mfma_f32_16x16x32_bf16 v[138:141], v[230:233], v[198:201], v[138:141]
	v_mfma_f32_16x16x32_bf16 v[134:137], v[234:237], v[198:201], v[134:137]
	v_mfma_f32_16x16x32_bf16 v[130:133], v[238:241], v[198:201], v[130:133]
	v_mfma_f32_16x16x32_bf16 v[126:129], v[226:229], v[202:205], v[126:129]
	v_mfma_f32_16x16x32_bf16 v[122:125], v[230:233], v[202:205], v[122:125]
	v_mfma_f32_16x16x32_bf16 v[118:121], v[234:237], v[202:205], v[118:121]
	v_mfma_f32_16x16x32_bf16 v[114:117], v[238:241], v[202:205], v[114:117]
	v_mfma_f32_16x16x32_bf16 v[110:113], v[226:229], v[206:209], v[110:113]
	v_mfma_f32_16x16x32_bf16 v[106:109], v[230:233], v[206:209], v[106:109]
	v_mfma_f32_16x16x32_bf16 v[102:105], v[234:237], v[206:209], v[102:105]
	v_mfma_f32_16x16x32_bf16 v[98:101], v[238:241], v[206:209], v[98:101]
	v_mfma_f32_16x16x32_bf16 v[90:93], v[226:229], v[210:213], v[90:93]
	v_mfma_f32_16x16x32_bf16 v[86:89], v[230:233], v[210:213], v[86:89]
	v_mfma_f32_16x16x32_bf16 v[82:85], v[234:237], v[210:213], v[82:85]
	v_mfma_f32_16x16x32_bf16 v[78:81], v[238:241], v[210:213], v[78:81]
	v_mfma_f32_16x16x32_bf16 v[74:77], v[226:229], v[214:217], v[74:77]
	v_mfma_f32_16x16x32_bf16 v[70:73], v[230:233], v[214:217], v[70:73]
	v_mfma_f32_16x16x32_bf16 v[66:69], v[234:237], v[214:217], v[66:69]
	v_mfma_f32_16x16x32_bf16 v[62:65], v[238:241], v[214:217], v[62:65]
	v_mfma_f32_16x16x32_bf16 v[58:61], v[226:229], v[218:221], v[58:61]
	v_mfma_f32_16x16x32_bf16 v[50:53], v[230:233], v[218:221], v[50:53]
	v_mfma_f32_16x16x32_bf16 v[46:49], v[234:237], v[218:221], v[46:49]
	v_mfma_f32_16x16x32_bf16 v[38:41], v[238:241], v[218:221], v[38:41]
	v_mfma_f32_16x16x32_bf16 v[30:33], v[226:229], v[222:225], v[30:33]
	v_mfma_f32_16x16x32_bf16 v[26:29], v[230:233], v[222:225], v[26:29]
	v_mfma_f32_16x16x32_bf16 v[22:25], v[234:237], v[222:225], v[22:25]
	v_mfma_f32_16x16x32_bf16 v[18:21], v[238:241], v[222:225], v[18:21]
	s_waitcnt vmcnt(7)
	ds_write_b128 v0, v[14:17] offset:32768
	s_waitcnt vmcnt(6)
	ds_write_b128 v0, v[2:5] offset:40960
	s_waitcnt vmcnt(5)
	ds_write_b128 v0, v[6:9] offset:49152
	s_waitcnt vmcnt(4)
	ds_write_b128 v0, v[10:13] offset:57344
	s_add_u32 s58, s56, s0
	s_addc_u32 s59, s57, s1
	global_load_dwordx4 v[14:17], v171, s[58:59]
	s_nop 0
	global_load_dwordx4 v[2:5], v169, s[58:59]
	s_nop 0
	global_load_dwordx4 v[6:9], v167, s[58:59]
	s_nop 0
	global_load_dwordx4 v[10:13], v165, s[58:59]
	v_lshl_add_u32 v0, v182, 1, s2
	v_add_u32_e32 v191, v0, v181
	ds_read_b128 v[192:195], v191
	ds_read_b128 v[198:201], v191 offset:2048
	ds_read_b128 v[202:205], v191 offset:4096
	ds_read_b128 v[206:209], v191 offset:6144
	ds_read_b128 v[210:213], v191 offset:8192
	ds_read_b128 v[214:217], v191 offset:10240
	ds_read_b128 v[218:221], v191 offset:12288
	ds_read_b128 v[222:225], v191 offset:14336
	v_add_u32_e32 v0, v0, v180
	ds_read_b128 v[226:229], v0 offset:32768
	ds_read_b128 v[230:233], v0 offset:34816
	ds_read_b128 v[234:237], v0 offset:36864
	ds_read_b128 v[238:241], v0 offset:38912
	s_cmp_lg_u32 s101, 0
	s_cbranch_scc1 .Lstg_1007_b
	s_waitcnt lgkmcnt(3)
	v_mfma_f32_16x16x32_bf16 v[158:161], v[226:229], v[192:195], v[158:161]
	s_waitcnt lgkmcnt(2)
	v_mfma_f32_16x16x32_bf16 v[154:157], v[230:233], v[192:195], v[154:157]
	s_waitcnt lgkmcnt(1)
	v_mfma_f32_16x16x32_bf16 v[150:153], v[234:237], v[192:195], v[150:153]
	s_waitcnt lgkmcnt(0)
	v_mfma_f32_16x16x32_bf16 v[146:149], v[238:241], v[192:195], v[146:149]
	v_mfma_f32_16x16x32_bf16 v[142:145], v[226:229], v[198:201], v[142:145]
	v_mfma_f32_16x16x32_bf16 v[138:141], v[230:233], v[198:201], v[138:141]
	v_mfma_f32_16x16x32_bf16 v[134:137], v[234:237], v[198:201], v[134:137]
	v_mfma_f32_16x16x32_bf16 v[130:133], v[238:241], v[198:201], v[130:133]
	v_mfma_f32_16x16x32_bf16 v[126:129], v[226:229], v[202:205], v[126:129]
	v_mfma_f32_16x16x32_bf16 v[122:125], v[230:233], v[202:205], v[122:125]
	v_mfma_f32_16x16x32_bf16 v[118:121], v[234:237], v[202:205], v[118:121]
	v_mfma_f32_16x16x32_bf16 v[114:117], v[238:241], v[202:205], v[114:117]
	v_mfma_f32_16x16x32_bf16 v[110:113], v[226:229], v[206:209], v[110:113]
	v_mfma_f32_16x16x32_bf16 v[106:109], v[230:233], v[206:209], v[106:109]
	v_mfma_f32_16x16x32_bf16 v[102:105], v[234:237], v[206:209], v[102:105]
	v_mfma_f32_16x16x32_bf16 v[98:101], v[238:241], v[206:209], v[98:101]
	v_mfma_f32_16x16x32_bf16 v[90:93], v[226:229], v[210:213], v[90:93]
	v_mfma_f32_16x16x32_bf16 v[86:89], v[230:233], v[210:213], v[86:89]
	v_mfma_f32_16x16x32_bf16 v[82:85], v[234:237], v[210:213], v[82:85]
	v_mfma_f32_16x16x32_bf16 v[78:81], v[238:241], v[210:213], v[78:81]
	v_mfma_f32_16x16x32_bf16 v[74:77], v[226:229], v[214:217], v[74:77]
	v_mfma_f32_16x16x32_bf16 v[70:73], v[230:233], v[214:217], v[70:73]
	v_mfma_f32_16x16x32_bf16 v[66:69], v[234:237], v[214:217], v[66:69]
	v_mfma_f32_16x16x32_bf16 v[62:65], v[238:241], v[214:217], v[62:65]
	v_mfma_f32_16x16x32_bf16 v[58:61], v[226:229], v[218:221], v[58:61]
	v_mfma_f32_16x16x32_bf16 v[50:53], v[230:233], v[218:221], v[50:53]
	v_mfma_f32_16x16x32_bf16 v[46:49], v[234:237], v[218:221], v[46:49]
	v_mfma_f32_16x16x32_bf16 v[38:41], v[238:241], v[218:221], v[38:41]
	v_mfma_f32_16x16x32_bf16 v[30:33], v[226:229], v[222:225], v[30:33]
	v_mfma_f32_16x16x32_bf16 v[26:29], v[230:233], v[222:225], v[26:29]
	v_mfma_f32_16x16x32_bf16 v[22:25], v[234:237], v[222:225], v[22:25]
	v_mfma_f32_16x16x32_bf16 v[18:21], v[238:241], v[222:225], v[18:21]
